# v18 + the s_setprio 0 / s_setprio 1 pair in the middle of every GEMM MFMA segment removed (outer raise/lower kept)
# baseline (speedup 1.0000x reference)
; #define PG8_STAGE(bufoff, gbase, voff) do { _Pragma("unroll") for (int _i = 0; _i < 2; ++_i) \
;         __builtin_amdgcn_global_load_lds((const unsigned*)((const char*)(gbase) + (voff)[_i]), (LAS unsigned*)(lds + (bufoff) + ldsw + _i * 8192), 16, 0, 0); } while (0)
; #define PG8_LDA(dst, b, h) do { _Pragma("unroll") for (int m = 0; m < 4; ++m) _Pragma("unroll") for (int k = 0; k < 2; ++k) dst[m][k] = *(const LAS bf16x8*)(lds + PG8_SA(b, h) + aoff + m * 2048 + k * 1024); } while (0)
; #define PG8_LDB(dst, b, h) do { _Pragma("unroll") for (int n = 0; n < 2; ++n) _Pragma("unroll") for (int k = 0; k < 2; ++k) dst[n][k] = *(const LAS bf16x8*)(lds + PG8_SB(b, h) + boff + n * 2048 + k * 1024); } while (0)
; #define PG8_MMA(ai, bj, At, Bt) do { __builtin_amdgcn_s_setprio(1); _Pragma("unroll") for (int m = 0; m < 4; ++m) _Pragma("unroll") for (int n = 0; n < 2; ++n) _Pragma("unroll") for (int k = 0; k < 2; ++k) \
;         acc[ai][bj][m][n] = __builtin_amdgcn_mfma_f32_16x16x32_bf16(Bt[n][k], At[m][k], acc[ai][bj][m][n], 0, 0, 0); __builtin_amdgcn_s_setprio(0); } while (0)
; #define PG8_WAIT_V(n) asm volatile("s_waitcnt vmcnt(" #n ")" ::: "memory")
; #define PG8_WAIT_L(n) asm volatile("s_waitcnt lgkmcnt(" #n ")" ::: "memory")
; #define PG8_BAR __builtin_amdgcn_s_barrier()
; #define PG8_SCHED __builtin_amdgcn_sched_barrier(0)
; template <class Epi, class Sched>
; __device__ __forceinline__ void gemm_phase(int wv, LAS unsigned char* lds, const Gemm g, const Sched& S, const Epi& E) {
;     ...
;         for (int t = 0; t < nt; t += 2) {
;             const bool last = (t == nt - 2);
;             const char* a1 = cA + (size_t)(t + 1) * kstep;
;             const char* a2 = last ? nA : cA + (size_t)(t + 2) * kstep; const char* b2 = last ? nB : cB + (size_t)(t + 2) * kstep;
;             const char* a3 = a2 + kstep; const char* b3 = b2 + kstep;
;             PG8_LDB(B0, 0, 0); PG8_LDB(B1, 0, 1); PG8_SCHED; PG8_LDA(At, 0, 0); PG8_STAGE(PG8_SA(1, 1), a1 + hstep, voffA);
;             PG8_WAIT_V(8); PG8_WAIT_L(0); PG8_BAR; PG8_MMA(0, 0, At, B0); PG8_MMA(0, 1, At, B1); PG8_BAR; PG8_SCHED;
;             PG8_LDA(At, 0, 1); PG8_STAGE(PG8_SB(0, 0), b2, voffB); PG8_STAGE(PG8_SB(0, 1), b2 + hstepB, voffB); PG8_STAGE(PG8_SA(0, 0), a2, voffA);
;             PG8_WAIT_V(8); PG8_WAIT_L(0); PG8_BAR; PG8_MMA(1, 0, At, B0); PG8_MMA(1, 1, At, B1); PG8_BAR; PG8_SCHED;
.LBB0_178:
	s_add_u32 s20, s18, 0xfffc0080
	s_addc_u32 s21, s19, -1
	s_add_i32 s47, 0, 0x10000
	s_cmp_eq_u32 s46, 12
	s_cselect_b32 s23, s11, s21
	s_cselect_b32 s22, s41, s20
	s_cselect_b32 s21, s13, s45
	s_cselect_b32 s20, s42, s43
	s_add_i32 s50, 0, 0x14000
	v_add_u32_e32 v154, s47, v143
	v_add_u32_e32 v170, s50, v143
	ds_read_b128 v[138:141], v154
	ds_read_b128 v[146:149], v154 offset:1024
	ds_read_b128 v[150:153], v154 offset:2048
	ds_read_b128 v[154:157], v154 offset:3072
	ds_read_b128 v[158:161], v170
	ds_read_b128 v[162:165], v170 offset:1024
	ds_read_b128 v[166:169], v170 offset:2048
	ds_read_b128 v[170:173], v170 offset:3072
	v_lshl_add_u64 v[186:187], s[18:19], 0, v[134:135]
	s_add_i32 m0, s29, 0xc000
	ds_read_b128 v[174:177], v145
	ds_read_b128 v[178:181], v145 offset:1024
	ds_read_b128 v[182:185], v145 offset:2048
	ds_read_b128 v[198:201], v145 offset:3072
	ds_read_b128 v[202:205], v145 offset:4096
	ds_read_b128 v[206:209], v145 offset:5120
	ds_read_b128 v[210:213], v145 offset:6144
	ds_read_b128 v[214:217], v145 offset:7168
	global_load_lds_dwordx4 v[186:187], off
	v_lshl_add_u64 v[186:187], s[18:19], 0, v[136:137]
	s_add_i32 m0, s29, 0xe000
	s_nop 0
	global_load_lds_dwordx4 v[186:187], off
	s_waitcnt vmcnt(8)
	s_waitcnt lgkmcnt(0)
	s_barrier
	s_setprio 1
	s_waitcnt lgkmcnt(0)
	v_mfma_f32_16x16x32_bf16 v[124:127], v[138:141], v[174:177], v[124:127]
	v_mfma_f32_16x16x32_bf16 v[120:123], v[150:153], v[174:177], v[120:123]
	v_mfma_f32_16x16x32_bf16 v[108:111], v[138:141], v[182:185], v[108:111]
	v_mfma_f32_16x16x32_bf16 v[100:103], v[150:153], v[182:185], v[100:103]
	v_mfma_f32_16x16x32_bf16 v[92:95], v[138:141], v[202:205], v[92:95]
	v_mfma_f32_16x16x32_bf16 v[84:87], v[150:153], v[202:205], v[84:87]
	v_mfma_f32_16x16x32_bf16 v[76:79], v[138:141], v[210:213], v[76:79]
	v_mfma_f32_16x16x32_bf16 v[68:71], v[150:153], v[210:213], v[68:71]
	v_mfma_f32_16x16x32_bf16 v[124:127], v[146:149], v[178:181], v[124:127]
	v_mfma_f32_16x16x32_bf16 v[120:123], v[154:157], v[178:181], v[120:123]
	v_mfma_f32_16x16x32_bf16 v[108:111], v[146:149], v[198:201], v[108:111]
	v_mfma_f32_16x16x32_bf16 v[100:103], v[154:157], v[198:201], v[100:103]
	v_mfma_f32_16x16x32_bf16 v[92:95], v[146:149], v[206:209], v[92:95]
	v_mfma_f32_16x16x32_bf16 v[84:87], v[154:157], v[206:209], v[84:87]
	v_mfma_f32_16x16x32_bf16 v[76:79], v[146:149], v[214:217], v[76:79]
	v_mfma_f32_16x16x32_bf16 v[68:71], v[154:157], v[214:217], v[68:71]
	v_mfma_f32_16x16x32_bf16 v[116:119], v[158:161], v[174:177], v[116:119]
	v_mfma_f32_16x16x32_bf16 v[112:115], v[166:169], v[174:177], v[112:115]
	v_mfma_f32_16x16x32_bf16 v[104:107], v[158:161], v[182:185], v[104:107]
	v_mfma_f32_16x16x32_bf16 v[96:99], v[166:169], v[182:185], v[96:99]
	v_mfma_f32_16x16x32_bf16 v[88:91], v[158:161], v[202:205], v[88:91]
	v_mfma_f32_16x16x32_bf16 v[80:83], v[166:169], v[202:205], v[80:83]
	v_mfma_f32_16x16x32_bf16 v[72:75], v[158:161], v[210:213], v[72:75]
	v_mfma_f32_16x16x32_bf16 v[64:67], v[166:169], v[210:213], v[64:67]
	v_mfma_f32_16x16x32_bf16 v[116:119], v[162:165], v[178:181], v[116:119]
	v_mfma_f32_16x16x32_bf16 v[112:115], v[170:173], v[178:181], v[112:115]
	v_mfma_f32_16x16x32_bf16 v[104:107], v[162:165], v[198:201], v[104:107]
	v_mfma_f32_16x16x32_bf16 v[96:99], v[170:173], v[198:201], v[96:99]
	v_mfma_f32_16x16x32_bf16 v[88:91], v[162:165], v[206:209], v[88:91]
	v_mfma_f32_16x16x32_bf16 v[80:83], v[170:173], v[206:209], v[80:83]
	v_mfma_f32_16x16x32_bf16 v[72:75], v[162:165], v[214:217], v[72:75]
	v_mfma_f32_16x16x32_bf16 v[64:67], v[170:173], v[214:217], v[64:67]
	s_setprio 0
	s_barrier
	s_add_i32 s47, s47, s28
	v_lshl_add_u64 v[186:187], s[20:21], 0, v[188:189]
	s_mov_b32 m0, s47
	ds_read_b128 v[174:177], v145 offset:16384
	ds_read_b128 v[178:181], v145 offset:17408
	ds_read_b128 v[182:185], v145 offset:18432
	ds_read_b128 v[198:201], v145 offset:19456
	ds_read_b128 v[202:205], v145 offset:20480
	ds_read_b128 v[206:209], v145 offset:21504
	ds_read_b128 v[210:213], v145 offset:22528
	ds_read_b128 v[214:217], v145 offset:23552
	global_load_lds_dwordx4 v[186:187], off
	s_add_i32 m0, s47, 0x2000
	s_add_u32 s48, s20, 0x40000
	v_lshl_add_u64 v[218:219], s[20:21], 0, v[128:129]
	s_addc_u32 s49, s21, 0
	s_add_i32 s47, s50, s28
	global_load_lds_dwordx4 v[218:219], off
	v_lshl_add_u64 v[220:221], s[48:49], 0, v[188:189]
	s_mov_b32 m0, s47
	v_lshl_add_u64 v[222:223], s[22:23], 0, v[130:131]
	global_load_lds_dwordx4 v[220:221], off
	v_lshl_add_u64 v[220:221], s[48:49], 0, v[128:129]
	s_add_i32 m0, s47, 0x2000
	s_nop 0
	global_load_lds_dwordx4 v[220:221], off
	v_lshl_add_u64 v[220:221], s[22:23], 0, v[132:133]
	s_mov_b32 m0, s29
	s_nop 0
	global_load_lds_dwordx4 v[220:221], off
	s_mov_b32 m0, s30
	s_nop 0
	global_load_lds_dwordx4 v[222:223], off
	s_waitcnt vmcnt(8)
	s_waitcnt lgkmcnt(0)
	s_barrier
; #define PG8_STAGE(bufoff, gbase, voff) do { _Pragma("unroll") for (int _i = 0; _i < 2; ++_i) \
;         __builtin_amdgcn_global_load_lds((const unsigned*)((const char*)(gbase) + (voff)[_i]), (LAS unsigned*)(lds + (bufoff) + ldsw + _i * 8192), 16, 0, 0); } while (0)
; #define PG8_LDA(dst, b, h) do { _Pragma("unroll") for (int m = 0; m < 4; ++m) _Pragma("unroll") for (int k = 0; k < 2; ++k) dst[m][k] = *(const LAS bf16x8*)(lds + PG8_SA(b, h) + aoff + m * 2048 + k * 1024); } while (0)
; #define PG8_LDB(dst, b, h) do { _Pragma("unroll") for (int n = 0; n < 2; ++n) _Pragma("unroll") for (int k = 0; k < 2; ++k) dst[n][k] = *(const LAS bf16x8*)(lds + PG8_SB(b, h) + boff + n * 2048 + k * 1024); } while (0)
; #define PG8_MMA(ai, bj, At, Bt) do { __builtin_amdgcn_s_setprio(1); _Pragma("unroll") for (int m = 0; m < 4; ++m) _Pragma("unroll") for (int n = 0; n < 2; ++n) _Pragma("unroll") for (int k = 0; k < 2; ++k) \
;         acc[ai][bj][m][n] = __builtin_amdgcn_mfma_f32_16x16x32_bf16(Bt[n][k], At[m][k], acc[ai][bj][m][n], 0, 0, 0); __builtin_amdgcn_s_setprio(0); } while (0)
; #define PG8_WAIT_V(n) asm volatile("s_waitcnt vmcnt(" #n ")" ::: "memory")
; #define PG8_WAIT_L(n) asm volatile("s_waitcnt lgkmcnt(" #n ")" ::: "memory")
; #define PG8_BAR __builtin_amdgcn_s_barrier()
; #define PG8_SCHED __builtin_amdgcn_sched_barrier(0)
; template <class Epi, class Sched>
; __device__ __forceinline__ void gemm_phase(int wv, LAS unsigned char* lds, const Gemm g, const Sched& S, const Epi& E) {
;     ...
;             PG8_WAIT_V(8); PG8_WAIT_L(0); PG8_BAR; PG8_MMA(1, 0, At, B0); PG8_MMA(1, 1, At, B1); PG8_BAR; PG8_SCHED;
;             PG8_LDB(B0, 1, 0); PG8_LDB(B1, 1, 1); PG8_SCHED; PG8_LDA(At, 1, 0); PG8_STAGE(PG8_SA(0, 1), a2 + hstep, voffA);
;             PG8_WAIT_V(8); PG8_WAIT_L(0); PG8_BAR; PG8_MMA(0, 0, At, B0); PG8_MMA(0, 1, At, B1); PG8_BAR; PG8_SCHED;
	s_setprio 1
	s_waitcnt lgkmcnt(0)
	v_mfma_f32_16x16x32_bf16 v[60:63], v[138:141], v[174:177], v[60:63]
	v_mfma_f32_16x16x32_bf16 v[52:55], v[150:153], v[174:177], v[52:55]
	v_mfma_f32_16x16x32_bf16 v[44:47], v[138:141], v[182:185], v[44:47]
	v_mfma_f32_16x16x32_bf16 v[36:39], v[150:153], v[182:185], v[36:39]
	v_mfma_f32_16x16x32_bf16 v[28:31], v[138:141], v[202:205], v[28:31]
	v_mfma_f32_16x16x32_bf16 v[20:23], v[150:153], v[202:205], v[20:23]
	v_mfma_f32_16x16x32_bf16 v[12:15], v[138:141], v[210:213], v[12:15]
	v_mfma_f32_16x16x32_bf16 v[4:7], v[150:153], v[210:213], v[4:7]
	v_mfma_f32_16x16x32_bf16 v[60:63], v[146:149], v[178:181], v[60:63]
	v_mfma_f32_16x16x32_bf16 v[52:55], v[154:157], v[178:181], v[52:55]
	v_mfma_f32_16x16x32_bf16 v[44:47], v[146:149], v[198:201], v[44:47]
	v_mfma_f32_16x16x32_bf16 v[36:39], v[154:157], v[198:201], v[36:39]
	v_mfma_f32_16x16x32_bf16 v[28:31], v[146:149], v[206:209], v[28:31]
	v_mfma_f32_16x16x32_bf16 v[20:23], v[154:157], v[206:209], v[20:23]
	v_mfma_f32_16x16x32_bf16 v[12:15], v[146:149], v[214:217], v[12:15]
	v_mfma_f32_16x16x32_bf16 v[4:7], v[154:157], v[214:217], v[4:7]
	v_mfma_f32_16x16x32_bf16 v[56:59], v[158:161], v[174:177], v[56:59]
	v_mfma_f32_16x16x32_bf16 v[48:51], v[166:169], v[174:177], v[48:51]
	v_mfma_f32_16x16x32_bf16 v[40:43], v[158:161], v[182:185], v[40:43]
	v_mfma_f32_16x16x32_bf16 v[32:35], v[166:169], v[182:185], v[32:35]
	v_mfma_f32_16x16x32_bf16 v[24:27], v[158:161], v[202:205], v[24:27]
	v_mfma_f32_16x16x32_bf16 v[16:19], v[166:169], v[202:205], v[16:19]
	v_mfma_f32_16x16x32_bf16 v[8:11], v[158:161], v[210:213], v[8:11]
	v_mfma_f32_16x16x32_bf16 v[0:3], v[166:169], v[210:213], v[0:3]
	v_mfma_f32_16x16x32_bf16 v[56:59], v[162:165], v[178:181], v[56:59]
	v_mfma_f32_16x16x32_bf16 v[48:51], v[170:173], v[178:181], v[48:51]
	v_mfma_f32_16x16x32_bf16 v[40:43], v[162:165], v[198:201], v[40:43]
	v_mfma_f32_16x16x32_bf16 v[32:35], v[170:173], v[198:201], v[32:35]
	v_mfma_f32_16x16x32_bf16 v[24:27], v[162:165], v[206:209], v[24:27]
	v_mfma_f32_16x16x32_bf16 v[16:19], v[170:173], v[206:209], v[16:19]
	v_mfma_f32_16x16x32_bf16 v[8:11], v[162:165], v[214:217], v[8:11]
	v_mfma_f32_16x16x32_bf16 v[0:3], v[170:173], v[214:217], v[0:3]
	s_setprio 0
	s_barrier
	s_add_i32 s47, 0, 0x18000
	s_add_i32 s48, 0, 0x1c000
	v_add_u32_e32 v154, s47, v143
	v_add_u32_e32 v170, s48, v143
	ds_read_b128 v[138:141], v154
	ds_read_b128 v[146:149], v154 offset:1024
	ds_read_b128 v[150:153], v154 offset:2048
	ds_read_b128 v[154:157], v154 offset:3072
	ds_read_b128 v[158:161], v170
	ds_read_b128 v[162:165], v170 offset:1024
	ds_read_b128 v[166:169], v170 offset:2048
	ds_read_b128 v[170:173], v170 offset:3072
	s_add_u32 s22, s22, 0x40000
	s_addc_u32 s23, s23, 0
	s_mov_b32 m0, s31
	v_lshl_add_u64 v[228:229], s[22:23], 0, v[132:133]
	ds_read_b128 v[174:177], v145 offset:32768
	ds_read_b128 v[178:181], v145 offset:33792
	ds_read_b128 v[182:185], v145 offset:34816
	ds_read_b128 v[198:201], v145 offset:35840
	ds_read_b128 v[202:205], v145 offset:36864
	ds_read_b128 v[206:209], v145 offset:37888
	ds_read_b128 v[210:213], v145 offset:38912
	ds_read_b128 v[214:217], v145 offset:39936
	global_load_lds_dwordx4 v[228:229], off
	v_lshl_add_u64 v[228:229], s[22:23], 0, v[130:131]
	s_mov_b32 m0, s36
	s_nop 0
	global_load_lds_dwordx4 v[228:229], off
	s_waitcnt vmcnt(8)
	s_waitcnt lgkmcnt(0)
	s_barrier
	s_setprio 1
	s_waitcnt lgkmcnt(0)
	v_mfma_f32_16x16x32_bf16 v[124:127], v[138:141], v[174:177], v[124:127]
	v_mfma_f32_16x16x32_bf16 v[120:123], v[150:153], v[174:177], v[120:123]
	v_mfma_f32_16x16x32_bf16 v[108:111], v[138:141], v[182:185], v[108:111]
	v_mfma_f32_16x16x32_bf16 v[100:103], v[150:153], v[182:185], v[100:103]
	v_mfma_f32_16x16x32_bf16 v[92:95], v[138:141], v[202:205], v[92:95]
	v_mfma_f32_16x16x32_bf16 v[84:87], v[150:153], v[202:205], v[84:87]
	v_mfma_f32_16x16x32_bf16 v[76:79], v[138:141], v[210:213], v[76:79]
	v_mfma_f32_16x16x32_bf16 v[68:71], v[150:153], v[210:213], v[68:71]
	v_mfma_f32_16x16x32_bf16 v[124:127], v[146:149], v[178:181], v[124:127]
	v_mfma_f32_16x16x32_bf16 v[120:123], v[154:157], v[178:181], v[120:123]
	v_mfma_f32_16x16x32_bf16 v[108:111], v[146:149], v[198:201], v[108:111]
	v_mfma_f32_16x16x32_bf16 v[100:103], v[154:157], v[198:201], v[100:103]
	v_mfma_f32_16x16x32_bf16 v[92:95], v[146:149], v[206:209], v[92:95]
	v_mfma_f32_16x16x32_bf16 v[84:87], v[154:157], v[206:209], v[84:87]
	v_mfma_f32_16x16x32_bf16 v[76:79], v[146:149], v[214:217], v[76:79]
	v_mfma_f32_16x16x32_bf16 v[68:71], v[154:157], v[214:217], v[68:71]
	v_mfma_f32_16x16x32_bf16 v[116:119], v[158:161], v[174:177], v[116:119]
	v_mfma_f32_16x16x32_bf16 v[112:115], v[166:169], v[174:177], v[112:115]
	v_mfma_f32_16x16x32_bf16 v[104:107], v[158:161], v[182:185], v[104:107]
	v_mfma_f32_16x16x32_bf16 v[96:99], v[166:169], v[182:185], v[96:99]
	v_mfma_f32_16x16x32_bf16 v[88:91], v[158:161], v[202:205], v[88:91]
	v_mfma_f32_16x16x32_bf16 v[80:83], v[166:169], v[202:205], v[80:83]
	v_mfma_f32_16x16x32_bf16 v[72:75], v[158:161], v[210:213], v[72:75]
	v_mfma_f32_16x16x32_bf16 v[64:67], v[166:169], v[210:213], v[64:67]
	v_mfma_f32_16x16x32_bf16 v[116:119], v[162:165], v[178:181], v[116:119]
	v_mfma_f32_16x16x32_bf16 v[112:115], v[170:173], v[178:181], v[112:115]
	v_mfma_f32_16x16x32_bf16 v[104:107], v[162:165], v[198:201], v[104:107]
	v_mfma_f32_16x16x32_bf16 v[96:99], v[170:173], v[198:201], v[96:99]
	v_mfma_f32_16x16x32_bf16 v[88:91], v[162:165], v[206:209], v[88:91]
	v_mfma_f32_16x16x32_bf16 v[80:83], v[170:173], v[206:209], v[80:83]
	v_mfma_f32_16x16x32_bf16 v[72:75], v[162:165], v[214:217], v[72:75]
	v_mfma_f32_16x16x32_bf16 v[64:67], v[170:173], v[214:217], v[64:67]
	s_setprio 0
	s_barrier
; #define PG8_STAGE(bufoff, gbase, voff) do { _Pragma("unroll") for (int _i = 0; _i < 2; ++_i) \
;         __builtin_amdgcn_global_load_lds((const unsigned*)((const char*)(gbase) + (voff)[_i]), (LAS unsigned*)(lds + (bufoff) + ldsw + _i * 8192), 16, 0, 0); } while (0)
; #define PG8_LDA(dst, b, h) do { _Pragma("unroll") for (int m = 0; m < 4; ++m) _Pragma("unroll") for (int k = 0; k < 2; ++k) dst[m][k] = *(const LAS bf16x8*)(lds + PG8_SA(b, h) + aoff + m * 2048 + k * 1024); } while (0)
; #define PG8_MMA(ai, bj, At, Bt) do { __builtin_amdgcn_s_setprio(1); _Pragma("unroll") for (int m = 0; m < 4; ++m) _Pragma("unroll") for (int n = 0; n < 2; ++n) _Pragma("unroll") for (int k = 0; k < 2; ++k) \
;         acc[ai][bj][m][n] = __builtin_amdgcn_mfma_f32_16x16x32_bf16(Bt[n][k], At[m][k], acc[ai][bj][m][n], 0, 0, 0); __builtin_amdgcn_s_setprio(0); } while (0)
; #define PG8_WAIT_V(n) asm volatile("s_waitcnt vmcnt(" #n ")" ::: "memory")
; #define PG8_WAIT_L(n) asm volatile("s_waitcnt lgkmcnt(" #n ")" ::: "memory")
; #define PG8_BAR __builtin_amdgcn_s_barrier()
; #define PG8_SCHED __builtin_amdgcn_sched_barrier(0)
; template <class Epi, class Sched>
; __device__ __forceinline__ void gemm_phase(int wv, LAS unsigned char* lds, const Gemm g, const Sched& S, const Epi& E) {
;     ...
;             PG8_LDA(At, 1, 1); PG8_STAGE(PG8_SB(1, 0), b3, voffB); PG8_STAGE(PG8_SB(1, 1), b3 + hstepB, voffB); PG8_STAGE(PG8_SA(1, 0), a3, voffA);
;             PG8_WAIT_V(8); PG8_WAIT_L(0); PG8_BAR; PG8_MMA(1, 0, At, B0); PG8_MMA(1, 1, At, B1); PG8_BAR; PG8_SCHED;
;         }
	s_add_i32 s22, s47, s28
	v_lshl_add_u64 v[186:187], v[186:187], 0, s[74:75]
	s_mov_b32 m0, s22
	ds_read_b128 v[174:177], v145 offset:49152
	ds_read_b128 v[178:181], v145 offset:50176
	ds_read_b128 v[182:185], v145 offset:51200
	ds_read_b128 v[198:201], v145 offset:52224
	ds_read_b128 v[202:205], v145 offset:53248
	ds_read_b128 v[206:209], v145 offset:54272
	ds_read_b128 v[210:213], v145 offset:55296
	ds_read_b128 v[214:217], v145 offset:56320
	global_load_lds_dwordx4 v[186:187], off
	s_add_i32 m0, s22, 0x2000
	s_add_u32 s20, s20, 0x40080
	v_lshl_add_u64 v[186:187], v[218:219], 0, s[74:75]
	s_addc_u32 s21, s21, 0
	s_add_i32 s22, s48, s28
	global_load_lds_dwordx4 v[186:187], off
	v_lshl_add_u64 v[186:187], s[20:21], 0, v[188:189]
	s_mov_b32 m0, s22
	s_nop 0
	global_load_lds_dwordx4 v[186:187], off
	v_lshl_add_u64 v[186:187], s[20:21], 0, v[128:129]
	s_add_i32 m0, s22, 0x2000
	s_nop 0
	global_load_lds_dwordx4 v[186:187], off
	v_lshl_add_u64 v[186:187], v[220:221], 0, s[74:75]
	s_mov_b32 m0, s37
	s_nop 0
	global_load_lds_dwordx4 v[186:187], off
	v_lshl_add_u64 v[186:187], v[222:223], 0, s[74:75]
	s_mov_b32 m0, s38
	s_nop 0
	global_load_lds_dwordx4 v[186:187], off
	s_waitcnt vmcnt(8)
	s_waitcnt lgkmcnt(0)
	s_barrier
	s_setprio 1
	s_waitcnt lgkmcnt(0)
	v_mfma_f32_16x16x32_bf16 v[60:63], v[138:141], v[174:177], v[60:63]
	v_mfma_f32_16x16x32_bf16 v[52:55], v[150:153], v[174:177], v[52:55]
	v_mfma_f32_16x16x32_bf16 v[44:47], v[138:141], v[182:185], v[44:47]
	v_mfma_f32_16x16x32_bf16 v[36:39], v[150:153], v[182:185], v[36:39]
	v_mfma_f32_16x16x32_bf16 v[28:31], v[138:141], v[202:205], v[28:31]
	v_mfma_f32_16x16x32_bf16 v[20:23], v[150:153], v[202:205], v[20:23]
	v_mfma_f32_16x16x32_bf16 v[12:15], v[138:141], v[210:213], v[12:15]
	v_mfma_f32_16x16x32_bf16 v[4:7], v[150:153], v[210:213], v[4:7]
	v_mfma_f32_16x16x32_bf16 v[60:63], v[146:149], v[178:181], v[60:63]
	v_mfma_f32_16x16x32_bf16 v[52:55], v[154:157], v[178:181], v[52:55]
	v_mfma_f32_16x16x32_bf16 v[44:47], v[146:149], v[198:201], v[44:47]
	v_mfma_f32_16x16x32_bf16 v[36:39], v[154:157], v[198:201], v[36:39]
	v_mfma_f32_16x16x32_bf16 v[28:31], v[146:149], v[206:209], v[28:31]
	v_mfma_f32_16x16x32_bf16 v[20:23], v[154:157], v[206:209], v[20:23]
	v_mfma_f32_16x16x32_bf16 v[12:15], v[146:149], v[214:217], v[12:15]
	v_mfma_f32_16x16x32_bf16 v[4:7], v[154:157], v[214:217], v[4:7]
	v_mfma_f32_16x16x32_bf16 v[56:59], v[158:161], v[174:177], v[56:59]
	v_mfma_f32_16x16x32_bf16 v[48:51], v[166:169], v[174:177], v[48:51]
	v_mfma_f32_16x16x32_bf16 v[40:43], v[158:161], v[182:185], v[40:43]
	v_mfma_f32_16x16x32_bf16 v[32:35], v[166:169], v[182:185], v[32:35]
	v_mfma_f32_16x16x32_bf16 v[24:27], v[158:161], v[202:205], v[24:27]
	v_mfma_f32_16x16x32_bf16 v[16:19], v[166:169], v[202:205], v[16:19]
	v_mfma_f32_16x16x32_bf16 v[8:11], v[158:161], v[210:213], v[8:11]
	v_mfma_f32_16x16x32_bf16 v[0:3], v[166:169], v[210:213], v[0:3]
	v_mfma_f32_16x16x32_bf16 v[56:59], v[162:165], v[178:181], v[56:59]
	v_mfma_f32_16x16x32_bf16 v[48:51], v[170:173], v[178:181], v[48:51]
	v_mfma_f32_16x16x32_bf16 v[40:43], v[162:165], v[198:201], v[40:43]
	v_mfma_f32_16x16x32_bf16 v[32:35], v[170:173], v[198:201], v[32:35]
	v_mfma_f32_16x16x32_bf16 v[24:27], v[162:165], v[206:209], v[24:27]
	v_mfma_f32_16x16x32_bf16 v[16:19], v[170:173], v[206:209], v[16:19]
	v_mfma_f32_16x16x32_bf16 v[8:11], v[162:165], v[214:217], v[8:11]
	v_mfma_f32_16x16x32_bf16 v[0:3], v[170:173], v[214:217], v[0:3]
	s_setprio 0
	s_barrier
	s_add_i32 s46, s46, 2
	s_add_u32 s18, s18, 0x100
	s_addc_u32 s19, s19, 0
	s_add_u32 s43, s43, 0x100
	s_addc_u32 s45, s45, 0
	s_cmp_gt_u32 s46, 13
	s_cbranch_scc0 .LBB0_178
	s_and_b64 vcc, exec, s[8:9]
	s_cbranch_vccz .LBB0_181
	s_barrier

; #define PG8_STAGE(bufoff, gbase, voff) do { _Pragma("unroll") for (int _i = 0; _i < 2; ++_i) \
;         __builtin_amdgcn_global_load_lds((const unsigned*)((const char*)(gbase) + (voff)[_i]), (LAS unsigned*)(lds + (bufoff) + ldsw + _i * 8192), 16, 0, 0); } while (0)
; #define PG8_LDA(dst, b, h) do { _Pragma("unroll") for (int m = 0; m < 4; ++m) _Pragma("unroll") for (int k = 0; k < 2; ++k) dst[m][k] = *(const LAS bf16x8*)(lds + PG8_SA(b, h) + aoff + m * 2048 + k * 1024); } while (0)
; #define PG8_LDB(dst, b, h) do { _Pragma("unroll") for (int n = 0; n < 2; ++n) _Pragma("unroll") for (int k = 0; k < 2; ++k) dst[n][k] = *(const LAS bf16x8*)(lds + PG8_SB(b, h) + boff + n * 2048 + k * 1024); } while (0)
; #define PG8_MMA(ai, bj, At, Bt) do { __builtin_amdgcn_s_setprio(1); _Pragma("unroll") for (int m = 0; m < 4; ++m) _Pragma("unroll") for (int n = 0; n < 2; ++n) _Pragma("unroll") for (int k = 0; k < 2; ++k) \
;         acc[ai][bj][m][n] = __builtin_amdgcn_mfma_f32_16x16x32_bf16(Bt[n][k], At[m][k], acc[ai][bj][m][n], 0, 0, 0); __builtin_amdgcn_s_setprio(0); } while (0)
; #define PG8_WAIT_V(n) asm volatile("s_waitcnt vmcnt(" #n ")" ::: "memory")
; #define PG8_WAIT_L(n) asm volatile("s_waitcnt lgkmcnt(" #n ")" ::: "memory")
; #define PG8_BAR __builtin_amdgcn_s_barrier()
; #define PG8_SCHED __builtin_amdgcn_sched_barrier(0)
; template <class Epi, class Sched>
; __device__ __forceinline__ void gemm_phase(int wv, LAS unsigned char* lds, const Gemm g, const Sched& S, const Epi& E) {
;     ...
;         for (int t = 0; t < nt; t += 2) {
;             const bool last = (t == nt - 2);
;             const char* a1 = cA + (size_t)(t + 1) * kstep;
;             const char* a2 = last ? nA : cA + (size_t)(t + 2) * kstep; const char* b2 = last ? nB : cB + (size_t)(t + 2) * kstep;
;             const char* a3 = a2 + kstep; const char* b3 = b2 + kstep;
;             PG8_LDB(B0, 0, 0); PG8_LDB(B1, 0, 1); PG8_SCHED; PG8_LDA(At, 0, 0); PG8_STAGE(PG8_SA(1, 1), a1 + hstep, voffA);
;             PG8_WAIT_V(8); PG8_WAIT_L(0); PG8_BAR; PG8_MMA(0, 0, At, B0); PG8_MMA(0, 1, At, B1); PG8_BAR; PG8_SCHED;
;             PG8_LDA(At, 0, 1); PG8_STAGE(PG8_SB(0, 0), b2, voffB); PG8_STAGE(PG8_SB(0, 1), b2 + hstepB, voffB); PG8_STAGE(PG8_SA(0, 0), a2, voffA);
;             PG8_WAIT_V(8); PG8_WAIT_L(0); PG8_BAR; PG8_MMA(1, 0, At, B0); PG8_MMA(1, 1, At, B1); PG8_BAR; PG8_SCHED;
.LBB0_255:
	s_add_u32 s20, s18, 0x100
	s_addc_u32 s21, s19, 0
	s_add_i32 s49, 0, 0x10000
	s_cmp_eq_u32 s48, 40
	s_cselect_b32 s25, s5, s21
	s_cselect_b32 s24, s4, s20
	s_cselect_b32 s23, s17, s47
	s_cselect_b32 s22, s16, s46
	s_add_i32 s50, 0, 0x14000
	v_add_u32_e32 v124, s49, v240
	v_add_u32_e32 v156, s50, v240
	ds_read_b128 v[112:115], v124
	ds_read_b128 v[116:119], v124 offset:1024
	ds_read_b128 v[120:123], v124 offset:2048
	ds_read_b128 v[124:127], v124 offset:3072
	ds_read_b128 v[128:131], v156
	ds_read_b128 v[140:143], v156 offset:1024
	ds_read_b128 v[152:155], v156 offset:2048
	ds_read_b128 v[156:159], v156 offset:3072
	v_lshl_add_u64 v[212:213], s[18:19], 0, v[204:205]
	s_add_i32 m0, s31, 0xc000
	ds_read_b128 v[160:163], v244
	ds_read_b128 v[164:167], v244 offset:1024
	ds_read_b128 v[168:171], v244 offset:2048
	ds_read_b128 v[172:175], v244 offset:3072
	ds_read_b128 v[176:179], v244 offset:4096
	ds_read_b128 v[180:183], v244 offset:5120
	ds_read_b128 v[184:187], v244 offset:6144
	ds_read_b128 v[208:211], v244 offset:7168
	global_load_lds_dwordx4 v[212:213], off
	v_lshl_add_u64 v[212:213], s[18:19], 0, v[206:207]
	s_add_i32 m0, s31, 0xe000
	s_nop 0
	global_load_lds_dwordx4 v[212:213], off
	s_waitcnt vmcnt(8)
	s_waitcnt lgkmcnt(0)
	s_barrier
	s_setprio 1
	s_waitcnt lgkmcnt(0)
	v_mfma_f32_16x16x32_bf16 v[148:151], v[112:115], v[160:163], v[148:151]
	v_mfma_f32_16x16x32_bf16 v[144:147], v[120:123], v[160:163], v[144:147]
	v_mfma_f32_16x16x32_bf16 v[108:111], v[112:115], v[168:171], v[108:111]
	v_mfma_f32_16x16x32_bf16 v[104:107], v[120:123], v[168:171], v[104:107]
	v_mfma_f32_16x16x32_bf16 v[92:95], v[112:115], v[176:179], v[92:95]
	v_mfma_f32_16x16x32_bf16 v[88:91], v[120:123], v[176:179], v[88:91]
	v_mfma_f32_16x16x32_bf16 v[76:79], v[112:115], v[184:187], v[76:79]
	v_mfma_f32_16x16x32_bf16 v[72:75], v[120:123], v[184:187], v[72:75]
	v_mfma_f32_16x16x32_bf16 v[148:151], v[116:119], v[164:167], v[148:151]
	v_mfma_f32_16x16x32_bf16 v[144:147], v[124:127], v[164:167], v[144:147]
	v_mfma_f32_16x16x32_bf16 v[108:111], v[116:119], v[172:175], v[108:111]
	v_mfma_f32_16x16x32_bf16 v[104:107], v[124:127], v[172:175], v[104:107]
	v_mfma_f32_16x16x32_bf16 v[92:95], v[116:119], v[180:183], v[92:95]
	v_mfma_f32_16x16x32_bf16 v[88:91], v[124:127], v[180:183], v[88:91]
	v_mfma_f32_16x16x32_bf16 v[76:79], v[116:119], v[208:211], v[76:79]
	v_mfma_f32_16x16x32_bf16 v[72:75], v[124:127], v[208:211], v[72:75]
	v_mfma_f32_16x16x32_bf16 v[136:139], v[128:131], v[160:163], v[136:139]
	v_mfma_f32_16x16x32_bf16 v[132:135], v[152:155], v[160:163], v[132:135]
	v_mfma_f32_16x16x32_bf16 v[100:103], v[128:131], v[168:171], v[100:103]
	v_mfma_f32_16x16x32_bf16 v[96:99], v[152:155], v[168:171], v[96:99]
	v_mfma_f32_16x16x32_bf16 v[84:87], v[128:131], v[176:179], v[84:87]
	v_mfma_f32_16x16x32_bf16 v[80:83], v[152:155], v[176:179], v[80:83]
	v_mfma_f32_16x16x32_bf16 v[68:71], v[128:131], v[184:187], v[68:71]
	v_mfma_f32_16x16x32_bf16 v[64:67], v[152:155], v[184:187], v[64:67]
	v_mfma_f32_16x16x32_bf16 v[136:139], v[140:143], v[164:167], v[136:139]
	v_mfma_f32_16x16x32_bf16 v[132:135], v[156:159], v[164:167], v[132:135]
	v_mfma_f32_16x16x32_bf16 v[100:103], v[140:143], v[172:175], v[100:103]
	v_mfma_f32_16x16x32_bf16 v[96:99], v[156:159], v[172:175], v[96:99]
	v_mfma_f32_16x16x32_bf16 v[84:87], v[140:143], v[180:183], v[84:87]
	v_mfma_f32_16x16x32_bf16 v[80:83], v[156:159], v[180:183], v[80:83]
	v_mfma_f32_16x16x32_bf16 v[68:71], v[140:143], v[208:211], v[68:71]
	v_mfma_f32_16x16x32_bf16 v[64:67], v[156:159], v[208:211], v[64:67]
	s_setprio 0
	s_barrier
	s_add_i32 s18, s49, s30
	v_lshl_add_u64 v[212:213], s[22:23], 0, v[188:189]
	s_mov_b32 m0, s18
	ds_read_b128 v[160:163], v244 offset:16384
	ds_read_b128 v[164:167], v244 offset:17408
	ds_read_b128 v[168:171], v244 offset:18432
	ds_read_b128 v[172:175], v244 offset:19456
	ds_read_b128 v[176:179], v244 offset:20480
	ds_read_b128 v[180:183], v244 offset:21504
	ds_read_b128 v[184:187], v244 offset:22528
	ds_read_b128 v[208:211], v244 offset:23552
	global_load_lds_dwordx4 v[212:213], off
	s_add_i32 m0, s18, 0x2000
	s_add_u32 s18, s22, 0xb000
	v_lshl_add_u64 v[214:215], s[22:23], 0, v[198:199]
	s_addc_u32 s19, s23, 0
	s_add_i32 s49, s50, s30
	global_load_lds_dwordx4 v[214:215], off
	v_lshl_add_u64 v[216:217], s[18:19], 0, v[188:189]
	s_mov_b32 m0, s49
	v_lshl_add_u64 v[218:219], s[24:25], 0, v[200:201]
	global_load_lds_dwordx4 v[216:217], off
	v_lshl_add_u64 v[216:217], s[18:19], 0, v[198:199]
	s_add_i32 m0, s49, 0x2000
	s_nop 0
	global_load_lds_dwordx4 v[216:217], off
	v_lshl_add_u64 v[216:217], s[24:25], 0, v[202:203]
	s_mov_b32 m0, s31
	s_nop 0
	global_load_lds_dwordx4 v[216:217], off
	s_mov_b32 m0, s36
	s_nop 0
	global_load_lds_dwordx4 v[218:219], off
	s_waitcnt vmcnt(8)
	s_waitcnt lgkmcnt(0)
	s_barrier
; #define PG8_STAGE(bufoff, gbase, voff) do { _Pragma("unroll") for (int _i = 0; _i < 2; ++_i) \
;         __builtin_amdgcn_global_load_lds((const unsigned*)((const char*)(gbase) + (voff)[_i]), (LAS unsigned*)(lds + (bufoff) + ldsw + _i * 8192), 16, 0, 0); } while (0)
; #define PG8_LDA(dst, b, h) do { _Pragma("unroll") for (int m = 0; m < 4; ++m) _Pragma("unroll") for (int k = 0; k < 2; ++k) dst[m][k] = *(const LAS bf16x8*)(lds + PG8_SA(b, h) + aoff + m * 2048 + k * 1024); } while (0)
; #define PG8_LDB(dst, b, h) do { _Pragma("unroll") for (int n = 0; n < 2; ++n) _Pragma("unroll") for (int k = 0; k < 2; ++k) dst[n][k] = *(const LAS bf16x8*)(lds + PG8_SB(b, h) + boff + n * 2048 + k * 1024); } while (0)
; #define PG8_MMA(ai, bj, At, Bt) do { __builtin_amdgcn_s_setprio(1); _Pragma("unroll") for (int m = 0; m < 4; ++m) _Pragma("unroll") for (int n = 0; n < 2; ++n) _Pragma("unroll") for (int k = 0; k < 2; ++k) \
;         acc[ai][bj][m][n] = __builtin_amdgcn_mfma_f32_16x16x32_bf16(Bt[n][k], At[m][k], acc[ai][bj][m][n], 0, 0, 0); __builtin_amdgcn_s_setprio(0); } while (0)
; #define PG8_WAIT_V(n) asm volatile("s_waitcnt vmcnt(" #n ")" ::: "memory")
; #define PG8_WAIT_L(n) asm volatile("s_waitcnt lgkmcnt(" #n ")" ::: "memory")
; #define PG8_BAR __builtin_amdgcn_s_barrier()
; #define PG8_SCHED __builtin_amdgcn_sched_barrier(0)
; template <class Epi, class Sched>
; __device__ __forceinline__ void gemm_phase(int wv, LAS unsigned char* lds, const Gemm g, const Sched& S, const Epi& E) {
;     ...
;             PG8_WAIT_V(8); PG8_WAIT_L(0); PG8_BAR; PG8_MMA(1, 0, At, B0); PG8_MMA(1, 1, At, B1); PG8_BAR; PG8_SCHED;
;             PG8_LDB(B0, 1, 0); PG8_LDB(B1, 1, 1); PG8_SCHED; PG8_LDA(At, 1, 0); PG8_STAGE(PG8_SA(0, 1), a2 + hstep, voffA);
;             PG8_WAIT_V(8); PG8_WAIT_L(0); PG8_BAR; PG8_MMA(0, 0, At, B0); PG8_MMA(0, 1, At, B1); PG8_BAR; PG8_SCHED;
	s_setprio 1
	s_waitcnt lgkmcnt(0)
	v_mfma_f32_16x16x32_bf16 v[60:63], v[112:115], v[160:163], v[60:63]
	v_mfma_f32_16x16x32_bf16 v[56:59], v[120:123], v[160:163], v[56:59]
	v_mfma_f32_16x16x32_bf16 v[44:47], v[112:115], v[168:171], v[44:47]
	v_mfma_f32_16x16x32_bf16 v[40:43], v[120:123], v[168:171], v[40:43]
	v_mfma_f32_16x16x32_bf16 v[28:31], v[112:115], v[176:179], v[28:31]
	v_mfma_f32_16x16x32_bf16 v[24:27], v[120:123], v[176:179], v[24:27]
	v_mfma_f32_16x16x32_bf16 v[12:15], v[112:115], v[184:187], v[12:15]
	v_mfma_f32_16x16x32_bf16 v[8:11], v[120:123], v[184:187], v[8:11]
	v_mfma_f32_16x16x32_bf16 v[60:63], v[116:119], v[164:167], v[60:63]
	v_mfma_f32_16x16x32_bf16 v[56:59], v[124:127], v[164:167], v[56:59]
	v_mfma_f32_16x16x32_bf16 v[44:47], v[116:119], v[172:175], v[44:47]
	v_mfma_f32_16x16x32_bf16 v[40:43], v[124:127], v[172:175], v[40:43]
	v_mfma_f32_16x16x32_bf16 v[28:31], v[116:119], v[180:183], v[28:31]
	v_mfma_f32_16x16x32_bf16 v[24:27], v[124:127], v[180:183], v[24:27]
	v_mfma_f32_16x16x32_bf16 v[12:15], v[116:119], v[208:211], v[12:15]
	v_mfma_f32_16x16x32_bf16 v[8:11], v[124:127], v[208:211], v[8:11]
	v_mfma_f32_16x16x32_bf16 v[52:55], v[128:131], v[160:163], v[52:55]
	v_mfma_f32_16x16x32_bf16 v[48:51], v[152:155], v[160:163], v[48:51]
	v_mfma_f32_16x16x32_bf16 v[36:39], v[128:131], v[168:171], v[36:39]
	v_mfma_f32_16x16x32_bf16 v[32:35], v[152:155], v[168:171], v[32:35]
	v_mfma_f32_16x16x32_bf16 v[20:23], v[128:131], v[176:179], v[20:23]
	v_mfma_f32_16x16x32_bf16 v[16:19], v[152:155], v[176:179], v[16:19]
	v_mfma_f32_16x16x32_bf16 v[4:7], v[128:131], v[184:187], v[4:7]
	v_mfma_f32_16x16x32_bf16 v[0:3], v[152:155], v[184:187], v[0:3]
	v_mfma_f32_16x16x32_bf16 v[52:55], v[140:143], v[164:167], v[52:55]
	v_mfma_f32_16x16x32_bf16 v[48:51], v[156:159], v[164:167], v[48:51]
	v_mfma_f32_16x16x32_bf16 v[36:39], v[140:143], v[172:175], v[36:39]
	v_mfma_f32_16x16x32_bf16 v[32:35], v[156:159], v[172:175], v[32:35]
	v_mfma_f32_16x16x32_bf16 v[20:23], v[140:143], v[180:183], v[20:23]
	v_mfma_f32_16x16x32_bf16 v[16:19], v[156:159], v[180:183], v[16:19]
	v_mfma_f32_16x16x32_bf16 v[4:7], v[140:143], v[208:211], v[4:7]
	v_mfma_f32_16x16x32_bf16 v[0:3], v[156:159], v[208:211], v[0:3]
	s_setprio 0
	s_barrier
	s_add_i32 s49, 0, 0x18000
	s_add_i32 s50, 0, 0x1c000
	v_add_u32_e32 v124, s49, v240
	v_add_u32_e32 v156, s50, v240
	ds_read_b128 v[112:115], v124
	ds_read_b128 v[116:119], v124 offset:1024
	ds_read_b128 v[120:123], v124 offset:2048
	ds_read_b128 v[124:127], v124 offset:3072
	ds_read_b128 v[128:131], v156
	ds_read_b128 v[140:143], v156 offset:1024
	ds_read_b128 v[152:155], v156 offset:2048
	ds_read_b128 v[156:159], v156 offset:3072
	s_add_u32 s18, s24, 0xb0000
	s_addc_u32 s19, s25, 0
	s_mov_b32 m0, s37
	v_lshl_add_u64 v[220:221], s[18:19], 0, v[202:203]
	ds_read_b128 v[160:163], v244 offset:32768
	ds_read_b128 v[164:167], v244 offset:33792
	ds_read_b128 v[168:171], v244 offset:34816
	ds_read_b128 v[172:175], v244 offset:35840
	ds_read_b128 v[176:179], v244 offset:36864
	ds_read_b128 v[180:183], v244 offset:37888
	ds_read_b128 v[184:187], v244 offset:38912
	ds_read_b128 v[208:211], v244 offset:39936
	global_load_lds_dwordx4 v[220:221], off
	v_lshl_add_u64 v[220:221], s[18:19], 0, v[200:201]
	s_mov_b32 m0, s38
	s_nop 0
	global_load_lds_dwordx4 v[220:221], off
	s_waitcnt vmcnt(8)
	s_waitcnt lgkmcnt(0)
	s_barrier
	s_setprio 1
	s_waitcnt lgkmcnt(0)
	v_mfma_f32_16x16x32_bf16 v[148:151], v[112:115], v[160:163], v[148:151]
	v_mfma_f32_16x16x32_bf16 v[144:147], v[120:123], v[160:163], v[144:147]
	v_mfma_f32_16x16x32_bf16 v[108:111], v[112:115], v[168:171], v[108:111]
	v_mfma_f32_16x16x32_bf16 v[104:107], v[120:123], v[168:171], v[104:107]
	v_mfma_f32_16x16x32_bf16 v[92:95], v[112:115], v[176:179], v[92:95]
	v_mfma_f32_16x16x32_bf16 v[88:91], v[120:123], v[176:179], v[88:91]
	v_mfma_f32_16x16x32_bf16 v[76:79], v[112:115], v[184:187], v[76:79]
	v_mfma_f32_16x16x32_bf16 v[72:75], v[120:123], v[184:187], v[72:75]
	v_mfma_f32_16x16x32_bf16 v[148:151], v[116:119], v[164:167], v[148:151]
	v_mfma_f32_16x16x32_bf16 v[144:147], v[124:127], v[164:167], v[144:147]
	v_mfma_f32_16x16x32_bf16 v[108:111], v[116:119], v[172:175], v[108:111]
	v_mfma_f32_16x16x32_bf16 v[104:107], v[124:127], v[172:175], v[104:107]
	v_mfma_f32_16x16x32_bf16 v[92:95], v[116:119], v[180:183], v[92:95]
	v_mfma_f32_16x16x32_bf16 v[88:91], v[124:127], v[180:183], v[88:91]
	v_mfma_f32_16x16x32_bf16 v[76:79], v[116:119], v[208:211], v[76:79]
	v_mfma_f32_16x16x32_bf16 v[72:75], v[124:127], v[208:211], v[72:75]
	v_mfma_f32_16x16x32_bf16 v[136:139], v[128:131], v[160:163], v[136:139]
	v_mfma_f32_16x16x32_bf16 v[132:135], v[152:155], v[160:163], v[132:135]
	v_mfma_f32_16x16x32_bf16 v[100:103], v[128:131], v[168:171], v[100:103]
	v_mfma_f32_16x16x32_bf16 v[96:99], v[152:155], v[168:171], v[96:99]
	v_mfma_f32_16x16x32_bf16 v[84:87], v[128:131], v[176:179], v[84:87]
	v_mfma_f32_16x16x32_bf16 v[80:83], v[152:155], v[176:179], v[80:83]
	v_mfma_f32_16x16x32_bf16 v[68:71], v[128:131], v[184:187], v[68:71]
	v_mfma_f32_16x16x32_bf16 v[64:67], v[152:155], v[184:187], v[64:67]
	v_mfma_f32_16x16x32_bf16 v[136:139], v[140:143], v[164:167], v[136:139]
	v_mfma_f32_16x16x32_bf16 v[132:135], v[156:159], v[164:167], v[132:135]
	v_mfma_f32_16x16x32_bf16 v[100:103], v[140:143], v[172:175], v[100:103]
	v_mfma_f32_16x16x32_bf16 v[96:99], v[156:159], v[172:175], v[96:99]
	v_mfma_f32_16x16x32_bf16 v[84:87], v[140:143], v[180:183], v[84:87]
	v_mfma_f32_16x16x32_bf16 v[80:83], v[156:159], v[180:183], v[80:83]
	v_mfma_f32_16x16x32_bf16 v[68:71], v[140:143], v[208:211], v[68:71]
	v_mfma_f32_16x16x32_bf16 v[64:67], v[156:159], v[208:211], v[64:67]
	s_setprio 0
	s_barrier
; #define PG8_STAGE(bufoff, gbase, voff) do { _Pragma("unroll") for (int _i = 0; _i < 2; ++_i) \
;         __builtin_amdgcn_global_load_lds((const unsigned*)((const char*)(gbase) + (voff)[_i]), (LAS unsigned*)(lds + (bufoff) + ldsw + _i * 8192), 16, 0, 0); } while (0)
; #define PG8_LDA(dst, b, h) do { _Pragma("unroll") for (int m = 0; m < 4; ++m) _Pragma("unroll") for (int k = 0; k < 2; ++k) dst[m][k] = *(const LAS bf16x8*)(lds + PG8_SA(b, h) + aoff + m * 2048 + k * 1024); } while (0)
; #define PG8_MMA(ai, bj, At, Bt) do { __builtin_amdgcn_s_setprio(1); _Pragma("unroll") for (int m = 0; m < 4; ++m) _Pragma("unroll") for (int n = 0; n < 2; ++n) _Pragma("unroll") for (int k = 0; k < 2; ++k) \
;         acc[ai][bj][m][n] = __builtin_amdgcn_mfma_f32_16x16x32_bf16(Bt[n][k], At[m][k], acc[ai][bj][m][n], 0, 0, 0); __builtin_amdgcn_s_setprio(0); } while (0)
; #define PG8_WAIT_V(n) asm volatile("s_waitcnt vmcnt(" #n ")" ::: "memory")
; #define PG8_WAIT_L(n) asm volatile("s_waitcnt lgkmcnt(" #n ")" ::: "memory")
; #define PG8_BAR __builtin_amdgcn_s_barrier()
; #define PG8_SCHED __builtin_amdgcn_sched_barrier(0)
; template <class Epi, class Sched>
; __device__ __forceinline__ void gemm_phase(int wv, LAS unsigned char* lds, const Gemm g, const Sched& S, const Epi& E) {
;     ...
;             PG8_LDA(At, 1, 1); PG8_STAGE(PG8_SB(1, 0), b3, voffB); PG8_STAGE(PG8_SB(1, 1), b3 + hstepB, voffB); PG8_STAGE(PG8_SA(1, 0), a3, voffA);
;             PG8_WAIT_V(8); PG8_WAIT_L(0); PG8_BAR; PG8_MMA(1, 0, At, B0); PG8_MMA(1, 1, At, B1); PG8_BAR; PG8_SCHED;
;         }
	s_add_i32 s18, s49, s30
	v_lshl_add_u64 v[212:213], v[212:213], 0, s[74:75]
	s_mov_b32 m0, s18
	ds_read_b128 v[160:163], v244 offset:49152
	ds_read_b128 v[164:167], v244 offset:50176
	ds_read_b128 v[168:171], v244 offset:51200
	ds_read_b128 v[172:175], v244 offset:52224
	ds_read_b128 v[176:179], v244 offset:53248
	ds_read_b128 v[180:183], v244 offset:54272
	ds_read_b128 v[184:187], v244 offset:55296
	ds_read_b128 v[208:211], v244 offset:56320
	global_load_lds_dwordx4 v[212:213], off
	s_add_i32 m0, s18, 0x2000
	s_add_u32 s18, s22, 0xb080
	v_lshl_add_u64 v[212:213], v[214:215], 0, s[74:75]
	s_addc_u32 s19, s23, 0
	s_add_i32 s22, s50, s30
	global_load_lds_dwordx4 v[212:213], off
	v_lshl_add_u64 v[212:213], s[18:19], 0, v[188:189]
	s_mov_b32 m0, s22
	s_nop 0
	global_load_lds_dwordx4 v[212:213], off
	v_lshl_add_u64 v[212:213], s[18:19], 0, v[198:199]
	s_add_i32 m0, s22, 0x2000
	s_nop 0
	global_load_lds_dwordx4 v[212:213], off
	v_lshl_add_u64 v[212:213], v[216:217], 0, s[74:75]
	s_mov_b32 m0, s39
	s_nop 0
	global_load_lds_dwordx4 v[212:213], off
	v_lshl_add_u64 v[212:213], v[218:219], 0, s[74:75]
	s_mov_b32 m0, s40
	s_nop 0
	global_load_lds_dwordx4 v[212:213], off
	s_waitcnt vmcnt(8)
	s_waitcnt lgkmcnt(0)
	s_barrier
	s_setprio 1
	s_waitcnt lgkmcnt(0)
	v_mfma_f32_16x16x32_bf16 v[60:63], v[112:115], v[160:163], v[60:63]
	v_mfma_f32_16x16x32_bf16 v[56:59], v[120:123], v[160:163], v[56:59]
	v_mfma_f32_16x16x32_bf16 v[44:47], v[112:115], v[168:171], v[44:47]
	v_mfma_f32_16x16x32_bf16 v[40:43], v[120:123], v[168:171], v[40:43]
	v_mfma_f32_16x16x32_bf16 v[28:31], v[112:115], v[176:179], v[28:31]
	v_mfma_f32_16x16x32_bf16 v[24:27], v[120:123], v[176:179], v[24:27]
	v_mfma_f32_16x16x32_bf16 v[12:15], v[112:115], v[184:187], v[12:15]
	v_mfma_f32_16x16x32_bf16 v[8:11], v[120:123], v[184:187], v[8:11]
	v_mfma_f32_16x16x32_bf16 v[60:63], v[116:119], v[164:167], v[60:63]
	v_mfma_f32_16x16x32_bf16 v[56:59], v[124:127], v[164:167], v[56:59]
	v_mfma_f32_16x16x32_bf16 v[44:47], v[116:119], v[172:175], v[44:47]
	v_mfma_f32_16x16x32_bf16 v[40:43], v[124:127], v[172:175], v[40:43]
	v_mfma_f32_16x16x32_bf16 v[28:31], v[116:119], v[180:183], v[28:31]
	v_mfma_f32_16x16x32_bf16 v[24:27], v[124:127], v[180:183], v[24:27]
	v_mfma_f32_16x16x32_bf16 v[12:15], v[116:119], v[208:211], v[12:15]
	v_mfma_f32_16x16x32_bf16 v[8:11], v[124:127], v[208:211], v[8:11]
	v_mfma_f32_16x16x32_bf16 v[52:55], v[128:131], v[160:163], v[52:55]
	v_mfma_f32_16x16x32_bf16 v[48:51], v[152:155], v[160:163], v[48:51]
	v_mfma_f32_16x16x32_bf16 v[36:39], v[128:131], v[168:171], v[36:39]
	v_mfma_f32_16x16x32_bf16 v[32:35], v[152:155], v[168:171], v[32:35]
	v_mfma_f32_16x16x32_bf16 v[20:23], v[128:131], v[176:179], v[20:23]
	v_mfma_f32_16x16x32_bf16 v[16:19], v[152:155], v[176:179], v[16:19]
	v_mfma_f32_16x16x32_bf16 v[4:7], v[128:131], v[184:187], v[4:7]
	v_mfma_f32_16x16x32_bf16 v[0:3], v[152:155], v[184:187], v[0:3]
	v_mfma_f32_16x16x32_bf16 v[52:55], v[140:143], v[164:167], v[52:55]
	v_mfma_f32_16x16x32_bf16 v[48:51], v[156:159], v[164:167], v[48:51]
	v_mfma_f32_16x16x32_bf16 v[36:39], v[140:143], v[172:175], v[36:39]
	v_mfma_f32_16x16x32_bf16 v[32:35], v[156:159], v[172:175], v[32:35]
	v_mfma_f32_16x16x32_bf16 v[20:23], v[140:143], v[180:183], v[20:23]
	v_mfma_f32_16x16x32_bf16 v[16:19], v[156:159], v[180:183], v[16:19]
	v_mfma_f32_16x16x32_bf16 v[4:7], v[140:143], v[208:211], v[4:7]
	v_mfma_f32_16x16x32_bf16 v[0:3], v[156:159], v[208:211], v[0:3]
	s_setprio 0
	s_barrier
	s_add_i32 s48, s48, 2
	s_add_u32 s46, s46, 0x100
	s_addc_u32 s47, s47, 0
	s_cmp_gt_u32 s48, 41
	s_mov_b64 s[18:19], s[20:21]
	s_cbranch_scc0 .LBB0_255
	s_and_b64 vcc, exec, s[14:15]
	s_cbranch_vccz .LBB0_258
	s_barrier

; #define PG8_STAGE(bufoff, gbase, voff) do { _Pragma("unroll") for (int _i = 0; _i < 2; ++_i) \
;         __builtin_amdgcn_global_load_lds((const unsigned*)((const char*)(gbase) + (voff)[_i]), (LAS unsigned*)(lds + (bufoff) + ldsw + _i * 8192), 16, 0, 0); } while (0)
; #define PG8_LDA(dst, b, h) do { _Pragma("unroll") for (int m = 0; m < 4; ++m) _Pragma("unroll") for (int k = 0; k < 2; ++k) dst[m][k] = *(const LAS bf16x8*)(lds + PG8_SA(b, h) + aoff + m * 2048 + k * 1024); } while (0)
; #define PG8_LDB(dst, b, h) do { _Pragma("unroll") for (int n = 0; n < 2; ++n) _Pragma("unroll") for (int k = 0; k < 2; ++k) dst[n][k] = *(const LAS bf16x8*)(lds + PG8_SB(b, h) + boff + n * 2048 + k * 1024); } while (0)
; #define PG8_MMA(ai, bj, At, Bt) do { __builtin_amdgcn_s_setprio(1); _Pragma("unroll") for (int m = 0; m < 4; ++m) _Pragma("unroll") for (int n = 0; n < 2; ++n) _Pragma("unroll") for (int k = 0; k < 2; ++k) \
;         acc[ai][bj][m][n] = __builtin_amdgcn_mfma_f32_16x16x32_bf16(Bt[n][k], At[m][k], acc[ai][bj][m][n], 0, 0, 0); __builtin_amdgcn_s_setprio(0); } while (0)
; #define PG8_WAIT_V(n) asm volatile("s_waitcnt vmcnt(" #n ")" ::: "memory")
; #define PG8_WAIT_L(n) asm volatile("s_waitcnt lgkmcnt(" #n ")" ::: "memory")
; #define PG8_BAR __builtin_amdgcn_s_barrier()
; #define PG8_SCHED __builtin_amdgcn_sched_barrier(0)
; template <class Epi, class Sched>
; __device__ __forceinline__ void gemm_phase(int wv, LAS unsigned char* lds, const Gemm g, const Sched& S, const Epi& E) {
;     ...
;         for (int t = 0; t < nt; t += 2) {
;             const bool last = (t == nt - 2);
;             const char* a1 = cA + (size_t)(t + 1) * kstep;
;             const char* a2 = last ? nA : cA + (size_t)(t + 2) * kstep; const char* b2 = last ? nB : cB + (size_t)(t + 2) * kstep;
;             const char* a3 = a2 + kstep; const char* b3 = b2 + kstep;
;             PG8_LDB(B0, 0, 0); PG8_LDB(B1, 0, 1); PG8_SCHED; PG8_LDA(At, 0, 0); PG8_STAGE(PG8_SA(1, 1), a1 + hstep, voffA);
;             PG8_WAIT_V(8); PG8_WAIT_L(0); PG8_BAR; PG8_MMA(0, 0, At, B0); PG8_MMA(0, 1, At, B1); PG8_BAR; PG8_SCHED;
;             PG8_LDA(At, 0, 1); PG8_STAGE(PG8_SB(0, 0), b2, voffB); PG8_STAGE(PG8_SB(0, 1), b2 + hstepB, voffB); PG8_STAGE(PG8_SA(0, 0), a2, voffA);
;             PG8_WAIT_V(8); PG8_WAIT_L(0); PG8_BAR; PG8_MMA(1, 0, At, B0); PG8_MMA(1, 1, At, B1); PG8_BAR; PG8_SCHED;
.LBB0_344:
	s_add_u32 s18, s2, 0xfffc0080
	s_addc_u32 s19, s3, -1
	s_add_i32 s47, 0, 0x10000
	s_cmp_eq_u32 s46, 12
	s_cselect_b32 s21, s11, s19
	s_cselect_b32 s20, s41, s18
	s_cselect_b32 s19, s13, s45
	s_cselect_b32 s18, s42, s43
	s_add_i32 s50, 0, 0x14000
	v_add_u32_e32 v156, s47, v145
	v_add_u32_e32 v172, s50, v145
	ds_read_b128 v[140:143], v156
	ds_read_b128 v[148:151], v156 offset:1024
	ds_read_b128 v[152:155], v156 offset:2048
	ds_read_b128 v[156:159], v156 offset:3072
	ds_read_b128 v[160:163], v172
	ds_read_b128 v[164:167], v172 offset:1024
	ds_read_b128 v[168:171], v172 offset:2048
	ds_read_b128 v[172:175], v172 offset:3072
	v_lshl_add_u64 v[218:219], s[2:3], 0, v[136:137]
	s_add_i32 m0, s27, 0xc000
	ds_read_b128 v[176:179], v147
	ds_read_b128 v[180:183], v147 offset:1024
	ds_read_b128 v[184:187], v147 offset:2048
	ds_read_b128 v[198:201], v147 offset:3072
	ds_read_b128 v[202:205], v147 offset:4096
	ds_read_b128 v[206:209], v147 offset:5120
	ds_read_b128 v[210:213], v147 offset:6144
	ds_read_b128 v[214:217], v147 offset:7168
	global_load_lds_dwordx4 v[218:219], off
	v_lshl_add_u64 v[218:219], s[2:3], 0, v[138:139]
	s_add_i32 m0, s27, 0xe000
	s_nop 0
	global_load_lds_dwordx4 v[218:219], off
	s_waitcnt vmcnt(8)
	s_waitcnt lgkmcnt(0)
	s_barrier
	s_setprio 1
	s_waitcnt lgkmcnt(0)
	v_mfma_f32_16x16x32_bf16 v[124:127], v[140:143], v[176:179], v[124:127]
	v_mfma_f32_16x16x32_bf16 v[120:123], v[152:155], v[176:179], v[120:123]
	v_mfma_f32_16x16x32_bf16 v[108:111], v[140:143], v[184:187], v[108:111]
	v_mfma_f32_16x16x32_bf16 v[104:107], v[152:155], v[184:187], v[104:107]
	v_mfma_f32_16x16x32_bf16 v[92:95], v[140:143], v[202:205], v[92:95]
	v_mfma_f32_16x16x32_bf16 v[88:91], v[152:155], v[202:205], v[88:91]
	v_mfma_f32_16x16x32_bf16 v[76:79], v[140:143], v[210:213], v[76:79]
	v_mfma_f32_16x16x32_bf16 v[72:75], v[152:155], v[210:213], v[72:75]
	v_mfma_f32_16x16x32_bf16 v[124:127], v[148:151], v[180:183], v[124:127]
	v_mfma_f32_16x16x32_bf16 v[120:123], v[156:159], v[180:183], v[120:123]
	v_mfma_f32_16x16x32_bf16 v[108:111], v[148:151], v[198:201], v[108:111]
	v_mfma_f32_16x16x32_bf16 v[104:107], v[156:159], v[198:201], v[104:107]
	v_mfma_f32_16x16x32_bf16 v[92:95], v[148:151], v[206:209], v[92:95]
	v_mfma_f32_16x16x32_bf16 v[88:91], v[156:159], v[206:209], v[88:91]
	v_mfma_f32_16x16x32_bf16 v[76:79], v[148:151], v[214:217], v[76:79]
	v_mfma_f32_16x16x32_bf16 v[72:75], v[156:159], v[214:217], v[72:75]
	v_mfma_f32_16x16x32_bf16 v[116:119], v[160:163], v[176:179], v[116:119]
	v_mfma_f32_16x16x32_bf16 v[112:115], v[168:171], v[176:179], v[112:115]
	v_mfma_f32_16x16x32_bf16 v[100:103], v[160:163], v[184:187], v[100:103]
	v_mfma_f32_16x16x32_bf16 v[96:99], v[168:171], v[184:187], v[96:99]
	v_mfma_f32_16x16x32_bf16 v[84:87], v[160:163], v[202:205], v[84:87]
	v_mfma_f32_16x16x32_bf16 v[80:83], v[168:171], v[202:205], v[80:83]
	v_mfma_f32_16x16x32_bf16 v[68:71], v[160:163], v[210:213], v[68:71]
	v_mfma_f32_16x16x32_bf16 v[64:67], v[168:171], v[210:213], v[64:67]
	v_mfma_f32_16x16x32_bf16 v[116:119], v[164:167], v[180:183], v[116:119]
	v_mfma_f32_16x16x32_bf16 v[112:115], v[172:175], v[180:183], v[112:115]
	v_mfma_f32_16x16x32_bf16 v[100:103], v[164:167], v[198:201], v[100:103]
	v_mfma_f32_16x16x32_bf16 v[96:99], v[172:175], v[198:201], v[96:99]
	v_mfma_f32_16x16x32_bf16 v[84:87], v[164:167], v[206:209], v[84:87]
	v_mfma_f32_16x16x32_bf16 v[80:83], v[172:175], v[206:209], v[80:83]
	v_mfma_f32_16x16x32_bf16 v[68:71], v[164:167], v[214:217], v[68:71]
	v_mfma_f32_16x16x32_bf16 v[64:67], v[172:175], v[214:217], v[64:67]
	s_setprio 0
	s_barrier
	s_add_i32 s47, s47, s26
	v_lshl_add_u64 v[218:219], s[18:19], 0, v[132:133]
	s_mov_b32 m0, s47
	ds_read_b128 v[176:179], v147 offset:16384
	ds_read_b128 v[180:183], v147 offset:17408
	ds_read_b128 v[184:187], v147 offset:18432
	ds_read_b128 v[198:201], v147 offset:19456
	ds_read_b128 v[202:205], v147 offset:20480
	ds_read_b128 v[206:209], v147 offset:21504
	ds_read_b128 v[210:213], v147 offset:22528
	ds_read_b128 v[214:217], v147 offset:23552
	global_load_lds_dwordx4 v[218:219], off
	s_add_i32 m0, s47, 0x2000
	s_add_u32 s48, s18, 0x4000
	v_lshl_add_u64 v[220:221], s[18:19], 0, v[128:129]
	s_addc_u32 s49, s19, 0
	s_add_i32 s47, s50, s26
	global_load_lds_dwordx4 v[220:221], off
	v_lshl_add_u64 v[222:223], s[48:49], 0, v[132:133]
	s_mov_b32 m0, s47
	v_lshl_add_u64 v[228:229], s[20:21], 0, v[130:131]
	global_load_lds_dwordx4 v[222:223], off
	v_lshl_add_u64 v[222:223], s[48:49], 0, v[128:129]
	s_add_i32 m0, s47, 0x2000
	s_nop 0
	global_load_lds_dwordx4 v[222:223], off
	v_lshl_add_u64 v[222:223], s[20:21], 0, v[134:135]
	s_mov_b32 m0, s27
	s_nop 0
	global_load_lds_dwordx4 v[222:223], off
	s_mov_b32 m0, s28
	s_nop 0
	global_load_lds_dwordx4 v[228:229], off
	s_waitcnt vmcnt(8)
	s_waitcnt lgkmcnt(0)
	s_barrier
; #define PG8_STAGE(bufoff, gbase, voff) do { _Pragma("unroll") for (int _i = 0; _i < 2; ++_i) \
;         __builtin_amdgcn_global_load_lds((const unsigned*)((const char*)(gbase) + (voff)[_i]), (LAS unsigned*)(lds + (bufoff) + ldsw + _i * 8192), 16, 0, 0); } while (0)
; #define PG8_LDA(dst, b, h) do { _Pragma("unroll") for (int m = 0; m < 4; ++m) _Pragma("unroll") for (int k = 0; k < 2; ++k) dst[m][k] = *(const LAS bf16x8*)(lds + PG8_SA(b, h) + aoff + m * 2048 + k * 1024); } while (0)
; #define PG8_LDB(dst, b, h) do { _Pragma("unroll") for (int n = 0; n < 2; ++n) _Pragma("unroll") for (int k = 0; k < 2; ++k) dst[n][k] = *(const LAS bf16x8*)(lds + PG8_SB(b, h) + boff + n * 2048 + k * 1024); } while (0)
; #define PG8_MMA(ai, bj, At, Bt) do { __builtin_amdgcn_s_setprio(1); _Pragma("unroll") for (int m = 0; m < 4; ++m) _Pragma("unroll") for (int n = 0; n < 2; ++n) _Pragma("unroll") for (int k = 0; k < 2; ++k) \
;         acc[ai][bj][m][n] = __builtin_amdgcn_mfma_f32_16x16x32_bf16(Bt[n][k], At[m][k], acc[ai][bj][m][n], 0, 0, 0); __builtin_amdgcn_s_setprio(0); } while (0)
; #define PG8_WAIT_V(n) asm volatile("s_waitcnt vmcnt(" #n ")" ::: "memory")
; #define PG8_WAIT_L(n) asm volatile("s_waitcnt lgkmcnt(" #n ")" ::: "memory")
; #define PG8_BAR __builtin_amdgcn_s_barrier()
; #define PG8_SCHED __builtin_amdgcn_sched_barrier(0)
; template <class Epi, class Sched>
; __device__ __forceinline__ void gemm_phase(int wv, LAS unsigned char* lds, const Gemm g, const Sched& S, const Epi& E) {
;     ...
;             PG8_WAIT_V(8); PG8_WAIT_L(0); PG8_BAR; PG8_MMA(1, 0, At, B0); PG8_MMA(1, 1, At, B1); PG8_BAR; PG8_SCHED;
;             PG8_LDB(B0, 1, 0); PG8_LDB(B1, 1, 1); PG8_SCHED; PG8_LDA(At, 1, 0); PG8_STAGE(PG8_SA(0, 1), a2 + hstep, voffA);
;             PG8_WAIT_V(8); PG8_WAIT_L(0); PG8_BAR; PG8_MMA(0, 0, At, B0); PG8_MMA(0, 1, At, B1); PG8_BAR; PG8_SCHED;
	s_setprio 1
	s_waitcnt lgkmcnt(0)
	v_mfma_f32_16x16x32_bf16 v[60:63], v[140:143], v[176:179], v[60:63]
	v_mfma_f32_16x16x32_bf16 v[56:59], v[152:155], v[176:179], v[56:59]
	v_mfma_f32_16x16x32_bf16 v[44:47], v[140:143], v[184:187], v[44:47]
	v_mfma_f32_16x16x32_bf16 v[40:43], v[152:155], v[184:187], v[40:43]
	v_mfma_f32_16x16x32_bf16 v[28:31], v[140:143], v[202:205], v[28:31]
	v_mfma_f32_16x16x32_bf16 v[24:27], v[152:155], v[202:205], v[24:27]
	v_mfma_f32_16x16x32_bf16 v[12:15], v[140:143], v[210:213], v[12:15]
	v_mfma_f32_16x16x32_bf16 v[8:11], v[152:155], v[210:213], v[8:11]
	v_mfma_f32_16x16x32_bf16 v[60:63], v[148:151], v[180:183], v[60:63]
	v_mfma_f32_16x16x32_bf16 v[56:59], v[156:159], v[180:183], v[56:59]
	v_mfma_f32_16x16x32_bf16 v[44:47], v[148:151], v[198:201], v[44:47]
	v_mfma_f32_16x16x32_bf16 v[40:43], v[156:159], v[198:201], v[40:43]
	v_mfma_f32_16x16x32_bf16 v[28:31], v[148:151], v[206:209], v[28:31]
	v_mfma_f32_16x16x32_bf16 v[24:27], v[156:159], v[206:209], v[24:27]
	v_mfma_f32_16x16x32_bf16 v[12:15], v[148:151], v[214:217], v[12:15]
	v_mfma_f32_16x16x32_bf16 v[8:11], v[156:159], v[214:217], v[8:11]
	v_mfma_f32_16x16x32_bf16 v[52:55], v[160:163], v[176:179], v[52:55]
	v_mfma_f32_16x16x32_bf16 v[48:51], v[168:171], v[176:179], v[48:51]
	v_mfma_f32_16x16x32_bf16 v[36:39], v[160:163], v[184:187], v[36:39]
	v_mfma_f32_16x16x32_bf16 v[32:35], v[168:171], v[184:187], v[32:35]
	v_mfma_f32_16x16x32_bf16 v[20:23], v[160:163], v[202:205], v[20:23]
	v_mfma_f32_16x16x32_bf16 v[16:19], v[168:171], v[202:205], v[16:19]
	v_mfma_f32_16x16x32_bf16 v[4:7], v[160:163], v[210:213], v[4:7]
	v_mfma_f32_16x16x32_bf16 v[0:3], v[168:171], v[210:213], v[0:3]
	v_mfma_f32_16x16x32_bf16 v[52:55], v[164:167], v[180:183], v[52:55]
	v_mfma_f32_16x16x32_bf16 v[48:51], v[172:175], v[180:183], v[48:51]
	v_mfma_f32_16x16x32_bf16 v[36:39], v[164:167], v[198:201], v[36:39]
	v_mfma_f32_16x16x32_bf16 v[32:35], v[172:175], v[198:201], v[32:35]
	v_mfma_f32_16x16x32_bf16 v[20:23], v[164:167], v[206:209], v[20:23]
	v_mfma_f32_16x16x32_bf16 v[16:19], v[172:175], v[206:209], v[16:19]
	v_mfma_f32_16x16x32_bf16 v[4:7], v[164:167], v[214:217], v[4:7]
	v_mfma_f32_16x16x32_bf16 v[0:3], v[172:175], v[214:217], v[0:3]
	s_setprio 0
	s_barrier
	s_add_i32 s47, 0, 0x18000
	s_add_i32 s48, 0, 0x1c000
	v_add_u32_e32 v156, s47, v145
	v_add_u32_e32 v172, s48, v145
	ds_read_b128 v[140:143], v156
	ds_read_b128 v[148:151], v156 offset:1024
	ds_read_b128 v[152:155], v156 offset:2048
	ds_read_b128 v[156:159], v156 offset:3072
	ds_read_b128 v[160:163], v172
	ds_read_b128 v[164:167], v172 offset:1024
	ds_read_b128 v[168:171], v172 offset:2048
	ds_read_b128 v[172:175], v172 offset:3072
	s_add_u32 s20, s20, 0x40000
	s_addc_u32 s21, s21, 0
	s_mov_b32 m0, s29
	v_lshl_add_u64 v[230:231], s[20:21], 0, v[134:135]
	ds_read_b128 v[176:179], v147 offset:32768
	ds_read_b128 v[180:183], v147 offset:33792
	ds_read_b128 v[184:187], v147 offset:34816
	ds_read_b128 v[198:201], v147 offset:35840
	ds_read_b128 v[202:205], v147 offset:36864
	ds_read_b128 v[206:209], v147 offset:37888
	ds_read_b128 v[210:213], v147 offset:38912
	ds_read_b128 v[214:217], v147 offset:39936
	global_load_lds_dwordx4 v[230:231], off
	v_lshl_add_u64 v[230:231], s[20:21], 0, v[130:131]
	s_mov_b32 m0, s30
	s_nop 0
	global_load_lds_dwordx4 v[230:231], off
	s_waitcnt vmcnt(8)
	s_waitcnt lgkmcnt(0)
	s_barrier
	s_setprio 1
	s_waitcnt lgkmcnt(0)
	v_mfma_f32_16x16x32_bf16 v[124:127], v[140:143], v[176:179], v[124:127]
	v_mfma_f32_16x16x32_bf16 v[120:123], v[152:155], v[176:179], v[120:123]
	v_mfma_f32_16x16x32_bf16 v[108:111], v[140:143], v[184:187], v[108:111]
	v_mfma_f32_16x16x32_bf16 v[104:107], v[152:155], v[184:187], v[104:107]
	v_mfma_f32_16x16x32_bf16 v[92:95], v[140:143], v[202:205], v[92:95]
	v_mfma_f32_16x16x32_bf16 v[88:91], v[152:155], v[202:205], v[88:91]
	v_mfma_f32_16x16x32_bf16 v[76:79], v[140:143], v[210:213], v[76:79]
	v_mfma_f32_16x16x32_bf16 v[72:75], v[152:155], v[210:213], v[72:75]
	v_mfma_f32_16x16x32_bf16 v[124:127], v[148:151], v[180:183], v[124:127]
	v_mfma_f32_16x16x32_bf16 v[120:123], v[156:159], v[180:183], v[120:123]
	v_mfma_f32_16x16x32_bf16 v[108:111], v[148:151], v[198:201], v[108:111]
	v_mfma_f32_16x16x32_bf16 v[104:107], v[156:159], v[198:201], v[104:107]
	v_mfma_f32_16x16x32_bf16 v[92:95], v[148:151], v[206:209], v[92:95]
	v_mfma_f32_16x16x32_bf16 v[88:91], v[156:159], v[206:209], v[88:91]
	v_mfma_f32_16x16x32_bf16 v[76:79], v[148:151], v[214:217], v[76:79]
	v_mfma_f32_16x16x32_bf16 v[72:75], v[156:159], v[214:217], v[72:75]
	v_mfma_f32_16x16x32_bf16 v[116:119], v[160:163], v[176:179], v[116:119]
	v_mfma_f32_16x16x32_bf16 v[112:115], v[168:171], v[176:179], v[112:115]
	v_mfma_f32_16x16x32_bf16 v[100:103], v[160:163], v[184:187], v[100:103]
	v_mfma_f32_16x16x32_bf16 v[96:99], v[168:171], v[184:187], v[96:99]
	v_mfma_f32_16x16x32_bf16 v[84:87], v[160:163], v[202:205], v[84:87]
	v_mfma_f32_16x16x32_bf16 v[80:83], v[168:171], v[202:205], v[80:83]
	v_mfma_f32_16x16x32_bf16 v[68:71], v[160:163], v[210:213], v[68:71]
	v_mfma_f32_16x16x32_bf16 v[64:67], v[168:171], v[210:213], v[64:67]
	v_mfma_f32_16x16x32_bf16 v[116:119], v[164:167], v[180:183], v[116:119]
	v_mfma_f32_16x16x32_bf16 v[112:115], v[172:175], v[180:183], v[112:115]
	v_mfma_f32_16x16x32_bf16 v[100:103], v[164:167], v[198:201], v[100:103]
	v_mfma_f32_16x16x32_bf16 v[96:99], v[172:175], v[198:201], v[96:99]
	v_mfma_f32_16x16x32_bf16 v[84:87], v[164:167], v[206:209], v[84:87]
	v_mfma_f32_16x16x32_bf16 v[80:83], v[172:175], v[206:209], v[80:83]
	v_mfma_f32_16x16x32_bf16 v[68:71], v[164:167], v[214:217], v[68:71]
	v_mfma_f32_16x16x32_bf16 v[64:67], v[172:175], v[214:217], v[64:67]
	s_setprio 0
	s_barrier
; #define PG8_STAGE(bufoff, gbase, voff) do { _Pragma("unroll") for (int _i = 0; _i < 2; ++_i) \
;         __builtin_amdgcn_global_load_lds((const unsigned*)((const char*)(gbase) + (voff)[_i]), (LAS unsigned*)(lds + (bufoff) + ldsw + _i * 8192), 16, 0, 0); } while (0)
; #define PG8_LDA(dst, b, h) do { _Pragma("unroll") for (int m = 0; m < 4; ++m) _Pragma("unroll") for (int k = 0; k < 2; ++k) dst[m][k] = *(const LAS bf16x8*)(lds + PG8_SA(b, h) + aoff + m * 2048 + k * 1024); } while (0)
; #define PG8_MMA(ai, bj, At, Bt) do { __builtin_amdgcn_s_setprio(1); _Pragma("unroll") for (int m = 0; m < 4; ++m) _Pragma("unroll") for (int n = 0; n < 2; ++n) _Pragma("unroll") for (int k = 0; k < 2; ++k) \
;         acc[ai][bj][m][n] = __builtin_amdgcn_mfma_f32_16x16x32_bf16(Bt[n][k], At[m][k], acc[ai][bj][m][n], 0, 0, 0); __builtin_amdgcn_s_setprio(0); } while (0)
; #define PG8_WAIT_V(n) asm volatile("s_waitcnt vmcnt(" #n ")" ::: "memory")
; #define PG8_WAIT_L(n) asm volatile("s_waitcnt lgkmcnt(" #n ")" ::: "memory")
; #define PG8_BAR __builtin_amdgcn_s_barrier()
; #define PG8_SCHED __builtin_amdgcn_sched_barrier(0)
; template <class Epi, class Sched>
; __device__ __forceinline__ void gemm_phase(int wv, LAS unsigned char* lds, const Gemm g, const Sched& S, const Epi& E) {
;     ...
;             PG8_LDA(At, 1, 1); PG8_STAGE(PG8_SB(1, 0), b3, voffB); PG8_STAGE(PG8_SB(1, 1), b3 + hstepB, voffB); PG8_STAGE(PG8_SA(1, 0), a3, voffA);
;             PG8_WAIT_V(8); PG8_WAIT_L(0); PG8_BAR; PG8_MMA(1, 0, At, B0); PG8_MMA(1, 1, At, B1); PG8_BAR; PG8_SCHED;
;         }
	s_add_i32 s20, s47, s26
	v_lshl_add_u64 v[218:219], v[218:219], 0, s[74:75]
	s_mov_b32 m0, s20
	ds_read_b128 v[176:179], v147 offset:49152
	ds_read_b128 v[180:183], v147 offset:50176
	ds_read_b128 v[184:187], v147 offset:51200
	ds_read_b128 v[198:201], v147 offset:52224
	ds_read_b128 v[202:205], v147 offset:53248
	ds_read_b128 v[206:209], v147 offset:54272
	ds_read_b128 v[210:213], v147 offset:55296
	ds_read_b128 v[214:217], v147 offset:56320
	global_load_lds_dwordx4 v[218:219], off
	s_add_i32 m0, s20, 0x2000
	s_add_u32 s18, s18, 0x4080
	v_lshl_add_u64 v[218:219], v[220:221], 0, s[74:75]
	s_addc_u32 s19, s19, 0
	s_add_i32 s20, s48, s26
	global_load_lds_dwordx4 v[218:219], off
	v_lshl_add_u64 v[218:219], s[18:19], 0, v[132:133]
	s_mov_b32 m0, s20
	s_nop 0
	global_load_lds_dwordx4 v[218:219], off
	v_lshl_add_u64 v[218:219], s[18:19], 0, v[128:129]
	s_add_i32 m0, s20, 0x2000
	s_nop 0
	global_load_lds_dwordx4 v[218:219], off
	v_lshl_add_u64 v[218:219], v[222:223], 0, s[74:75]
	s_mov_b32 m0, s37
	s_nop 0
	global_load_lds_dwordx4 v[218:219], off
	v_lshl_add_u64 v[218:219], v[228:229], 0, s[74:75]
	s_mov_b32 m0, s38
	s_nop 0
	global_load_lds_dwordx4 v[218:219], off
	s_waitcnt vmcnt(8)
	s_waitcnt lgkmcnt(0)
	s_barrier
	s_setprio 1
	s_waitcnt lgkmcnt(0)
	v_mfma_f32_16x16x32_bf16 v[60:63], v[140:143], v[176:179], v[60:63]
	v_mfma_f32_16x16x32_bf16 v[56:59], v[152:155], v[176:179], v[56:59]
	v_mfma_f32_16x16x32_bf16 v[44:47], v[140:143], v[184:187], v[44:47]
	v_mfma_f32_16x16x32_bf16 v[40:43], v[152:155], v[184:187], v[40:43]
	v_mfma_f32_16x16x32_bf16 v[28:31], v[140:143], v[202:205], v[28:31]
	v_mfma_f32_16x16x32_bf16 v[24:27], v[152:155], v[202:205], v[24:27]
	v_mfma_f32_16x16x32_bf16 v[12:15], v[140:143], v[210:213], v[12:15]
	v_mfma_f32_16x16x32_bf16 v[8:11], v[152:155], v[210:213], v[8:11]
	v_mfma_f32_16x16x32_bf16 v[60:63], v[148:151], v[180:183], v[60:63]
	v_mfma_f32_16x16x32_bf16 v[56:59], v[156:159], v[180:183], v[56:59]
	v_mfma_f32_16x16x32_bf16 v[44:47], v[148:151], v[198:201], v[44:47]
	v_mfma_f32_16x16x32_bf16 v[40:43], v[156:159], v[198:201], v[40:43]
	v_mfma_f32_16x16x32_bf16 v[28:31], v[148:151], v[206:209], v[28:31]
	v_mfma_f32_16x16x32_bf16 v[24:27], v[156:159], v[206:209], v[24:27]
	v_mfma_f32_16x16x32_bf16 v[12:15], v[148:151], v[214:217], v[12:15]
	v_mfma_f32_16x16x32_bf16 v[8:11], v[156:159], v[214:217], v[8:11]
	v_mfma_f32_16x16x32_bf16 v[52:55], v[160:163], v[176:179], v[52:55]
	v_mfma_f32_16x16x32_bf16 v[48:51], v[168:171], v[176:179], v[48:51]
	v_mfma_f32_16x16x32_bf16 v[36:39], v[160:163], v[184:187], v[36:39]
	v_mfma_f32_16x16x32_bf16 v[32:35], v[168:171], v[184:187], v[32:35]
	v_mfma_f32_16x16x32_bf16 v[20:23], v[160:163], v[202:205], v[20:23]
	v_mfma_f32_16x16x32_bf16 v[16:19], v[168:171], v[202:205], v[16:19]
	v_mfma_f32_16x16x32_bf16 v[4:7], v[160:163], v[210:213], v[4:7]
	v_mfma_f32_16x16x32_bf16 v[0:3], v[168:171], v[210:213], v[0:3]
	v_mfma_f32_16x16x32_bf16 v[52:55], v[164:167], v[180:183], v[52:55]
	v_mfma_f32_16x16x32_bf16 v[48:51], v[172:175], v[180:183], v[48:51]
	v_mfma_f32_16x16x32_bf16 v[36:39], v[164:167], v[198:201], v[36:39]
	v_mfma_f32_16x16x32_bf16 v[32:35], v[172:175], v[198:201], v[32:35]
	v_mfma_f32_16x16x32_bf16 v[20:23], v[164:167], v[206:209], v[20:23]
	v_mfma_f32_16x16x32_bf16 v[16:19], v[172:175], v[206:209], v[16:19]
	v_mfma_f32_16x16x32_bf16 v[4:7], v[164:167], v[214:217], v[4:7]
	v_mfma_f32_16x16x32_bf16 v[0:3], v[172:175], v[214:217], v[0:3]
	s_setprio 0
	s_barrier
	s_add_i32 s46, s46, 2
	s_add_u32 s2, s2, 0x100
	s_addc_u32 s3, s3, 0
	s_add_u32 s43, s43, 0x100
	s_addc_u32 s45, s45, 0
	s_cmp_gt_u32 s46, 13
	s_cbranch_scc0 .LBB0_344
	s_and_b64 vcc, exec, s[8:9]
	s_cbranch_vccz .LBB0_347
	s_barrier

; #define PG8_STAGE(bufoff, gbase, voff) do { _Pragma("unroll") for (int _i = 0; _i < 2; ++_i) \
;         __builtin_amdgcn_global_load_lds((const unsigned*)((const char*)(gbase) + (voff)[_i]), (LAS unsigned*)(lds + (bufoff) + ldsw + _i * 8192), 16, 0, 0); } while (0)
; #define PG8_LDA(dst, b, h) do { _Pragma("unroll") for (int m = 0; m < 4; ++m) _Pragma("unroll") for (int k = 0; k < 2; ++k) dst[m][k] = *(const LAS bf16x8*)(lds + PG8_SA(b, h) + aoff + m * 2048 + k * 1024); } while (0)
; #define PG8_LDB(dst, b, h) do { _Pragma("unroll") for (int n = 0; n < 2; ++n) _Pragma("unroll") for (int k = 0; k < 2; ++k) dst[n][k] = *(const LAS bf16x8*)(lds + PG8_SB(b, h) + boff + n * 2048 + k * 1024); } while (0)
; #define PG8_MMA(ai, bj, At, Bt) do { __builtin_amdgcn_s_setprio(1); _Pragma("unroll") for (int m = 0; m < 4; ++m) _Pragma("unroll") for (int n = 0; n < 2; ++n) _Pragma("unroll") for (int k = 0; k < 2; ++k) \
;         acc[ai][bj][m][n] = __builtin_amdgcn_mfma_f32_16x16x32_bf16(Bt[n][k], At[m][k], acc[ai][bj][m][n], 0, 0, 0); __builtin_amdgcn_s_setprio(0); } while (0)
; #define PG8_WAIT_V(n) asm volatile("s_waitcnt vmcnt(" #n ")" ::: "memory")
; #define PG8_WAIT_L(n) asm volatile("s_waitcnt lgkmcnt(" #n ")" ::: "memory")
; #define PG8_BAR __builtin_amdgcn_s_barrier()
; #define PG8_SCHED __builtin_amdgcn_sched_barrier(0)
; template <class Epi, class Sched>
; __device__ __forceinline__ void gemm_phase(int wv, LAS unsigned char* lds, const Gemm g, const Sched& S, const Epi& E) {
;     ...
;         for (int t = 0; t < nt; t += 2) {
;             const bool last = (t == nt - 2);
;             const char* a1 = cA + (size_t)(t + 1) * kstep;
;             const char* a2 = last ? nA : cA + (size_t)(t + 2) * kstep; const char* b2 = last ? nB : cB + (size_t)(t + 2) * kstep;
;             const char* a3 = a2 + kstep; const char* b3 = b2 + kstep;
;             PG8_LDB(B0, 0, 0); PG8_LDB(B1, 0, 1); PG8_SCHED; PG8_LDA(At, 0, 0); PG8_STAGE(PG8_SA(1, 1), a1 + hstep, voffA);
;             PG8_WAIT_V(8); PG8_WAIT_L(0); PG8_BAR; PG8_MMA(0, 0, At, B0); PG8_MMA(0, 1, At, B1); PG8_BAR; PG8_SCHED;
;             PG8_LDA(At, 0, 1); PG8_STAGE(PG8_SB(0, 0), b2, voffB); PG8_STAGE(PG8_SB(0, 1), b2 + hstepB, voffB); PG8_STAGE(PG8_SA(0, 0), a2, voffA);
;             PG8_WAIT_V(8); PG8_WAIT_L(0); PG8_BAR; PG8_MMA(1, 0, At, B0); PG8_MMA(1, 1, At, B1); PG8_BAR; PG8_SCHED;
.LBB0_542:
	s_add_u32 s28, s4, 0xfffc0080
	s_addc_u32 s29, s5, -1
	s_add_i32 s55, 0, 0x10000
	s_cmp_eq_u32 s54, 12
	s_cselect_b32 s31, s21, s29
	s_cselect_b32 s30, s50, s28
	s_cselect_b32 s29, s23, s53
	s_cselect_b32 s28, s51, s52
	s_add_i32 s58, 0, 0x14000
	v_add_u32_e32 v60, s55, v206
	s_waitcnt vmcnt(0)
	v_add_u32_e32 v92, s58, v206
	ds_read_b128 v[48:51], v60
	ds_read_b128 v[52:55], v60 offset:1024
	ds_read_b128 v[56:59], v60 offset:2048
	ds_read_b128 v[60:63], v60 offset:3072
	ds_read_b128 v[64:67], v92
	ds_read_b128 v[68:71], v92 offset:1024
	ds_read_b128 v[88:91], v92 offset:2048
	ds_read_b128 v[92:95], v92 offset:3072
	v_lshl_add_u64 v[222:223], s[4:5], 0, v[174:175]
	s_add_i32 m0, s41, 0xc000
	ds_read_b128 v[180:183], v209
	ds_read_b128 v[184:187], v209 offset:1024
	ds_read_b128 v[198:201], v209 offset:2048
	ds_read_b128 v[202:205], v209 offset:3072
	ds_read_b128 v[210:213], v209 offset:4096
	ds_read_b128 v[214:217], v209 offset:5120
	ds_read_b128 v[218:221], v209 offset:6144
	ds_read_b128 v[228:231], v209 offset:7168
	global_load_lds_dwordx4 v[222:223], off
	v_lshl_add_u64 v[222:223], s[4:5], 0, v[176:177]
	s_add_i32 m0, s41, 0xe000
	s_nop 0
	global_load_lds_dwordx4 v[222:223], off
	s_waitcnt vmcnt(8)
	s_waitcnt lgkmcnt(0)
	s_barrier
	s_setprio 1
	s_waitcnt lgkmcnt(0)
	v_mfma_f32_16x16x32_bf16 v[156:159], v[48:51], v[180:183], v[156:159]
	v_mfma_f32_16x16x32_bf16 v[152:155], v[56:59], v[180:183], v[152:155]
	v_mfma_f32_16x16x32_bf16 v[140:143], v[48:51], v[198:201], v[140:143]
	v_mfma_f32_16x16x32_bf16 v[136:139], v[56:59], v[198:201], v[136:139]
	v_mfma_f32_16x16x32_bf16 v[124:127], v[48:51], v[210:213], v[124:127]
	v_mfma_f32_16x16x32_bf16 v[120:123], v[56:59], v[210:213], v[120:123]
	v_mfma_f32_16x16x32_bf16 v[108:111], v[48:51], v[218:221], v[108:111]
	v_mfma_f32_16x16x32_bf16 v[104:107], v[56:59], v[218:221], v[104:107]
	v_mfma_f32_16x16x32_bf16 v[156:159], v[52:55], v[184:187], v[156:159]
	v_mfma_f32_16x16x32_bf16 v[152:155], v[60:63], v[184:187], v[152:155]
	v_mfma_f32_16x16x32_bf16 v[140:143], v[52:55], v[202:205], v[140:143]
	v_mfma_f32_16x16x32_bf16 v[136:139], v[60:63], v[202:205], v[136:139]
	v_mfma_f32_16x16x32_bf16 v[124:127], v[52:55], v[214:217], v[124:127]
	v_mfma_f32_16x16x32_bf16 v[120:123], v[60:63], v[214:217], v[120:123]
	v_mfma_f32_16x16x32_bf16 v[108:111], v[52:55], v[228:231], v[108:111]
	v_mfma_f32_16x16x32_bf16 v[104:107], v[60:63], v[228:231], v[104:107]
	v_mfma_f32_16x16x32_bf16 v[148:151], v[64:67], v[180:183], v[148:151]
	v_mfma_f32_16x16x32_bf16 v[144:147], v[88:91], v[180:183], v[144:147]
	v_mfma_f32_16x16x32_bf16 v[132:135], v[64:67], v[198:201], v[132:135]
	v_mfma_f32_16x16x32_bf16 v[128:131], v[88:91], v[198:201], v[128:131]
	v_mfma_f32_16x16x32_bf16 v[116:119], v[64:67], v[210:213], v[116:119]
	v_mfma_f32_16x16x32_bf16 v[112:115], v[88:91], v[210:213], v[112:115]
	v_mfma_f32_16x16x32_bf16 v[100:103], v[64:67], v[218:221], v[100:103]
	v_mfma_f32_16x16x32_bf16 v[96:99], v[88:91], v[218:221], v[96:99]
	v_mfma_f32_16x16x32_bf16 v[148:151], v[68:71], v[184:187], v[148:151]
	v_mfma_f32_16x16x32_bf16 v[144:147], v[92:95], v[184:187], v[144:147]
	v_mfma_f32_16x16x32_bf16 v[132:135], v[68:71], v[202:205], v[132:135]
	v_mfma_f32_16x16x32_bf16 v[128:131], v[92:95], v[202:205], v[128:131]
	v_mfma_f32_16x16x32_bf16 v[116:119], v[68:71], v[214:217], v[116:119]
	v_mfma_f32_16x16x32_bf16 v[112:115], v[92:95], v[214:217], v[112:115]
	v_mfma_f32_16x16x32_bf16 v[100:103], v[68:71], v[228:231], v[100:103]
	v_mfma_f32_16x16x32_bf16 v[96:99], v[92:95], v[228:231], v[96:99]
	s_setprio 0
	s_barrier
	s_add_i32 s55, s55, s40
	v_lshl_add_u64 v[222:223], s[28:29], 0, v[164:165]
	s_mov_b32 m0, s55
	ds_read_b128 v[180:183], v209 offset:16384
	ds_read_b128 v[184:187], v209 offset:17408
	ds_read_b128 v[198:201], v209 offset:18432
	ds_read_b128 v[202:205], v209 offset:19456
	ds_read_b128 v[210:213], v209 offset:20480
	ds_read_b128 v[214:217], v209 offset:21504
	ds_read_b128 v[218:221], v209 offset:22528
	ds_read_b128 v[228:231], v209 offset:23552
	global_load_lds_dwordx4 v[222:223], off
	s_add_i32 m0, s55, 0x2000
	s_add_u32 s56, s28, 0x20000
	v_lshl_add_u64 v[240:241], s[28:29], 0, v[160:161]
	s_addc_u32 s57, s29, 0
	s_add_i32 s55, s58, s40
	global_load_lds_dwordx4 v[240:241], off
	v_lshl_add_u64 v[232:233], s[56:57], 0, v[164:165]
	s_mov_b32 m0, s55
	v_lshl_add_u64 v[242:243], s[30:31], 0, v[166:167]
	global_load_lds_dwordx4 v[232:233], off
	v_lshl_add_u64 v[232:233], s[56:57], 0, v[160:161]
	s_add_i32 m0, s55, 0x2000
	v_lshl_add_u64 v[244:245], s[30:31], 0, v[162:163]
	global_load_lds_dwordx4 v[232:233], off
	s_mov_b32 m0, s41
	s_nop 0
	global_load_lds_dwordx4 v[242:243], off
	s_mov_b32 m0, s42
	s_nop 0
	global_load_lds_dwordx4 v[244:245], off
	s_waitcnt vmcnt(8)
	s_waitcnt lgkmcnt(0)
	s_barrier
; #define PG8_STAGE(bufoff, gbase, voff) do { _Pragma("unroll") for (int _i = 0; _i < 2; ++_i) \
;         __builtin_amdgcn_global_load_lds((const unsigned*)((const char*)(gbase) + (voff)[_i]), (LAS unsigned*)(lds + (bufoff) + ldsw + _i * 8192), 16, 0, 0); } while (0)
; #define PG8_LDA(dst, b, h) do { _Pragma("unroll") for (int m = 0; m < 4; ++m) _Pragma("unroll") for (int k = 0; k < 2; ++k) dst[m][k] = *(const LAS bf16x8*)(lds + PG8_SA(b, h) + aoff + m * 2048 + k * 1024); } while (0)
; #define PG8_LDB(dst, b, h) do { _Pragma("unroll") for (int n = 0; n < 2; ++n) _Pragma("unroll") for (int k = 0; k < 2; ++k) dst[n][k] = *(const LAS bf16x8*)(lds + PG8_SB(b, h) + boff + n * 2048 + k * 1024); } while (0)
; #define PG8_MMA(ai, bj, At, Bt) do { __builtin_amdgcn_s_setprio(1); _Pragma("unroll") for (int m = 0; m < 4; ++m) _Pragma("unroll") for (int n = 0; n < 2; ++n) _Pragma("unroll") for (int k = 0; k < 2; ++k) \
;         acc[ai][bj][m][n] = __builtin_amdgcn_mfma_f32_16x16x32_bf16(Bt[n][k], At[m][k], acc[ai][bj][m][n], 0, 0, 0); __builtin_amdgcn_s_setprio(0); } while (0)
; #define PG8_WAIT_V(n) asm volatile("s_waitcnt vmcnt(" #n ")" ::: "memory")
; #define PG8_WAIT_L(n) asm volatile("s_waitcnt lgkmcnt(" #n ")" ::: "memory")
; #define PG8_BAR __builtin_amdgcn_s_barrier()
; #define PG8_SCHED __builtin_amdgcn_sched_barrier(0)
; template <class Epi, class Sched>
; __device__ __forceinline__ void gemm_phase(int wv, LAS unsigned char* lds, const Gemm g, const Sched& S, const Epi& E) {
;     ...
;             PG8_WAIT_V(8); PG8_WAIT_L(0); PG8_BAR; PG8_MMA(1, 0, At, B0); PG8_MMA(1, 1, At, B1); PG8_BAR; PG8_SCHED;
;             PG8_LDB(B0, 1, 0); PG8_LDB(B1, 1, 1); PG8_SCHED; PG8_LDA(At, 1, 0); PG8_STAGE(PG8_SA(0, 1), a2 + hstep, voffA);
;             PG8_WAIT_V(8); PG8_WAIT_L(0); PG8_BAR; PG8_MMA(0, 0, At, B0); PG8_MMA(0, 1, At, B1); PG8_BAR; PG8_SCHED;
	s_setprio 1
	s_waitcnt lgkmcnt(0)
	v_mfma_f32_16x16x32_bf16 v[84:87], v[48:51], v[180:183], v[84:87]
	v_mfma_f32_16x16x32_bf16 v[80:83], v[56:59], v[180:183], v[80:83]
	v_mfma_f32_16x16x32_bf16 v[44:47], v[48:51], v[198:201], v[44:47]
	v_mfma_f32_16x16x32_bf16 v[40:43], v[56:59], v[198:201], v[40:43]
	v_mfma_f32_16x16x32_bf16 v[28:31], v[48:51], v[210:213], v[28:31]
	v_mfma_f32_16x16x32_bf16 v[24:27], v[56:59], v[210:213], v[24:27]
	v_mfma_f32_16x16x32_bf16 v[12:15], v[48:51], v[218:221], v[12:15]
	v_mfma_f32_16x16x32_bf16 v[8:11], v[56:59], v[218:221], v[8:11]
	v_mfma_f32_16x16x32_bf16 v[84:87], v[52:55], v[184:187], v[84:87]
	v_mfma_f32_16x16x32_bf16 v[80:83], v[60:63], v[184:187], v[80:83]
	v_mfma_f32_16x16x32_bf16 v[44:47], v[52:55], v[202:205], v[44:47]
	v_mfma_f32_16x16x32_bf16 v[40:43], v[60:63], v[202:205], v[40:43]
	v_mfma_f32_16x16x32_bf16 v[28:31], v[52:55], v[214:217], v[28:31]
	v_mfma_f32_16x16x32_bf16 v[24:27], v[60:63], v[214:217], v[24:27]
	v_mfma_f32_16x16x32_bf16 v[12:15], v[52:55], v[228:231], v[12:15]
	v_mfma_f32_16x16x32_bf16 v[8:11], v[60:63], v[228:231], v[8:11]
	v_mfma_f32_16x16x32_bf16 v[36:39], v[64:67], v[198:201], v[36:39]
	v_mfma_f32_16x16x32_bf16 v[32:35], v[88:91], v[198:201], v[32:35]
	v_mfma_f32_16x16x32_bf16 v[20:23], v[64:67], v[210:213], v[20:23]
	v_mfma_f32_16x16x32_bf16 v[16:19], v[88:91], v[210:213], v[16:19]
	v_mfma_f32_16x16x32_bf16 v[4:7], v[64:67], v[218:221], v[4:7]
	v_mfma_f32_16x16x32_bf16 v[0:3], v[88:91], v[218:221], v[0:3]
	v_mfma_f32_16x16x32_bf16 v[48:51], v[64:67], v[180:183], v[76:79]
	v_mfma_f32_16x16x32_bf16 v[52:55], v[88:91], v[180:183], v[72:75]
	v_mfma_f32_16x16x32_bf16 v[36:39], v[68:71], v[202:205], v[36:39]
	v_mfma_f32_16x16x32_bf16 v[32:35], v[92:95], v[202:205], v[32:35]
	v_mfma_f32_16x16x32_bf16 v[20:23], v[68:71], v[214:217], v[20:23]
	v_mfma_f32_16x16x32_bf16 v[16:19], v[92:95], v[214:217], v[16:19]
	v_mfma_f32_16x16x32_bf16 v[4:7], v[68:71], v[228:231], v[4:7]
	v_mfma_f32_16x16x32_bf16 v[0:3], v[92:95], v[228:231], v[0:3]
	v_mfma_f32_16x16x32_bf16 v[48:51], v[68:71], v[184:187], v[48:51]
	v_mfma_f32_16x16x32_bf16 v[52:55], v[92:95], v[184:187], v[52:55]
	s_setprio 0
	s_barrier
	s_add_i32 s55, 0, 0x1c000
	v_add_u32_e32 v68, s95, v206
	v_add_u32_e32 v72, s55, v206
	ds_read_b128 v[56:59], v68
	ds_read_b128 v[60:63], v68 offset:1024
	ds_read_b128 v[64:67], v68 offset:2048
	ds_read_b128 v[68:71], v68 offset:3072
	ds_read_b128 v[88:91], v72
	ds_read_b128 v[92:95], v72 offset:1024
	ds_read_b128 v[180:183], v72 offset:2048
	ds_read_b128 v[184:187], v72 offset:3072
	s_add_u32 s30, s30, 0x40000
	s_addc_u32 s31, s31, 0
	s_mov_b32 m0, s43
	v_lshl_add_u64 v[232:233], s[30:31], 0, v[166:167]
	ds_read_b128 v[72:75], v209 offset:32768
	ds_read_b128 v[76:79], v209 offset:33792
	ds_read_b128 v[198:201], v209 offset:34816
	ds_read_b128 v[202:205], v209 offset:35840
	ds_read_b128 v[210:213], v209 offset:36864
	ds_read_b128 v[214:217], v209 offset:37888
	ds_read_b128 v[218:221], v209 offset:38912
	ds_read_b128 v[228:231], v209 offset:39936
	global_load_lds_dwordx4 v[232:233], off
	v_lshl_add_u64 v[232:233], s[30:31], 0, v[162:163]
	s_mov_b32 m0, s45
	s_nop 0
	global_load_lds_dwordx4 v[232:233], off
	s_waitcnt vmcnt(8)
	s_waitcnt lgkmcnt(0)
	s_barrier
	s_setprio 1
	s_waitcnt lgkmcnt(0)
	v_mfma_f32_16x16x32_bf16 v[156:159], v[56:59], v[72:75], v[156:159]
	v_mfma_f32_16x16x32_bf16 v[152:155], v[64:67], v[72:75], v[152:155]
	v_mfma_f32_16x16x32_bf16 v[140:143], v[56:59], v[198:201], v[140:143]
	v_mfma_f32_16x16x32_bf16 v[136:139], v[64:67], v[198:201], v[136:139]
	v_mfma_f32_16x16x32_bf16 v[124:127], v[56:59], v[210:213], v[124:127]
	v_mfma_f32_16x16x32_bf16 v[120:123], v[64:67], v[210:213], v[120:123]
	v_mfma_f32_16x16x32_bf16 v[108:111], v[56:59], v[218:221], v[108:111]
	v_mfma_f32_16x16x32_bf16 v[104:107], v[64:67], v[218:221], v[104:107]
	v_mfma_f32_16x16x32_bf16 v[156:159], v[60:63], v[76:79], v[156:159]
	v_mfma_f32_16x16x32_bf16 v[152:155], v[68:71], v[76:79], v[152:155]
	v_mfma_f32_16x16x32_bf16 v[140:143], v[60:63], v[202:205], v[140:143]
	v_mfma_f32_16x16x32_bf16 v[136:139], v[68:71], v[202:205], v[136:139]
	v_mfma_f32_16x16x32_bf16 v[124:127], v[60:63], v[214:217], v[124:127]
	v_mfma_f32_16x16x32_bf16 v[120:123], v[68:71], v[214:217], v[120:123]
	v_mfma_f32_16x16x32_bf16 v[108:111], v[60:63], v[228:231], v[108:111]
	v_mfma_f32_16x16x32_bf16 v[104:107], v[68:71], v[228:231], v[104:107]
	v_mfma_f32_16x16x32_bf16 v[148:151], v[88:91], v[72:75], v[148:151]
	v_mfma_f32_16x16x32_bf16 v[72:75], v[180:183], v[72:75], v[144:147]
	v_mfma_f32_16x16x32_bf16 v[144:147], v[184:187], v[76:79], v[72:75]
	v_mfma_f32_16x16x32_bf16 v[72:75], v[88:91], v[198:201], v[132:135]
	v_mfma_f32_16x16x32_bf16 v[132:135], v[92:95], v[202:205], v[72:75]
	v_mfma_f32_16x16x32_bf16 v[72:75], v[180:183], v[198:201], v[128:131]
	v_mfma_f32_16x16x32_bf16 v[128:131], v[184:187], v[202:205], v[72:75]
	v_mfma_f32_16x16x32_bf16 v[72:75], v[88:91], v[210:213], v[116:119]
	v_mfma_f32_16x16x32_bf16 v[116:119], v[92:95], v[214:217], v[72:75]
	v_mfma_f32_16x16x32_bf16 v[72:75], v[180:183], v[210:213], v[112:115]
	v_mfma_f32_16x16x32_bf16 v[112:115], v[184:187], v[214:217], v[72:75]
	v_mfma_f32_16x16x32_bf16 v[72:75], v[88:91], v[218:221], v[100:103]
	v_mfma_f32_16x16x32_bf16 v[100:103], v[92:95], v[228:231], v[72:75]
	v_mfma_f32_16x16x32_bf16 v[72:75], v[180:183], v[218:221], v[96:99]
	v_mfma_f32_16x16x32_bf16 v[148:151], v[92:95], v[76:79], v[148:151]
	v_mfma_f32_16x16x32_bf16 v[96:99], v[184:187], v[228:231], v[72:75]
	s_setprio 0
	s_barrier
; #define PG8_STAGE(bufoff, gbase, voff) do { _Pragma("unroll") for (int _i = 0; _i < 2; ++_i) \
;         __builtin_amdgcn_global_load_lds((const unsigned*)((const char*)(gbase) + (voff)[_i]), (LAS unsigned*)(lds + (bufoff) + ldsw + _i * 8192), 16, 0, 0); } while (0)
; #define PG8_LDA(dst, b, h) do { _Pragma("unroll") for (int m = 0; m < 4; ++m) _Pragma("unroll") for (int k = 0; k < 2; ++k) dst[m][k] = *(const LAS bf16x8*)(lds + PG8_SA(b, h) + aoff + m * 2048 + k * 1024); } while (0)
; #define PG8_MMA(ai, bj, At, Bt) do { __builtin_amdgcn_s_setprio(1); _Pragma("unroll") for (int m = 0; m < 4; ++m) _Pragma("unroll") for (int n = 0; n < 2; ++n) _Pragma("unroll") for (int k = 0; k < 2; ++k) \
;         acc[ai][bj][m][n] = __builtin_amdgcn_mfma_f32_16x16x32_bf16(Bt[n][k], At[m][k], acc[ai][bj][m][n], 0, 0, 0); __builtin_amdgcn_s_setprio(0); } while (0)
; #define PG8_WAIT_V(n) asm volatile("s_waitcnt vmcnt(" #n ")" ::: "memory")
; #define PG8_WAIT_L(n) asm volatile("s_waitcnt lgkmcnt(" #n ")" ::: "memory")
; #define PG8_BAR __builtin_amdgcn_s_barrier()
; #define PG8_SCHED __builtin_amdgcn_sched_barrier(0)
; template <class Epi, class Sched>
; __device__ __forceinline__ void gemm_phase(int wv, LAS unsigned char* lds, const Gemm g, const Sched& S, const Epi& E) {
;     ...
;             PG8_LDA(At, 1, 1); PG8_STAGE(PG8_SB(1, 0), b3, voffB); PG8_STAGE(PG8_SB(1, 1), b3 + hstepB, voffB); PG8_STAGE(PG8_SA(1, 0), a3, voffA);
;             PG8_WAIT_V(8); PG8_WAIT_L(0); PG8_BAR; PG8_MMA(1, 0, At, B0); PG8_MMA(1, 1, At, B1); PG8_BAR; PG8_SCHED;
;         }
	s_add_i32 s30, s95, s40
	v_lshl_add_u64 v[76:77], v[222:223], 0, s[74:75]
	s_mov_b32 m0, s30
	s_nop 0
	ds_read_b128 v[72:75], v209 offset:49152
	ds_read_b128 v[198:201], v209 offset:50176
	ds_read_b128 v[202:205], v209 offset:51200
	ds_read_b128 v[210:213], v209 offset:52224
	ds_read_b128 v[214:217], v209 offset:53248
	ds_read_b128 v[218:221], v209 offset:54272
	ds_read_b128 v[228:231], v209 offset:55296
	ds_read_b128 v[232:235], v209 offset:56320
	global_load_lds_dwordx4 v[76:77], off
	s_add_i32 m0, s30, 0x2000
	s_add_u32 s28, s28, 0x20080
	v_lshl_add_u64 v[76:77], v[240:241], 0, s[74:75]
	s_addc_u32 s29, s29, 0
	s_add_i32 s30, s55, s40
	global_load_lds_dwordx4 v[76:77], off
	v_lshl_add_u64 v[76:77], s[28:29], 0, v[164:165]
	s_mov_b32 m0, s30
	s_nop 0
	global_load_lds_dwordx4 v[76:77], off
	v_lshl_add_u64 v[76:77], s[28:29], 0, v[160:161]
	s_add_i32 m0, s30, 0x2000
	s_nop 0
	global_load_lds_dwordx4 v[76:77], off
	v_lshl_add_u64 v[76:77], v[242:243], 0, s[74:75]
	s_mov_b32 m0, s48
	s_nop 0
	global_load_lds_dwordx4 v[76:77], off
	v_lshl_add_u64 v[76:77], v[244:245], 0, s[74:75]
	s_mov_b32 m0, s49
	s_nop 0
	global_load_lds_dwordx4 v[76:77], off
	s_waitcnt vmcnt(8)
	s_waitcnt lgkmcnt(0)
	s_barrier
	s_setprio 1
	s_waitcnt lgkmcnt(0)
	v_mfma_f32_16x16x32_bf16 v[76:79], v[56:59], v[72:75], v[84:87]
	v_mfma_f32_16x16x32_bf16 v[84:87], v[60:63], v[198:201], v[76:79]
	v_mfma_f32_16x16x32_bf16 v[76:79], v[64:67], v[72:75], v[80:83]
	v_mfma_f32_16x16x32_bf16 v[44:47], v[56:59], v[202:205], v[44:47]
	v_mfma_f32_16x16x32_bf16 v[40:43], v[64:67], v[202:205], v[40:43]
	v_mfma_f32_16x16x32_bf16 v[28:31], v[56:59], v[214:217], v[28:31]
	v_mfma_f32_16x16x32_bf16 v[24:27], v[64:67], v[214:217], v[24:27]
	v_mfma_f32_16x16x32_bf16 v[12:15], v[56:59], v[228:231], v[12:15]
	v_mfma_f32_16x16x32_bf16 v[8:11], v[64:67], v[228:231], v[8:11]
	v_mfma_f32_16x16x32_bf16 v[80:83], v[68:71], v[198:201], v[76:79]
	v_mfma_f32_16x16x32_bf16 v[44:47], v[60:63], v[210:213], v[44:47]
	v_mfma_f32_16x16x32_bf16 v[40:43], v[68:71], v[210:213], v[40:43]
	v_mfma_f32_16x16x32_bf16 v[28:31], v[60:63], v[218:221], v[28:31]
	v_mfma_f32_16x16x32_bf16 v[24:27], v[68:71], v[218:221], v[24:27]
	v_mfma_f32_16x16x32_bf16 v[12:15], v[60:63], v[232:235], v[12:15]
	v_mfma_f32_16x16x32_bf16 v[8:11], v[68:71], v[232:235], v[8:11]
	v_mfma_f32_16x16x32_bf16 v[48:51], v[88:91], v[72:75], v[48:51]
	v_mfma_f32_16x16x32_bf16 v[76:79], v[92:95], v[198:201], v[48:51]
	v_mfma_f32_16x16x32_bf16 v[48:51], v[180:183], v[72:75], v[52:55]
	v_mfma_f32_16x16x32_bf16 v[36:39], v[88:91], v[202:205], v[36:39]
	v_mfma_f32_16x16x32_bf16 v[32:35], v[180:183], v[202:205], v[32:35]
	v_mfma_f32_16x16x32_bf16 v[20:23], v[88:91], v[214:217], v[20:23]
	v_mfma_f32_16x16x32_bf16 v[16:19], v[180:183], v[214:217], v[16:19]
	v_mfma_f32_16x16x32_bf16 v[4:7], v[88:91], v[228:231], v[4:7]
	v_mfma_f32_16x16x32_bf16 v[0:3], v[180:183], v[228:231], v[0:3]
	v_mfma_f32_16x16x32_bf16 v[72:75], v[184:187], v[198:201], v[48:51]
	v_mfma_f32_16x16x32_bf16 v[36:39], v[92:95], v[210:213], v[36:39]
	v_mfma_f32_16x16x32_bf16 v[32:35], v[184:187], v[210:213], v[32:35]
	v_mfma_f32_16x16x32_bf16 v[20:23], v[92:95], v[218:221], v[20:23]
	v_mfma_f32_16x16x32_bf16 v[16:19], v[184:187], v[218:221], v[16:19]
	v_mfma_f32_16x16x32_bf16 v[4:7], v[92:95], v[232:235], v[4:7]
	v_mfma_f32_16x16x32_bf16 v[0:3], v[184:187], v[232:235], v[0:3]
	s_setprio 0
	s_barrier
	s_add_i32 s54, s54, 2
	s_add_u32 s4, s4, 0x100
	s_addc_u32 s5, s5, 0
	s_add_u32 s52, s52, 0x100
	s_addc_u32 s53, s53, 0
	s_cmp_gt_u32 s54, 13
	s_cbranch_scc0 .LBB0_542
	s_and_b64 vcc, exec, s[16:17]
	s_cbranch_vccz .LBB0_545
	s_barrier

; #define PG8_STAGE(bufoff, gbase, voff) do { _Pragma("unroll") for (int _i = 0; _i < 2; ++_i) \
;         __builtin_amdgcn_global_load_lds((const unsigned*)((const char*)(gbase) + (voff)[_i]), (LAS unsigned*)(lds + (bufoff) + ldsw + _i * 8192), 16, 0, 0); } while (0)
; #define PG8_LDA(dst, b, h) do { _Pragma("unroll") for (int m = 0; m < 4; ++m) _Pragma("unroll") for (int k = 0; k < 2; ++k) dst[m][k] = *(const LAS bf16x8*)(lds + PG8_SA(b, h) + aoff + m * 2048 + k * 1024); } while (0)
; #define PG8_LDB(dst, b, h) do { _Pragma("unroll") for (int n = 0; n < 2; ++n) _Pragma("unroll") for (int k = 0; k < 2; ++k) dst[n][k] = *(const LAS bf16x8*)(lds + PG8_SB(b, h) + boff + n * 2048 + k * 1024); } while (0)
; #define PG8_MMA(ai, bj, At, Bt) do { __builtin_amdgcn_s_setprio(1); _Pragma("unroll") for (int m = 0; m < 4; ++m) _Pragma("unroll") for (int n = 0; n < 2; ++n) _Pragma("unroll") for (int k = 0; k < 2; ++k) \
;         acc[ai][bj][m][n] = __builtin_amdgcn_mfma_f32_16x16x32_bf16(Bt[n][k], At[m][k], acc[ai][bj][m][n], 0, 0, 0); __builtin_amdgcn_s_setprio(0); } while (0)
; #define PG8_WAIT_V(n) asm volatile("s_waitcnt vmcnt(" #n ")" ::: "memory")
; #define PG8_WAIT_L(n) asm volatile("s_waitcnt lgkmcnt(" #n ")" ::: "memory")
; #define PG8_BAR __builtin_amdgcn_s_barrier()
; #define PG8_SCHED __builtin_amdgcn_sched_barrier(0)
; template <class Epi, class Sched>
; __device__ __forceinline__ void gemm_phase(int wv, LAS unsigned char* lds, const Gemm g, const Sched& S, const Epi& E) {
;     ...
;         for (int t = 0; t < nt; t += 2) {
;             const bool last = (t == nt - 2);
;             const char* a1 = cA + (size_t)(t + 1) * kstep;
;             const char* a2 = last ? nA : cA + (size_t)(t + 2) * kstep; const char* b2 = last ? nB : cB + (size_t)(t + 2) * kstep;
;             const char* a3 = a2 + kstep; const char* b3 = b2 + kstep;
;             PG8_LDB(B0, 0, 0); PG8_LDB(B1, 0, 1); PG8_SCHED; PG8_LDA(At, 0, 0); PG8_STAGE(PG8_SA(1, 1), a1 + hstep, voffA);
;             PG8_WAIT_V(8); PG8_WAIT_L(0); PG8_BAR; PG8_MMA(0, 0, At, B0); PG8_MMA(0, 1, At, B1); PG8_BAR; PG8_SCHED;
;             PG8_LDA(At, 0, 1); PG8_STAGE(PG8_SB(0, 0), b2, voffB); PG8_STAGE(PG8_SB(0, 1), b2 + hstepB, voffB); PG8_STAGE(PG8_SA(0, 0), a2, voffA);
;             PG8_WAIT_V(8); PG8_WAIT_L(0); PG8_BAR; PG8_MMA(1, 0, At, B0); PG8_MMA(1, 1, At, B1); PG8_BAR; PG8_SCHED;
.LBB0_781:
	s_add_u32 s22, s20, 0xfffc0080
	s_addc_u32 s23, s21, -1
	s_add_i32 s44, 0, 0x10000
	s_cmp_eq_u32 s43, 12
	s_cselect_b32 s25, s13, s23
	s_cselect_b32 s24, s39, s22
	s_cselect_b32 s23, s15, s42
	s_cselect_b32 s22, s40, s41
	s_add_i32 s46, 0, 0x14000
	v_add_u32_e32 v154, s44, v139
	v_add_u32_e32 v170, s46, v139
	ds_read_b128 v[142:145], v154
	ds_read_b128 v[146:149], v154 offset:1024
	ds_read_b128 v[150:153], v154 offset:2048
	ds_read_b128 v[154:157], v154 offset:3072
	ds_read_b128 v[158:161], v170
	ds_read_b128 v[162:165], v170 offset:1024
	ds_read_b128 v[166:169], v170 offset:2048
	ds_read_b128 v[170:173], v170 offset:3072
	v_lshl_add_u64 v[186:187], s[20:21], 0, v[134:135]
	s_add_i32 m0, s29, 0xc000
	ds_read_b128 v[174:177], v141
	ds_read_b128 v[178:181], v141 offset:1024
	ds_read_b128 v[182:185], v141 offset:2048
	ds_read_b128 v[198:201], v141 offset:3072
	ds_read_b128 v[202:205], v141 offset:4096
	ds_read_b128 v[206:209], v141 offset:5120
	ds_read_b128 v[210:213], v141 offset:6144
	ds_read_b128 v[214:217], v141 offset:7168
	global_load_lds_dwordx4 v[186:187], off
	v_lshl_add_u64 v[186:187], s[20:21], 0, v[136:137]
	s_add_i32 m0, s29, 0xe000
	s_nop 0
	global_load_lds_dwordx4 v[186:187], off
	s_waitcnt vmcnt(8)
	s_waitcnt lgkmcnt(0)
	s_barrier
	s_setprio 1
	s_waitcnt lgkmcnt(0)
	v_mfma_f32_16x16x32_bf16 v[124:127], v[142:145], v[174:177], v[124:127]
	v_mfma_f32_16x16x32_bf16 v[120:123], v[150:153], v[174:177], v[120:123]
	v_mfma_f32_16x16x32_bf16 v[116:119], v[142:145], v[182:185], v[116:119]
	v_mfma_f32_16x16x32_bf16 v[108:111], v[150:153], v[182:185], v[108:111]
	v_mfma_f32_16x16x32_bf16 v[100:103], v[142:145], v[202:205], v[100:103]
	v_mfma_f32_16x16x32_bf16 v[96:99], v[150:153], v[202:205], v[96:99]
	v_mfma_f32_16x16x32_bf16 v[84:87], v[142:145], v[210:213], v[84:87]
	v_mfma_f32_16x16x32_bf16 v[80:83], v[150:153], v[210:213], v[80:83]
	v_mfma_f32_16x16x32_bf16 v[124:127], v[146:149], v[178:181], v[124:127]
	v_mfma_f32_16x16x32_bf16 v[120:123], v[154:157], v[178:181], v[120:123]
	v_mfma_f32_16x16x32_bf16 v[116:119], v[146:149], v[198:201], v[116:119]
	v_mfma_f32_16x16x32_bf16 v[108:111], v[154:157], v[198:201], v[108:111]
	v_mfma_f32_16x16x32_bf16 v[100:103], v[146:149], v[206:209], v[100:103]
	v_mfma_f32_16x16x32_bf16 v[96:99], v[154:157], v[206:209], v[96:99]
	v_mfma_f32_16x16x32_bf16 v[84:87], v[146:149], v[214:217], v[84:87]
	v_mfma_f32_16x16x32_bf16 v[80:83], v[154:157], v[214:217], v[80:83]
	v_mfma_f32_16x16x32_bf16 v[112:115], v[158:161], v[174:177], v[112:115]
	v_mfma_f32_16x16x32_bf16 v[104:107], v[166:169], v[174:177], v[104:107]
	v_mfma_f32_16x16x32_bf16 v[92:95], v[158:161], v[182:185], v[92:95]
	v_mfma_f32_16x16x32_bf16 v[88:91], v[166:169], v[182:185], v[88:91]
	v_mfma_f32_16x16x32_bf16 v[76:79], v[158:161], v[202:205], v[76:79]
	v_mfma_f32_16x16x32_bf16 v[72:75], v[166:169], v[202:205], v[72:75]
	v_mfma_f32_16x16x32_bf16 v[68:71], v[158:161], v[210:213], v[68:71]
	v_mfma_f32_16x16x32_bf16 v[64:67], v[166:169], v[210:213], v[64:67]
	v_mfma_f32_16x16x32_bf16 v[112:115], v[162:165], v[178:181], v[112:115]
	v_mfma_f32_16x16x32_bf16 v[104:107], v[170:173], v[178:181], v[104:107]
	v_mfma_f32_16x16x32_bf16 v[92:95], v[162:165], v[198:201], v[92:95]
	v_mfma_f32_16x16x32_bf16 v[88:91], v[170:173], v[198:201], v[88:91]
	v_mfma_f32_16x16x32_bf16 v[76:79], v[162:165], v[206:209], v[76:79]
	v_mfma_f32_16x16x32_bf16 v[72:75], v[170:173], v[206:209], v[72:75]
	v_mfma_f32_16x16x32_bf16 v[68:71], v[162:165], v[214:217], v[68:71]
	v_mfma_f32_16x16x32_bf16 v[64:67], v[170:173], v[214:217], v[64:67]
	s_setprio 0
	s_barrier
	s_add_i32 s44, s44, s28
	v_lshl_add_u64 v[186:187], s[22:23], 0, v[188:189]
	s_mov_b32 m0, s44
	ds_read_b128 v[174:177], v141 offset:16384
	ds_read_b128 v[178:181], v141 offset:17408
	ds_read_b128 v[182:185], v141 offset:18432
	ds_read_b128 v[198:201], v141 offset:19456
	ds_read_b128 v[202:205], v141 offset:20480
	ds_read_b128 v[206:209], v141 offset:21504
	ds_read_b128 v[210:213], v141 offset:22528
	ds_read_b128 v[214:217], v141 offset:23552
	global_load_lds_dwordx4 v[186:187], off
	s_add_i32 m0, s44, 0x2000
	s_add_u32 s44, s22, 0x4000
	v_lshl_add_u64 v[218:219], s[22:23], 0, v[128:129]
	s_addc_u32 s45, s23, 0
	s_add_i32 s46, s46, s28
	global_load_lds_dwordx4 v[218:219], off
	v_lshl_add_u64 v[220:221], s[44:45], 0, v[188:189]
	s_mov_b32 m0, s46
	v_lshl_add_u64 v[222:223], s[24:25], 0, v[130:131]
	global_load_lds_dwordx4 v[220:221], off
	v_lshl_add_u64 v[220:221], s[44:45], 0, v[128:129]
	s_add_i32 m0, s46, 0x2000
	s_nop 0
	global_load_lds_dwordx4 v[220:221], off
	v_lshl_add_u64 v[220:221], s[24:25], 0, v[132:133]
	s_mov_b32 m0, s29
	s_nop 0
	global_load_lds_dwordx4 v[220:221], off
	s_mov_b32 m0, s30
	s_nop 0
	global_load_lds_dwordx4 v[222:223], off
	s_waitcnt vmcnt(8)
	s_waitcnt lgkmcnt(0)
	s_barrier
; #define PG8_STAGE(bufoff, gbase, voff) do { _Pragma("unroll") for (int _i = 0; _i < 2; ++_i) \
;         __builtin_amdgcn_global_load_lds((const unsigned*)((const char*)(gbase) + (voff)[_i]), (LAS unsigned*)(lds + (bufoff) + ldsw + _i * 8192), 16, 0, 0); } while (0)
; #define PG8_LDA(dst, b, h) do { _Pragma("unroll") for (int m = 0; m < 4; ++m) _Pragma("unroll") for (int k = 0; k < 2; ++k) dst[m][k] = *(const LAS bf16x8*)(lds + PG8_SA(b, h) + aoff + m * 2048 + k * 1024); } while (0)
; #define PG8_LDB(dst, b, h) do { _Pragma("unroll") for (int n = 0; n < 2; ++n) _Pragma("unroll") for (int k = 0; k < 2; ++k) dst[n][k] = *(const LAS bf16x8*)(lds + PG8_SB(b, h) + boff + n * 2048 + k * 1024); } while (0)
; #define PG8_MMA(ai, bj, At, Bt) do { __builtin_amdgcn_s_setprio(1); _Pragma("unroll") for (int m = 0; m < 4; ++m) _Pragma("unroll") for (int n = 0; n < 2; ++n) _Pragma("unroll") for (int k = 0; k < 2; ++k) \
;         acc[ai][bj][m][n] = __builtin_amdgcn_mfma_f32_16x16x32_bf16(Bt[n][k], At[m][k], acc[ai][bj][m][n], 0, 0, 0); __builtin_amdgcn_s_setprio(0); } while (0)
; #define PG8_WAIT_V(n) asm volatile("s_waitcnt vmcnt(" #n ")" ::: "memory")
; #define PG8_WAIT_L(n) asm volatile("s_waitcnt lgkmcnt(" #n ")" ::: "memory")
; #define PG8_BAR __builtin_amdgcn_s_barrier()
; #define PG8_SCHED __builtin_amdgcn_sched_barrier(0)
; template <class Epi, class Sched>
; __device__ __forceinline__ void gemm_phase(int wv, LAS unsigned char* lds, const Gemm g, const Sched& S, const Epi& E) {
;     ...
;             PG8_WAIT_V(8); PG8_WAIT_L(0); PG8_BAR; PG8_MMA(1, 0, At, B0); PG8_MMA(1, 1, At, B1); PG8_BAR; PG8_SCHED;
;             PG8_LDB(B0, 1, 0); PG8_LDB(B1, 1, 1); PG8_SCHED; PG8_LDA(At, 1, 0); PG8_STAGE(PG8_SA(0, 1), a2 + hstep, voffA);
;             PG8_WAIT_V(8); PG8_WAIT_L(0); PG8_BAR; PG8_MMA(0, 0, At, B0); PG8_MMA(0, 1, At, B1); PG8_BAR; PG8_SCHED;
	s_setprio 1
	s_waitcnt lgkmcnt(0)
	v_mfma_f32_16x16x32_bf16 v[60:63], v[142:145], v[174:177], v[60:63]
	v_mfma_f32_16x16x32_bf16 v[56:59], v[150:153], v[174:177], v[56:59]
	v_mfma_f32_16x16x32_bf16 v[52:55], v[142:145], v[182:185], v[52:55]
	v_mfma_f32_16x16x32_bf16 v[48:51], v[150:153], v[182:185], v[48:51]
	v_mfma_f32_16x16x32_bf16 v[36:39], v[142:145], v[202:205], v[36:39]
	v_mfma_f32_16x16x32_bf16 v[32:35], v[150:153], v[202:205], v[32:35]
	v_mfma_f32_16x16x32_bf16 v[20:23], v[142:145], v[210:213], v[20:23]
	v_mfma_f32_16x16x32_bf16 v[16:19], v[150:153], v[210:213], v[16:19]
	v_mfma_f32_16x16x32_bf16 v[60:63], v[146:149], v[178:181], v[60:63]
	v_mfma_f32_16x16x32_bf16 v[56:59], v[154:157], v[178:181], v[56:59]
	v_mfma_f32_16x16x32_bf16 v[52:55], v[146:149], v[198:201], v[52:55]
	v_mfma_f32_16x16x32_bf16 v[48:51], v[154:157], v[198:201], v[48:51]
	v_mfma_f32_16x16x32_bf16 v[36:39], v[146:149], v[206:209], v[36:39]
	v_mfma_f32_16x16x32_bf16 v[32:35], v[154:157], v[206:209], v[32:35]
	v_mfma_f32_16x16x32_bf16 v[20:23], v[146:149], v[214:217], v[20:23]
	v_mfma_f32_16x16x32_bf16 v[16:19], v[154:157], v[214:217], v[16:19]
	v_mfma_f32_16x16x32_bf16 v[44:47], v[158:161], v[174:177], v[44:47]
	v_mfma_f32_16x16x32_bf16 v[40:43], v[166:169], v[174:177], v[40:43]
	v_mfma_f32_16x16x32_bf16 v[28:31], v[158:161], v[182:185], v[28:31]
	v_mfma_f32_16x16x32_bf16 v[24:27], v[166:169], v[182:185], v[24:27]
	v_mfma_f32_16x16x32_bf16 v[12:15], v[158:161], v[202:205], v[12:15]
	v_mfma_f32_16x16x32_bf16 v[8:11], v[166:169], v[202:205], v[8:11]
	v_mfma_f32_16x16x32_bf16 v[4:7], v[158:161], v[210:213], v[4:7]
	v_mfma_f32_16x16x32_bf16 v[0:3], v[166:169], v[210:213], v[0:3]
	v_mfma_f32_16x16x32_bf16 v[44:47], v[162:165], v[178:181], v[44:47]
	v_mfma_f32_16x16x32_bf16 v[40:43], v[170:173], v[178:181], v[40:43]
	v_mfma_f32_16x16x32_bf16 v[28:31], v[162:165], v[198:201], v[28:31]
	v_mfma_f32_16x16x32_bf16 v[24:27], v[170:173], v[198:201], v[24:27]
	v_mfma_f32_16x16x32_bf16 v[12:15], v[162:165], v[206:209], v[12:15]
	v_mfma_f32_16x16x32_bf16 v[8:11], v[170:173], v[206:209], v[8:11]
	v_mfma_f32_16x16x32_bf16 v[4:7], v[162:165], v[214:217], v[4:7]
	v_mfma_f32_16x16x32_bf16 v[0:3], v[170:173], v[214:217], v[0:3]
	s_setprio 0
	s_barrier
	s_add_i32 s44, 0, 0x1c000
	v_add_u32_e32 v154, s95, v139
	v_add_u32_e32 v170, s44, v139
	ds_read_b128 v[142:145], v154
	ds_read_b128 v[146:149], v154 offset:1024
	ds_read_b128 v[150:153], v154 offset:2048
	ds_read_b128 v[154:157], v154 offset:3072
	ds_read_b128 v[158:161], v170
	ds_read_b128 v[162:165], v170 offset:1024
	ds_read_b128 v[166:169], v170 offset:2048
	ds_read_b128 v[170:173], v170 offset:3072
	s_add_u32 s24, s24, 0x40000
	s_addc_u32 s25, s25, 0
	s_mov_b32 m0, s31
	v_lshl_add_u64 v[228:229], s[24:25], 0, v[132:133]
	ds_read_b128 v[174:177], v141 offset:32768
	ds_read_b128 v[178:181], v141 offset:33792
	ds_read_b128 v[182:185], v141 offset:34816
	ds_read_b128 v[198:201], v141 offset:35840
	ds_read_b128 v[202:205], v141 offset:36864
	ds_read_b128 v[206:209], v141 offset:37888
	ds_read_b128 v[210:213], v141 offset:38912
	ds_read_b128 v[214:217], v141 offset:39936
	global_load_lds_dwordx4 v[228:229], off
	v_lshl_add_u64 v[228:229], s[24:25], 0, v[130:131]
	s_mov_b32 m0, s34
	s_nop 0
	global_load_lds_dwordx4 v[228:229], off
	s_waitcnt vmcnt(8)
	s_waitcnt lgkmcnt(0)
	s_barrier
	s_setprio 1
	s_waitcnt lgkmcnt(0)
	v_mfma_f32_16x16x32_bf16 v[124:127], v[142:145], v[174:177], v[124:127]
	v_mfma_f32_16x16x32_bf16 v[120:123], v[150:153], v[174:177], v[120:123]
	v_mfma_f32_16x16x32_bf16 v[116:119], v[142:145], v[182:185], v[116:119]
	v_mfma_f32_16x16x32_bf16 v[108:111], v[150:153], v[182:185], v[108:111]
	v_mfma_f32_16x16x32_bf16 v[100:103], v[142:145], v[202:205], v[100:103]
	v_mfma_f32_16x16x32_bf16 v[96:99], v[150:153], v[202:205], v[96:99]
	v_mfma_f32_16x16x32_bf16 v[84:87], v[142:145], v[210:213], v[84:87]
	v_mfma_f32_16x16x32_bf16 v[80:83], v[150:153], v[210:213], v[80:83]
	v_mfma_f32_16x16x32_bf16 v[124:127], v[146:149], v[178:181], v[124:127]
	v_mfma_f32_16x16x32_bf16 v[120:123], v[154:157], v[178:181], v[120:123]
	v_mfma_f32_16x16x32_bf16 v[116:119], v[146:149], v[198:201], v[116:119]
	v_mfma_f32_16x16x32_bf16 v[108:111], v[154:157], v[198:201], v[108:111]
	v_mfma_f32_16x16x32_bf16 v[100:103], v[146:149], v[206:209], v[100:103]
	v_mfma_f32_16x16x32_bf16 v[96:99], v[154:157], v[206:209], v[96:99]
	v_mfma_f32_16x16x32_bf16 v[84:87], v[146:149], v[214:217], v[84:87]
	v_mfma_f32_16x16x32_bf16 v[80:83], v[154:157], v[214:217], v[80:83]
	v_mfma_f32_16x16x32_bf16 v[112:115], v[158:161], v[174:177], v[112:115]
	v_mfma_f32_16x16x32_bf16 v[104:107], v[166:169], v[174:177], v[104:107]
	v_mfma_f32_16x16x32_bf16 v[92:95], v[158:161], v[182:185], v[92:95]
	v_mfma_f32_16x16x32_bf16 v[88:91], v[166:169], v[182:185], v[88:91]
	v_mfma_f32_16x16x32_bf16 v[76:79], v[158:161], v[202:205], v[76:79]
	v_mfma_f32_16x16x32_bf16 v[72:75], v[166:169], v[202:205], v[72:75]
	v_mfma_f32_16x16x32_bf16 v[68:71], v[158:161], v[210:213], v[68:71]
	v_mfma_f32_16x16x32_bf16 v[64:67], v[166:169], v[210:213], v[64:67]
	v_mfma_f32_16x16x32_bf16 v[112:115], v[162:165], v[178:181], v[112:115]
	v_mfma_f32_16x16x32_bf16 v[104:107], v[170:173], v[178:181], v[104:107]
	v_mfma_f32_16x16x32_bf16 v[92:95], v[162:165], v[198:201], v[92:95]
	v_mfma_f32_16x16x32_bf16 v[88:91], v[170:173], v[198:201], v[88:91]
	v_mfma_f32_16x16x32_bf16 v[76:79], v[162:165], v[206:209], v[76:79]
	v_mfma_f32_16x16x32_bf16 v[72:75], v[170:173], v[206:209], v[72:75]
	v_mfma_f32_16x16x32_bf16 v[68:71], v[162:165], v[214:217], v[68:71]
	v_mfma_f32_16x16x32_bf16 v[64:67], v[170:173], v[214:217], v[64:67]
	s_setprio 0
	s_barrier
; #define PG8_STAGE(bufoff, gbase, voff) do { _Pragma("unroll") for (int _i = 0; _i < 2; ++_i) \
;         __builtin_amdgcn_global_load_lds((const unsigned*)((const char*)(gbase) + (voff)[_i]), (LAS unsigned*)(lds + (bufoff) + ldsw + _i * 8192), 16, 0, 0); } while (0)
; #define PG8_LDA(dst, b, h) do { _Pragma("unroll") for (int m = 0; m < 4; ++m) _Pragma("unroll") for (int k = 0; k < 2; ++k) dst[m][k] = *(const LAS bf16x8*)(lds + PG8_SA(b, h) + aoff + m * 2048 + k * 1024); } while (0)
; #define PG8_MMA(ai, bj, At, Bt) do { __builtin_amdgcn_s_setprio(1); _Pragma("unroll") for (int m = 0; m < 4; ++m) _Pragma("unroll") for (int n = 0; n < 2; ++n) _Pragma("unroll") for (int k = 0; k < 2; ++k) \
;         acc[ai][bj][m][n] = __builtin_amdgcn_mfma_f32_16x16x32_bf16(Bt[n][k], At[m][k], acc[ai][bj][m][n], 0, 0, 0); __builtin_amdgcn_s_setprio(0); } while (0)
; #define PG8_WAIT_V(n) asm volatile("s_waitcnt vmcnt(" #n ")" ::: "memory")
; #define PG8_WAIT_L(n) asm volatile("s_waitcnt lgkmcnt(" #n ")" ::: "memory")
; #define PG8_BAR __builtin_amdgcn_s_barrier()
; #define PG8_SCHED __builtin_amdgcn_sched_barrier(0)
; template <class Epi, class Sched>
; __device__ __forceinline__ void gemm_phase(int wv, LAS unsigned char* lds, const Gemm g, const Sched& S, const Epi& E) {
;     ...
;             PG8_LDA(At, 1, 1); PG8_STAGE(PG8_SB(1, 0), b3, voffB); PG8_STAGE(PG8_SB(1, 1), b3 + hstepB, voffB); PG8_STAGE(PG8_SA(1, 0), a3, voffA);
;             PG8_WAIT_V(8); PG8_WAIT_L(0); PG8_BAR; PG8_MMA(1, 0, At, B0); PG8_MMA(1, 1, At, B1); PG8_BAR; PG8_SCHED;
;         }
	s_add_i32 s24, s95, s28
	v_lshl_add_u64 v[186:187], v[186:187], 0, s[74:75]
	s_mov_b32 m0, s24
	ds_read_b128 v[174:177], v141 offset:49152
	ds_read_b128 v[178:181], v141 offset:50176
	ds_read_b128 v[182:185], v141 offset:51200
	ds_read_b128 v[198:201], v141 offset:52224
	ds_read_b128 v[202:205], v141 offset:53248
	ds_read_b128 v[206:209], v141 offset:54272
	ds_read_b128 v[210:213], v141 offset:55296
	ds_read_b128 v[214:217], v141 offset:56320
	global_load_lds_dwordx4 v[186:187], off
	s_add_i32 m0, s24, 0x2000
	s_add_u32 s22, s22, 0x4080
	v_lshl_add_u64 v[186:187], v[218:219], 0, s[74:75]
	s_addc_u32 s23, s23, 0
	s_add_i32 s24, s44, s28
	global_load_lds_dwordx4 v[186:187], off
	v_lshl_add_u64 v[186:187], s[22:23], 0, v[188:189]
	s_mov_b32 m0, s24
	s_nop 0
	global_load_lds_dwordx4 v[186:187], off
	v_lshl_add_u64 v[186:187], s[22:23], 0, v[128:129]
	s_add_i32 m0, s24, 0x2000
	s_nop 0
	global_load_lds_dwordx4 v[186:187], off
	v_lshl_add_u64 v[186:187], v[220:221], 0, s[74:75]
	s_mov_b32 m0, s35
	s_nop 0
	global_load_lds_dwordx4 v[186:187], off
	v_lshl_add_u64 v[186:187], v[222:223], 0, s[74:75]
	s_mov_b32 m0, s36
	s_nop 0
	global_load_lds_dwordx4 v[186:187], off
	s_waitcnt vmcnt(8)
	s_waitcnt lgkmcnt(0)
	s_barrier
	s_setprio 1
	s_waitcnt lgkmcnt(0)
	v_mfma_f32_16x16x32_bf16 v[60:63], v[142:145], v[174:177], v[60:63]
	v_mfma_f32_16x16x32_bf16 v[56:59], v[150:153], v[174:177], v[56:59]
	v_mfma_f32_16x16x32_bf16 v[52:55], v[142:145], v[182:185], v[52:55]
	v_mfma_f32_16x16x32_bf16 v[48:51], v[150:153], v[182:185], v[48:51]
	v_mfma_f32_16x16x32_bf16 v[36:39], v[142:145], v[202:205], v[36:39]
	v_mfma_f32_16x16x32_bf16 v[32:35], v[150:153], v[202:205], v[32:35]
	v_mfma_f32_16x16x32_bf16 v[20:23], v[142:145], v[210:213], v[20:23]
	v_mfma_f32_16x16x32_bf16 v[16:19], v[150:153], v[210:213], v[16:19]
	v_mfma_f32_16x16x32_bf16 v[60:63], v[146:149], v[178:181], v[60:63]
	v_mfma_f32_16x16x32_bf16 v[56:59], v[154:157], v[178:181], v[56:59]
	v_mfma_f32_16x16x32_bf16 v[52:55], v[146:149], v[198:201], v[52:55]
	v_mfma_f32_16x16x32_bf16 v[48:51], v[154:157], v[198:201], v[48:51]
	v_mfma_f32_16x16x32_bf16 v[36:39], v[146:149], v[206:209], v[36:39]
	v_mfma_f32_16x16x32_bf16 v[32:35], v[154:157], v[206:209], v[32:35]
	v_mfma_f32_16x16x32_bf16 v[20:23], v[146:149], v[214:217], v[20:23]
	v_mfma_f32_16x16x32_bf16 v[16:19], v[154:157], v[214:217], v[16:19]
	v_mfma_f32_16x16x32_bf16 v[44:47], v[158:161], v[174:177], v[44:47]
	v_mfma_f32_16x16x32_bf16 v[40:43], v[166:169], v[174:177], v[40:43]
	v_mfma_f32_16x16x32_bf16 v[28:31], v[158:161], v[182:185], v[28:31]
	v_mfma_f32_16x16x32_bf16 v[24:27], v[166:169], v[182:185], v[24:27]
	v_mfma_f32_16x16x32_bf16 v[12:15], v[158:161], v[202:205], v[12:15]
	v_mfma_f32_16x16x32_bf16 v[8:11], v[166:169], v[202:205], v[8:11]
	v_mfma_f32_16x16x32_bf16 v[4:7], v[158:161], v[210:213], v[4:7]
	v_mfma_f32_16x16x32_bf16 v[0:3], v[166:169], v[210:213], v[0:3]
	v_mfma_f32_16x16x32_bf16 v[44:47], v[162:165], v[178:181], v[44:47]
	v_mfma_f32_16x16x32_bf16 v[40:43], v[170:173], v[178:181], v[40:43]
	v_mfma_f32_16x16x32_bf16 v[28:31], v[162:165], v[198:201], v[28:31]
	v_mfma_f32_16x16x32_bf16 v[24:27], v[170:173], v[198:201], v[24:27]
	v_mfma_f32_16x16x32_bf16 v[12:15], v[162:165], v[206:209], v[12:15]
	v_mfma_f32_16x16x32_bf16 v[8:11], v[170:173], v[206:209], v[8:11]
	v_mfma_f32_16x16x32_bf16 v[4:7], v[162:165], v[214:217], v[4:7]
	v_mfma_f32_16x16x32_bf16 v[0:3], v[170:173], v[214:217], v[0:3]
	s_setprio 0
	s_barrier
	s_add_i32 s43, s43, 2
	s_add_u32 s20, s20, 0x100
	s_addc_u32 s21, s21, 0
	s_add_u32 s41, s41, 0x100
	s_addc_u32 s42, s42, 0
	s_cmp_gt_u32 s43, 13
	s_cbranch_scc0 .LBB0_781
	s_and_b64 vcc, exec, s[10:11]
	s_cbranch_vccz .LBB0_784
	s_barrier

; #define PG8_STAGE(bufoff, gbase, voff) do { _Pragma("unroll") for (int _i = 0; _i < 2; ++_i) \
;         __builtin_amdgcn_global_load_lds((const unsigned*)((const char*)(gbase) + (voff)[_i]), (LAS unsigned*)(lds + (bufoff) + ldsw + _i * 8192), 16, 0, 0); } while (0)
; #define PG8_LDA(dst, b, h) do { _Pragma("unroll") for (int m = 0; m < 4; ++m) _Pragma("unroll") for (int k = 0; k < 2; ++k) dst[m][k] = *(const LAS bf16x8*)(lds + PG8_SA(b, h) + aoff + m * 2048 + k * 1024); } while (0)
; #define PG8_LDB(dst, b, h) do { _Pragma("unroll") for (int n = 0; n < 2; ++n) _Pragma("unroll") for (int k = 0; k < 2; ++k) dst[n][k] = *(const LAS bf16x8*)(lds + PG8_SB(b, h) + boff + n * 2048 + k * 1024); } while (0)
; #define PG8_MMA(ai, bj, At, Bt) do { __builtin_amdgcn_s_setprio(1); _Pragma("unroll") for (int m = 0; m < 4; ++m) _Pragma("unroll") for (int n = 0; n < 2; ++n) _Pragma("unroll") for (int k = 0; k < 2; ++k) \
;         acc[ai][bj][m][n] = __builtin_amdgcn_mfma_f32_16x16x32_bf16(Bt[n][k], At[m][k], acc[ai][bj][m][n], 0, 0, 0); __builtin_amdgcn_s_setprio(0); } while (0)
; #define PG8_WAIT_V(n) asm volatile("s_waitcnt vmcnt(" #n ")" ::: "memory")
; #define PG8_WAIT_L(n) asm volatile("s_waitcnt lgkmcnt(" #n ")" ::: "memory")
; #define PG8_BAR __builtin_amdgcn_s_barrier()
; #define PG8_SCHED __builtin_amdgcn_sched_barrier(0)
; template <class Epi, class Sched>
; __device__ __forceinline__ void gemm_phase(int wv, LAS unsigned char* lds, const Gemm g, const Sched& S, const Epi& E) {
;     ...
;         for (int t = 0; t < nt; t += 2) {
;             const bool last = (t == nt - 2);
;             const char* a1 = cA + (size_t)(t + 1) * kstep;
;             const char* a2 = last ? nA : cA + (size_t)(t + 2) * kstep; const char* b2 = last ? nB : cB + (size_t)(t + 2) * kstep;
;             const char* a3 = a2 + kstep; const char* b3 = b2 + kstep;
;             PG8_LDB(B0, 0, 0); PG8_LDB(B1, 0, 1); PG8_SCHED; PG8_LDA(At, 0, 0); PG8_STAGE(PG8_SA(1, 1), a1 + hstep, voffA);
;             PG8_WAIT_V(8); PG8_WAIT_L(0); PG8_BAR; PG8_MMA(0, 0, At, B0); PG8_MMA(0, 1, At, B1); PG8_BAR; PG8_SCHED;
;             PG8_LDA(At, 0, 1); PG8_STAGE(PG8_SB(0, 0), b2, voffB); PG8_STAGE(PG8_SB(0, 1), b2 + hstepB, voffB); PG8_STAGE(PG8_SA(0, 0), a2, voffA);
;             PG8_WAIT_V(8); PG8_WAIT_L(0); PG8_BAR; PG8_MMA(1, 0, At, B0); PG8_MMA(1, 1, At, B1); PG8_BAR; PG8_SCHED;
.LBB0_801:
	s_add_u32 s20, s18, 0xfffe0080
	s_addc_u32 s21, s19, -1
	s_add_i32 s44, 0, 0x10000
	s_cmp_eq_u32 s43, 4
	s_cselect_b32 s23, s11, s21
	s_cselect_b32 s22, s39, s20
	s_cselect_b32 s21, s13, s42
	s_cselect_b32 s20, s40, s41
	s_add_i32 s46, 0, 0x14000
	v_add_u32_e32 v154, s44, v139
	v_add_u32_e32 v170, s46, v139
	ds_read_b128 v[142:145], v154
	ds_read_b128 v[146:149], v154 offset:1024
	ds_read_b128 v[150:153], v154 offset:2048
	ds_read_b128 v[154:157], v154 offset:3072
	ds_read_b128 v[158:161], v170
	ds_read_b128 v[162:165], v170 offset:1024
	ds_read_b128 v[166:169], v170 offset:2048
	ds_read_b128 v[170:173], v170 offset:3072
	v_lshl_add_u64 v[186:187], s[18:19], 0, v[134:135]
	s_add_i32 m0, s29, 0xc000
	ds_read_b128 v[174:177], v141
	ds_read_b128 v[178:181], v141 offset:1024
	ds_read_b128 v[182:185], v141 offset:2048
	ds_read_b128 v[198:201], v141 offset:3072
	ds_read_b128 v[202:205], v141 offset:4096
	ds_read_b128 v[206:209], v141 offset:5120
	ds_read_b128 v[210:213], v141 offset:6144
	ds_read_b128 v[214:217], v141 offset:7168
	global_load_lds_dwordx4 v[186:187], off
	v_lshl_add_u64 v[186:187], s[18:19], 0, v[136:137]
	s_add_i32 m0, s29, 0xe000
	s_nop 0
	global_load_lds_dwordx4 v[186:187], off
	s_waitcnt vmcnt(8)
	s_waitcnt lgkmcnt(0)
	s_barrier
	s_setprio 1
	s_waitcnt lgkmcnt(0)
	v_mfma_f32_16x16x32_bf16 v[124:127], v[142:145], v[174:177], v[124:127]
	v_mfma_f32_16x16x32_bf16 v[120:123], v[150:153], v[174:177], v[120:123]
	v_mfma_f32_16x16x32_bf16 v[116:119], v[142:145], v[182:185], v[116:119]
	v_mfma_f32_16x16x32_bf16 v[108:111], v[150:153], v[182:185], v[108:111]
	v_mfma_f32_16x16x32_bf16 v[100:103], v[142:145], v[202:205], v[100:103]
	v_mfma_f32_16x16x32_bf16 v[96:99], v[150:153], v[202:205], v[96:99]
	v_mfma_f32_16x16x32_bf16 v[84:87], v[142:145], v[210:213], v[84:87]
	v_mfma_f32_16x16x32_bf16 v[80:83], v[150:153], v[210:213], v[80:83]
	v_mfma_f32_16x16x32_bf16 v[124:127], v[146:149], v[178:181], v[124:127]
	v_mfma_f32_16x16x32_bf16 v[120:123], v[154:157], v[178:181], v[120:123]
	v_mfma_f32_16x16x32_bf16 v[116:119], v[146:149], v[198:201], v[116:119]
	v_mfma_f32_16x16x32_bf16 v[108:111], v[154:157], v[198:201], v[108:111]
	v_mfma_f32_16x16x32_bf16 v[100:103], v[146:149], v[206:209], v[100:103]
	v_mfma_f32_16x16x32_bf16 v[96:99], v[154:157], v[206:209], v[96:99]
	v_mfma_f32_16x16x32_bf16 v[84:87], v[146:149], v[214:217], v[84:87]
	v_mfma_f32_16x16x32_bf16 v[80:83], v[154:157], v[214:217], v[80:83]
	v_mfma_f32_16x16x32_bf16 v[112:115], v[158:161], v[174:177], v[112:115]
	v_mfma_f32_16x16x32_bf16 v[104:107], v[166:169], v[174:177], v[104:107]
	v_mfma_f32_16x16x32_bf16 v[92:95], v[158:161], v[182:185], v[92:95]
	v_mfma_f32_16x16x32_bf16 v[88:91], v[166:169], v[182:185], v[88:91]
	v_mfma_f32_16x16x32_bf16 v[76:79], v[158:161], v[202:205], v[76:79]
	v_mfma_f32_16x16x32_bf16 v[72:75], v[166:169], v[202:205], v[72:75]
	v_mfma_f32_16x16x32_bf16 v[68:71], v[158:161], v[210:213], v[68:71]
	v_mfma_f32_16x16x32_bf16 v[64:67], v[166:169], v[210:213], v[64:67]
	v_mfma_f32_16x16x32_bf16 v[112:115], v[162:165], v[178:181], v[112:115]
	v_mfma_f32_16x16x32_bf16 v[104:107], v[170:173], v[178:181], v[104:107]
	v_mfma_f32_16x16x32_bf16 v[92:95], v[162:165], v[198:201], v[92:95]
	v_mfma_f32_16x16x32_bf16 v[88:91], v[170:173], v[198:201], v[88:91]
	v_mfma_f32_16x16x32_bf16 v[76:79], v[162:165], v[206:209], v[76:79]
	v_mfma_f32_16x16x32_bf16 v[72:75], v[170:173], v[206:209], v[72:75]
	v_mfma_f32_16x16x32_bf16 v[68:71], v[162:165], v[214:217], v[68:71]
	v_mfma_f32_16x16x32_bf16 v[64:67], v[170:173], v[214:217], v[64:67]
	s_setprio 0
	s_barrier
	s_add_i32 s44, s44, s28
	v_lshl_add_u64 v[186:187], s[20:21], 0, v[188:189]
	s_mov_b32 m0, s44
	ds_read_b128 v[174:177], v141 offset:16384
	ds_read_b128 v[178:181], v141 offset:17408
	ds_read_b128 v[182:185], v141 offset:18432
	ds_read_b128 v[198:201], v141 offset:19456
	ds_read_b128 v[202:205], v141 offset:20480
	ds_read_b128 v[206:209], v141 offset:21504
	ds_read_b128 v[210:213], v141 offset:22528
	ds_read_b128 v[214:217], v141 offset:23552
	global_load_lds_dwordx4 v[186:187], off
	s_add_i32 m0, s44, 0x2000
	s_add_u32 s44, s20, 0x2000
	v_lshl_add_u64 v[218:219], s[20:21], 0, v[128:129]
	s_addc_u32 s45, s21, 0
	s_add_i32 s46, s46, s28
	global_load_lds_dwordx4 v[218:219], off
	v_lshl_add_u64 v[220:221], s[44:45], 0, v[188:189]
	s_mov_b32 m0, s46
	v_lshl_add_u64 v[222:223], s[22:23], 0, v[130:131]
	global_load_lds_dwordx4 v[220:221], off
	v_lshl_add_u64 v[220:221], s[44:45], 0, v[128:129]
	s_add_i32 m0, s46, 0x2000
	s_nop 0
	global_load_lds_dwordx4 v[220:221], off
	v_lshl_add_u64 v[220:221], s[22:23], 0, v[132:133]
	s_mov_b32 m0, s29
	s_nop 0
	global_load_lds_dwordx4 v[220:221], off
	s_mov_b32 m0, s30
	s_nop 0
	global_load_lds_dwordx4 v[222:223], off
	s_waitcnt vmcnt(8)
	s_waitcnt lgkmcnt(0)
	s_barrier
; #define PG8_STAGE(bufoff, gbase, voff) do { _Pragma("unroll") for (int _i = 0; _i < 2; ++_i) \
;         __builtin_amdgcn_global_load_lds((const unsigned*)((const char*)(gbase) + (voff)[_i]), (LAS unsigned*)(lds + (bufoff) + ldsw + _i * 8192), 16, 0, 0); } while (0)
; #define PG8_LDA(dst, b, h) do { _Pragma("unroll") for (int m = 0; m < 4; ++m) _Pragma("unroll") for (int k = 0; k < 2; ++k) dst[m][k] = *(const LAS bf16x8*)(lds + PG8_SA(b, h) + aoff + m * 2048 + k * 1024); } while (0)
; #define PG8_LDB(dst, b, h) do { _Pragma("unroll") for (int n = 0; n < 2; ++n) _Pragma("unroll") for (int k = 0; k < 2; ++k) dst[n][k] = *(const LAS bf16x8*)(lds + PG8_SB(b, h) + boff + n * 2048 + k * 1024); } while (0)
; #define PG8_MMA(ai, bj, At, Bt) do { __builtin_amdgcn_s_setprio(1); _Pragma("unroll") for (int m = 0; m < 4; ++m) _Pragma("unroll") for (int n = 0; n < 2; ++n) _Pragma("unroll") for (int k = 0; k < 2; ++k) \
;         acc[ai][bj][m][n] = __builtin_amdgcn_mfma_f32_16x16x32_bf16(Bt[n][k], At[m][k], acc[ai][bj][m][n], 0, 0, 0); __builtin_amdgcn_s_setprio(0); } while (0)
; #define PG8_WAIT_V(n) asm volatile("s_waitcnt vmcnt(" #n ")" ::: "memory")
; #define PG8_WAIT_L(n) asm volatile("s_waitcnt lgkmcnt(" #n ")" ::: "memory")
; #define PG8_BAR __builtin_amdgcn_s_barrier()
; #define PG8_SCHED __builtin_amdgcn_sched_barrier(0)
; template <class Epi, class Sched>
; __device__ __forceinline__ void gemm_phase(int wv, LAS unsigned char* lds, const Gemm g, const Sched& S, const Epi& E) {
;     ...
;             PG8_WAIT_V(8); PG8_WAIT_L(0); PG8_BAR; PG8_MMA(1, 0, At, B0); PG8_MMA(1, 1, At, B1); PG8_BAR; PG8_SCHED;
;             PG8_LDB(B0, 1, 0); PG8_LDB(B1, 1, 1); PG8_SCHED; PG8_LDA(At, 1, 0); PG8_STAGE(PG8_SA(0, 1), a2 + hstep, voffA);
;             PG8_WAIT_V(8); PG8_WAIT_L(0); PG8_BAR; PG8_MMA(0, 0, At, B0); PG8_MMA(0, 1, At, B1); PG8_BAR; PG8_SCHED;
	s_setprio 1
	s_waitcnt lgkmcnt(0)
	v_mfma_f32_16x16x32_bf16 v[60:63], v[142:145], v[174:177], v[60:63]
	v_mfma_f32_16x16x32_bf16 v[56:59], v[150:153], v[174:177], v[56:59]
	v_mfma_f32_16x16x32_bf16 v[52:55], v[142:145], v[182:185], v[52:55]
	v_mfma_f32_16x16x32_bf16 v[48:51], v[150:153], v[182:185], v[48:51]
	v_mfma_f32_16x16x32_bf16 v[36:39], v[142:145], v[202:205], v[36:39]
	v_mfma_f32_16x16x32_bf16 v[32:35], v[150:153], v[202:205], v[32:35]
	v_mfma_f32_16x16x32_bf16 v[20:23], v[142:145], v[210:213], v[20:23]
	v_mfma_f32_16x16x32_bf16 v[16:19], v[150:153], v[210:213], v[16:19]
	v_mfma_f32_16x16x32_bf16 v[60:63], v[146:149], v[178:181], v[60:63]
	v_mfma_f32_16x16x32_bf16 v[56:59], v[154:157], v[178:181], v[56:59]
	v_mfma_f32_16x16x32_bf16 v[52:55], v[146:149], v[198:201], v[52:55]
	v_mfma_f32_16x16x32_bf16 v[48:51], v[154:157], v[198:201], v[48:51]
	v_mfma_f32_16x16x32_bf16 v[36:39], v[146:149], v[206:209], v[36:39]
	v_mfma_f32_16x16x32_bf16 v[32:35], v[154:157], v[206:209], v[32:35]
	v_mfma_f32_16x16x32_bf16 v[20:23], v[146:149], v[214:217], v[20:23]
	v_mfma_f32_16x16x32_bf16 v[16:19], v[154:157], v[214:217], v[16:19]
	v_mfma_f32_16x16x32_bf16 v[44:47], v[158:161], v[174:177], v[44:47]
	v_mfma_f32_16x16x32_bf16 v[40:43], v[166:169], v[174:177], v[40:43]
	v_mfma_f32_16x16x32_bf16 v[28:31], v[158:161], v[182:185], v[28:31]
	v_mfma_f32_16x16x32_bf16 v[24:27], v[166:169], v[182:185], v[24:27]
	v_mfma_f32_16x16x32_bf16 v[12:15], v[158:161], v[202:205], v[12:15]
	v_mfma_f32_16x16x32_bf16 v[8:11], v[166:169], v[202:205], v[8:11]
	v_mfma_f32_16x16x32_bf16 v[4:7], v[158:161], v[210:213], v[4:7]
	v_mfma_f32_16x16x32_bf16 v[0:3], v[166:169], v[210:213], v[0:3]
	v_mfma_f32_16x16x32_bf16 v[44:47], v[162:165], v[178:181], v[44:47]
	v_mfma_f32_16x16x32_bf16 v[40:43], v[170:173], v[178:181], v[40:43]
	v_mfma_f32_16x16x32_bf16 v[28:31], v[162:165], v[198:201], v[28:31]
	v_mfma_f32_16x16x32_bf16 v[24:27], v[170:173], v[198:201], v[24:27]
	v_mfma_f32_16x16x32_bf16 v[12:15], v[162:165], v[206:209], v[12:15]
	v_mfma_f32_16x16x32_bf16 v[8:11], v[170:173], v[206:209], v[8:11]
	v_mfma_f32_16x16x32_bf16 v[4:7], v[162:165], v[214:217], v[4:7]
	v_mfma_f32_16x16x32_bf16 v[0:3], v[170:173], v[214:217], v[0:3]
	s_setprio 0
	s_barrier
	s_add_i32 s44, 0, 0x1c000
	v_add_u32_e32 v154, s95, v139
	v_add_u32_e32 v170, s44, v139
	ds_read_b128 v[142:145], v154
	ds_read_b128 v[146:149], v154 offset:1024
	ds_read_b128 v[150:153], v154 offset:2048
	ds_read_b128 v[154:157], v154 offset:3072
	ds_read_b128 v[158:161], v170
	ds_read_b128 v[162:165], v170 offset:1024
	ds_read_b128 v[166:169], v170 offset:2048
	ds_read_b128 v[170:173], v170 offset:3072
	s_add_u32 s22, s22, 0x20000
	s_addc_u32 s23, s23, 0
	s_mov_b32 m0, s31
	v_lshl_add_u64 v[228:229], s[22:23], 0, v[132:133]
	ds_read_b128 v[174:177], v141 offset:32768
	ds_read_b128 v[178:181], v141 offset:33792
	ds_read_b128 v[182:185], v141 offset:34816
	ds_read_b128 v[198:201], v141 offset:35840
	ds_read_b128 v[202:205], v141 offset:36864
	ds_read_b128 v[206:209], v141 offset:37888
	ds_read_b128 v[210:213], v141 offset:38912
	ds_read_b128 v[214:217], v141 offset:39936
	global_load_lds_dwordx4 v[228:229], off
	v_lshl_add_u64 v[228:229], s[22:23], 0, v[130:131]
	s_mov_b32 m0, s34
	s_nop 0
	global_load_lds_dwordx4 v[228:229], off
	s_waitcnt vmcnt(8)
	s_waitcnt lgkmcnt(0)
	s_barrier
	s_setprio 1
	s_waitcnt lgkmcnt(0)
	v_mfma_f32_16x16x32_bf16 v[124:127], v[142:145], v[174:177], v[124:127]
	v_mfma_f32_16x16x32_bf16 v[120:123], v[150:153], v[174:177], v[120:123]
	v_mfma_f32_16x16x32_bf16 v[116:119], v[142:145], v[182:185], v[116:119]
	v_mfma_f32_16x16x32_bf16 v[108:111], v[150:153], v[182:185], v[108:111]
	v_mfma_f32_16x16x32_bf16 v[100:103], v[142:145], v[202:205], v[100:103]
	v_mfma_f32_16x16x32_bf16 v[96:99], v[150:153], v[202:205], v[96:99]
	v_mfma_f32_16x16x32_bf16 v[84:87], v[142:145], v[210:213], v[84:87]
	v_mfma_f32_16x16x32_bf16 v[80:83], v[150:153], v[210:213], v[80:83]
	v_mfma_f32_16x16x32_bf16 v[124:127], v[146:149], v[178:181], v[124:127]
	v_mfma_f32_16x16x32_bf16 v[120:123], v[154:157], v[178:181], v[120:123]
	v_mfma_f32_16x16x32_bf16 v[116:119], v[146:149], v[198:201], v[116:119]
	v_mfma_f32_16x16x32_bf16 v[108:111], v[154:157], v[198:201], v[108:111]
	v_mfma_f32_16x16x32_bf16 v[100:103], v[146:149], v[206:209], v[100:103]
	v_mfma_f32_16x16x32_bf16 v[96:99], v[154:157], v[206:209], v[96:99]
	v_mfma_f32_16x16x32_bf16 v[84:87], v[146:149], v[214:217], v[84:87]
	v_mfma_f32_16x16x32_bf16 v[80:83], v[154:157], v[214:217], v[80:83]
	v_mfma_f32_16x16x32_bf16 v[112:115], v[158:161], v[174:177], v[112:115]
	v_mfma_f32_16x16x32_bf16 v[104:107], v[166:169], v[174:177], v[104:107]
	v_mfma_f32_16x16x32_bf16 v[92:95], v[158:161], v[182:185], v[92:95]
	v_mfma_f32_16x16x32_bf16 v[88:91], v[166:169], v[182:185], v[88:91]
	v_mfma_f32_16x16x32_bf16 v[76:79], v[158:161], v[202:205], v[76:79]
	v_mfma_f32_16x16x32_bf16 v[72:75], v[166:169], v[202:205], v[72:75]
	v_mfma_f32_16x16x32_bf16 v[68:71], v[158:161], v[210:213], v[68:71]
	v_mfma_f32_16x16x32_bf16 v[64:67], v[166:169], v[210:213], v[64:67]
	v_mfma_f32_16x16x32_bf16 v[112:115], v[162:165], v[178:181], v[112:115]
	v_mfma_f32_16x16x32_bf16 v[104:107], v[170:173], v[178:181], v[104:107]
	v_mfma_f32_16x16x32_bf16 v[92:95], v[162:165], v[198:201], v[92:95]
	v_mfma_f32_16x16x32_bf16 v[88:91], v[170:173], v[198:201], v[88:91]
	v_mfma_f32_16x16x32_bf16 v[76:79], v[162:165], v[206:209], v[76:79]
	v_mfma_f32_16x16x32_bf16 v[72:75], v[170:173], v[206:209], v[72:75]
	v_mfma_f32_16x16x32_bf16 v[68:71], v[162:165], v[214:217], v[68:71]
	v_mfma_f32_16x16x32_bf16 v[64:67], v[170:173], v[214:217], v[64:67]
	s_setprio 0
	s_barrier
; #define PG8_STAGE(bufoff, gbase, voff) do { _Pragma("unroll") for (int _i = 0; _i < 2; ++_i) \
;         __builtin_amdgcn_global_load_lds((const unsigned*)((const char*)(gbase) + (voff)[_i]), (LAS unsigned*)(lds + (bufoff) + ldsw + _i * 8192), 16, 0, 0); } while (0)
; #define PG8_LDA(dst, b, h) do { _Pragma("unroll") for (int m = 0; m < 4; ++m) _Pragma("unroll") for (int k = 0; k < 2; ++k) dst[m][k] = *(const LAS bf16x8*)(lds + PG8_SA(b, h) + aoff + m * 2048 + k * 1024); } while (0)
; #define PG8_MMA(ai, bj, At, Bt) do { __builtin_amdgcn_s_setprio(1); _Pragma("unroll") for (int m = 0; m < 4; ++m) _Pragma("unroll") for (int n = 0; n < 2; ++n) _Pragma("unroll") for (int k = 0; k < 2; ++k) \
;         acc[ai][bj][m][n] = __builtin_amdgcn_mfma_f32_16x16x32_bf16(Bt[n][k], At[m][k], acc[ai][bj][m][n], 0, 0, 0); __builtin_amdgcn_s_setprio(0); } while (0)
; #define PG8_WAIT_V(n) asm volatile("s_waitcnt vmcnt(" #n ")" ::: "memory")
; #define PG8_WAIT_L(n) asm volatile("s_waitcnt lgkmcnt(" #n ")" ::: "memory")
; #define PG8_BAR __builtin_amdgcn_s_barrier()
; #define PG8_SCHED __builtin_amdgcn_sched_barrier(0)
; template <class Epi, class Sched>
; __device__ __forceinline__ void gemm_phase(int wv, LAS unsigned char* lds, const Gemm g, const Sched& S, const Epi& E) {
;     ...
;             PG8_LDA(At, 1, 1); PG8_STAGE(PG8_SB(1, 0), b3, voffB); PG8_STAGE(PG8_SB(1, 1), b3 + hstepB, voffB); PG8_STAGE(PG8_SA(1, 0), a3, voffA);
;             PG8_WAIT_V(8); PG8_WAIT_L(0); PG8_BAR; PG8_MMA(1, 0, At, B0); PG8_MMA(1, 1, At, B1); PG8_BAR; PG8_SCHED;
;         }
	s_add_i32 s22, s95, s28
	v_lshl_add_u64 v[186:187], v[186:187], 0, s[74:75]
	s_mov_b32 m0, s22
	ds_read_b128 v[174:177], v141 offset:49152
	ds_read_b128 v[178:181], v141 offset:50176
	ds_read_b128 v[182:185], v141 offset:51200
	ds_read_b128 v[198:201], v141 offset:52224
	ds_read_b128 v[202:205], v141 offset:53248
	ds_read_b128 v[206:209], v141 offset:54272
	ds_read_b128 v[210:213], v141 offset:55296
	ds_read_b128 v[214:217], v141 offset:56320
	global_load_lds_dwordx4 v[186:187], off
	s_add_i32 m0, s22, 0x2000
	s_add_u32 s20, s20, 0x2080
	v_lshl_add_u64 v[186:187], v[218:219], 0, s[74:75]
	s_addc_u32 s21, s21, 0
	s_add_i32 s22, s44, s28
	global_load_lds_dwordx4 v[186:187], off
	v_lshl_add_u64 v[186:187], s[20:21], 0, v[188:189]
	s_mov_b32 m0, s22
	s_nop 0
	global_load_lds_dwordx4 v[186:187], off
	v_lshl_add_u64 v[186:187], s[20:21], 0, v[128:129]
	s_add_i32 m0, s22, 0x2000
	s_nop 0
	global_load_lds_dwordx4 v[186:187], off
	v_lshl_add_u64 v[186:187], v[220:221], 0, s[74:75]
	s_mov_b32 m0, s35
	s_nop 0
	global_load_lds_dwordx4 v[186:187], off
	v_lshl_add_u64 v[186:187], v[222:223], 0, s[74:75]
	s_mov_b32 m0, s36
	s_nop 0
	global_load_lds_dwordx4 v[186:187], off
	s_waitcnt vmcnt(8)
	s_waitcnt lgkmcnt(0)
	s_barrier
	s_setprio 1
	s_waitcnt lgkmcnt(0)
	v_mfma_f32_16x16x32_bf16 v[60:63], v[142:145], v[174:177], v[60:63]
	v_mfma_f32_16x16x32_bf16 v[56:59], v[150:153], v[174:177], v[56:59]
	v_mfma_f32_16x16x32_bf16 v[52:55], v[142:145], v[182:185], v[52:55]
	v_mfma_f32_16x16x32_bf16 v[48:51], v[150:153], v[182:185], v[48:51]
	v_mfma_f32_16x16x32_bf16 v[36:39], v[142:145], v[202:205], v[36:39]
	v_mfma_f32_16x16x32_bf16 v[32:35], v[150:153], v[202:205], v[32:35]
	v_mfma_f32_16x16x32_bf16 v[20:23], v[142:145], v[210:213], v[20:23]
	v_mfma_f32_16x16x32_bf16 v[16:19], v[150:153], v[210:213], v[16:19]
	v_mfma_f32_16x16x32_bf16 v[60:63], v[146:149], v[178:181], v[60:63]
	v_mfma_f32_16x16x32_bf16 v[56:59], v[154:157], v[178:181], v[56:59]
	v_mfma_f32_16x16x32_bf16 v[52:55], v[146:149], v[198:201], v[52:55]
	v_mfma_f32_16x16x32_bf16 v[48:51], v[154:157], v[198:201], v[48:51]
	v_mfma_f32_16x16x32_bf16 v[36:39], v[146:149], v[206:209], v[36:39]
	v_mfma_f32_16x16x32_bf16 v[32:35], v[154:157], v[206:209], v[32:35]
	v_mfma_f32_16x16x32_bf16 v[20:23], v[146:149], v[214:217], v[20:23]
	v_mfma_f32_16x16x32_bf16 v[16:19], v[154:157], v[214:217], v[16:19]
	v_mfma_f32_16x16x32_bf16 v[44:47], v[158:161], v[174:177], v[44:47]
	v_mfma_f32_16x16x32_bf16 v[40:43], v[166:169], v[174:177], v[40:43]
	v_mfma_f32_16x16x32_bf16 v[28:31], v[158:161], v[182:185], v[28:31]
	v_mfma_f32_16x16x32_bf16 v[24:27], v[166:169], v[182:185], v[24:27]
	v_mfma_f32_16x16x32_bf16 v[12:15], v[158:161], v[202:205], v[12:15]
	v_mfma_f32_16x16x32_bf16 v[8:11], v[166:169], v[202:205], v[8:11]
	v_mfma_f32_16x16x32_bf16 v[4:7], v[158:161], v[210:213], v[4:7]
	v_mfma_f32_16x16x32_bf16 v[0:3], v[166:169], v[210:213], v[0:3]
	v_mfma_f32_16x16x32_bf16 v[44:47], v[162:165], v[178:181], v[44:47]
	v_mfma_f32_16x16x32_bf16 v[40:43], v[170:173], v[178:181], v[40:43]
	v_mfma_f32_16x16x32_bf16 v[28:31], v[162:165], v[198:201], v[28:31]
	v_mfma_f32_16x16x32_bf16 v[24:27], v[170:173], v[198:201], v[24:27]
	v_mfma_f32_16x16x32_bf16 v[12:15], v[162:165], v[206:209], v[12:15]
	v_mfma_f32_16x16x32_bf16 v[8:11], v[170:173], v[206:209], v[8:11]
	v_mfma_f32_16x16x32_bf16 v[4:7], v[162:165], v[214:217], v[4:7]
	v_mfma_f32_16x16x32_bf16 v[0:3], v[170:173], v[214:217], v[0:3]
	s_setprio 0
	s_barrier
	s_add_i32 s43, s43, 2
	s_add_u32 s18, s18, 0x100
	s_addc_u32 s19, s19, 0
	s_add_u32 s41, s41, 0x100
	s_addc_u32 s42, s42, 0
	s_cmp_gt_u32 s43, 5
	s_cbranch_scc0 .LBB0_801
	s_and_b64 vcc, exec, s[8:9]
	s_cbranch_vccz .LBB0_804
	s_barrier

; #define PG8_STAGE(bufoff, gbase, voff) do { _Pragma("unroll") for (int _i = 0; _i < 2; ++_i) \
;         __builtin_amdgcn_global_load_lds((const unsigned*)((const char*)(gbase) + (voff)[_i]), (LAS unsigned*)(lds + (bufoff) + ldsw + _i * 8192), 16, 0, 0); } while (0)
; #define PG8_LDA(dst, b, h) do { _Pragma("unroll") for (int m = 0; m < 4; ++m) _Pragma("unroll") for (int k = 0; k < 2; ++k) dst[m][k] = *(const LAS bf16x8*)(lds + PG8_SA(b, h) + aoff + m * 2048 + k * 1024); } while (0)
; #define PG8_LDB(dst, b, h) do { _Pragma("unroll") for (int n = 0; n < 2; ++n) _Pragma("unroll") for (int k = 0; k < 2; ++k) dst[n][k] = *(const LAS bf16x8*)(lds + PG8_SB(b, h) + boff + n * 2048 + k * 1024); } while (0)
; #define PG8_MMA(ai, bj, At, Bt) do { __builtin_amdgcn_s_setprio(1); _Pragma("unroll") for (int m = 0; m < 4; ++m) _Pragma("unroll") for (int n = 0; n < 2; ++n) _Pragma("unroll") for (int k = 0; k < 2; ++k) \
;         acc[ai][bj][m][n] = __builtin_amdgcn_mfma_f32_16x16x32_bf16(Bt[n][k], At[m][k], acc[ai][bj][m][n], 0, 0, 0); __builtin_amdgcn_s_setprio(0); } while (0)
; #define PG8_WAIT_V(n) asm volatile("s_waitcnt vmcnt(" #n ")" ::: "memory")
; #define PG8_WAIT_L(n) asm volatile("s_waitcnt lgkmcnt(" #n ")" ::: "memory")
; #define PG8_BAR __builtin_amdgcn_s_barrier()
; #define PG8_SCHED __builtin_amdgcn_sched_barrier(0)
; template <class Epi, class Sched>
; __device__ __forceinline__ void gemm_phase(int wv, LAS unsigned char* lds, const Gemm g, const Sched& S, const Epi& E) {
;     ...
;         for (int t = 0; t < nt; t += 2) {
;             const bool last = (t == nt - 2);
;             const char* a1 = cA + (size_t)(t + 1) * kstep;
;             const char* a2 = last ? nA : cA + (size_t)(t + 2) * kstep; const char* b2 = last ? nB : cB + (size_t)(t + 2) * kstep;
;             const char* a3 = a2 + kstep; const char* b3 = b2 + kstep;
;             PG8_LDB(B0, 0, 0); PG8_LDB(B1, 0, 1); PG8_SCHED; PG8_LDA(At, 0, 0); PG8_STAGE(PG8_SA(1, 1), a1 + hstep, voffA);
;             PG8_WAIT_V(8); PG8_WAIT_L(0); PG8_BAR; PG8_MMA(0, 0, At, B0); PG8_MMA(0, 1, At, B1); PG8_BAR; PG8_SCHED;
;             PG8_LDA(At, 0, 1); PG8_STAGE(PG8_SB(0, 0), b2, voffB); PG8_STAGE(PG8_SB(0, 1), b2 + hstepB, voffB); PG8_STAGE(PG8_SA(0, 0), a2, voffA);
;             PG8_WAIT_V(8); PG8_WAIT_L(0); PG8_BAR; PG8_MMA(1, 0, At, B0); PG8_MMA(1, 1, At, B1); PG8_BAR; PG8_SCHED;
.LBB0_821:
	s_add_u32 s22, s20, 0xfffc0080
	s_addc_u32 s23, s21, -1
	s_add_i32 s47, 0, 0x10000
	s_cmp_eq_u32 s46, 12
	s_cselect_b32 s25, s13, s23
	s_cselect_b32 s24, s42, s22
	s_cselect_b32 s23, s15, s45
	s_cselect_b32 s22, s43, s44
	s_add_i32 s50, 0, 0x14000
	v_add_u32_e32 v140, s47, v201
	v_add_u32_e32 v156, s50, v201
	ds_read_b128 v[120:123], v140
	ds_read_b128 v[124:127], v140 offset:1024
	ds_read_b128 v[136:139], v140 offset:2048
	ds_read_b128 v[140:143], v140 offset:3072
	ds_read_b128 v[144:147], v156
	ds_read_b128 v[148:151], v156 offset:1024
	ds_read_b128 v[152:155], v156 offset:2048
	ds_read_b128 v[156:159], v156 offset:3072
	v_lshl_add_u64 v[186:187], s[20:21], 0, v[174:175]
	s_add_i32 m0, s31, 0xc000
	ds_read_b128 v[160:163], v203
	ds_read_b128 v[164:167], v203 offset:1024
	ds_read_b128 v[178:181], v203 offset:2048
	ds_read_b128 v[182:185], v203 offset:3072
	ds_read_b128 v[204:207], v203 offset:4096
	ds_read_b128 v[208:211], v203 offset:5120
	ds_read_b128 v[212:215], v203 offset:6144
	ds_read_b128 v[216:219], v203 offset:7168
	global_load_lds_dwordx4 v[186:187], off
	v_lshl_add_u64 v[186:187], s[20:21], 0, v[176:177]
	s_add_i32 m0, s31, 0xe000
	s_nop 0
	global_load_lds_dwordx4 v[186:187], off
	s_waitcnt vmcnt(8)
	s_waitcnt lgkmcnt(0)
	s_barrier
	s_setprio 1
	s_waitcnt lgkmcnt(0)
	v_mfma_f32_16x16x32_bf16 v[132:135], v[120:123], v[160:163], v[132:135]
	v_mfma_f32_16x16x32_bf16 v[116:119], v[136:139], v[160:163], v[116:119]
	v_mfma_f32_16x16x32_bf16 v[108:111], v[120:123], v[178:181], v[108:111]
	v_mfma_f32_16x16x32_bf16 v[100:103], v[136:139], v[178:181], v[100:103]
	v_mfma_f32_16x16x32_bf16 v[92:95], v[120:123], v[204:207], v[92:95]
	v_mfma_f32_16x16x32_bf16 v[84:87], v[136:139], v[204:207], v[84:87]
	v_mfma_f32_16x16x32_bf16 v[76:79], v[120:123], v[212:215], v[76:79]
	v_mfma_f32_16x16x32_bf16 v[68:71], v[136:139], v[212:215], v[68:71]
	v_mfma_f32_16x16x32_bf16 v[132:135], v[124:127], v[164:167], v[132:135]
	v_mfma_f32_16x16x32_bf16 v[116:119], v[140:143], v[164:167], v[116:119]
	v_mfma_f32_16x16x32_bf16 v[108:111], v[124:127], v[182:185], v[108:111]
	v_mfma_f32_16x16x32_bf16 v[100:103], v[140:143], v[182:185], v[100:103]
	v_mfma_f32_16x16x32_bf16 v[92:95], v[124:127], v[208:211], v[92:95]
	v_mfma_f32_16x16x32_bf16 v[84:87], v[140:143], v[208:211], v[84:87]
	v_mfma_f32_16x16x32_bf16 v[76:79], v[124:127], v[216:219], v[76:79]
	v_mfma_f32_16x16x32_bf16 v[68:71], v[140:143], v[216:219], v[68:71]
	v_mfma_f32_16x16x32_bf16 v[128:131], v[144:147], v[160:163], v[128:131]
	v_mfma_f32_16x16x32_bf16 v[112:115], v[152:155], v[160:163], v[112:115]
	v_mfma_f32_16x16x32_bf16 v[104:107], v[144:147], v[178:181], v[104:107]
	v_mfma_f32_16x16x32_bf16 v[96:99], v[152:155], v[178:181], v[96:99]
	v_mfma_f32_16x16x32_bf16 v[88:91], v[144:147], v[204:207], v[88:91]
	v_mfma_f32_16x16x32_bf16 v[80:83], v[152:155], v[204:207], v[80:83]
	v_mfma_f32_16x16x32_bf16 v[72:75], v[144:147], v[212:215], v[72:75]
	v_mfma_f32_16x16x32_bf16 v[64:67], v[152:155], v[212:215], v[64:67]
	v_mfma_f32_16x16x32_bf16 v[128:131], v[148:151], v[164:167], v[128:131]
	v_mfma_f32_16x16x32_bf16 v[112:115], v[156:159], v[164:167], v[112:115]
	v_mfma_f32_16x16x32_bf16 v[104:107], v[148:151], v[182:185], v[104:107]
	v_mfma_f32_16x16x32_bf16 v[96:99], v[156:159], v[182:185], v[96:99]
	v_mfma_f32_16x16x32_bf16 v[88:91], v[148:151], v[208:211], v[88:91]
	v_mfma_f32_16x16x32_bf16 v[80:83], v[156:159], v[208:211], v[80:83]
	v_mfma_f32_16x16x32_bf16 v[72:75], v[148:151], v[216:219], v[72:75]
	v_mfma_f32_16x16x32_bf16 v[64:67], v[156:159], v[216:219], v[64:67]
	s_setprio 0
	s_barrier
	s_add_i32 s47, s47, s30
	v_lshl_add_u64 v[186:187], s[22:23], 0, v[188:189]
	s_mov_b32 m0, s47
	ds_read_b128 v[160:163], v203 offset:16384
	ds_read_b128 v[164:167], v203 offset:17408
	ds_read_b128 v[178:181], v203 offset:18432
	ds_read_b128 v[182:185], v203 offset:19456
	ds_read_b128 v[204:207], v203 offset:20480
	ds_read_b128 v[208:211], v203 offset:21504
	ds_read_b128 v[212:215], v203 offset:22528
	ds_read_b128 v[216:219], v203 offset:23552
	global_load_lds_dwordx4 v[186:187], off
	s_add_i32 m0, s47, 0x2000
	s_add_u32 s48, s22, 0x200000
	v_lshl_add_u64 v[198:199], s[22:23], 0, v[168:169]
	s_addc_u32 s49, s23, 0
	s_add_i32 s47, s50, s30
	global_load_lds_dwordx4 v[198:199], off
	v_lshl_add_u64 v[220:221], s[48:49], 0, v[188:189]
	s_mov_b32 m0, s47
	v_lshl_add_u64 v[222:223], s[24:25], 0, v[170:171]
	global_load_lds_dwordx4 v[220:221], off
	v_lshl_add_u64 v[220:221], s[48:49], 0, v[168:169]
	s_add_i32 m0, s47, 0x2000
	s_nop 0
	global_load_lds_dwordx4 v[220:221], off
	v_lshl_add_u64 v[220:221], s[24:25], 0, v[172:173]
	s_mov_b32 m0, s31
	s_nop 0
	global_load_lds_dwordx4 v[220:221], off
	s_mov_b32 m0, s34
	s_nop 0
	global_load_lds_dwordx4 v[222:223], off
	s_waitcnt vmcnt(8)
	s_waitcnt lgkmcnt(0)
	s_barrier
; #define PG8_STAGE(bufoff, gbase, voff) do { _Pragma("unroll") for (int _i = 0; _i < 2; ++_i) \
;         __builtin_amdgcn_global_load_lds((const unsigned*)((const char*)(gbase) + (voff)[_i]), (LAS unsigned*)(lds + (bufoff) + ldsw + _i * 8192), 16, 0, 0); } while (0)
; #define PG8_LDA(dst, b, h) do { _Pragma("unroll") for (int m = 0; m < 4; ++m) _Pragma("unroll") for (int k = 0; k < 2; ++k) dst[m][k] = *(const LAS bf16x8*)(lds + PG8_SA(b, h) + aoff + m * 2048 + k * 1024); } while (0)
; #define PG8_LDB(dst, b, h) do { _Pragma("unroll") for (int n = 0; n < 2; ++n) _Pragma("unroll") for (int k = 0; k < 2; ++k) dst[n][k] = *(const LAS bf16x8*)(lds + PG8_SB(b, h) + boff + n * 2048 + k * 1024); } while (0)
; #define PG8_MMA(ai, bj, At, Bt) do { __builtin_amdgcn_s_setprio(1); _Pragma("unroll") for (int m = 0; m < 4; ++m) _Pragma("unroll") for (int n = 0; n < 2; ++n) _Pragma("unroll") for (int k = 0; k < 2; ++k) \
;         acc[ai][bj][m][n] = __builtin_amdgcn_mfma_f32_16x16x32_bf16(Bt[n][k], At[m][k], acc[ai][bj][m][n], 0, 0, 0); __builtin_amdgcn_s_setprio(0); } while (0)
; #define PG8_WAIT_V(n) asm volatile("s_waitcnt vmcnt(" #n ")" ::: "memory")
; #define PG8_WAIT_L(n) asm volatile("s_waitcnt lgkmcnt(" #n ")" ::: "memory")
; #define PG8_BAR __builtin_amdgcn_s_barrier()
; #define PG8_SCHED __builtin_amdgcn_sched_barrier(0)
; template <class Epi, class Sched>
; __device__ __forceinline__ void gemm_phase(int wv, LAS unsigned char* lds, const Gemm g, const Sched& S, const Epi& E) {
;     ...
;             PG8_WAIT_V(8); PG8_WAIT_L(0); PG8_BAR; PG8_MMA(1, 0, At, B0); PG8_MMA(1, 1, At, B1); PG8_BAR; PG8_SCHED;
;             PG8_LDB(B0, 1, 0); PG8_LDB(B1, 1, 1); PG8_SCHED; PG8_LDA(At, 1, 0); PG8_STAGE(PG8_SA(0, 1), a2 + hstep, voffA);
;             PG8_WAIT_V(8); PG8_WAIT_L(0); PG8_BAR; PG8_MMA(0, 0, At, B0); PG8_MMA(0, 1, At, B1); PG8_BAR; PG8_SCHED;
	s_setprio 1
	s_waitcnt lgkmcnt(0)
	v_mfma_f32_16x16x32_bf16 v[60:63], v[120:123], v[160:163], v[60:63]
	v_mfma_f32_16x16x32_bf16 v[52:55], v[136:139], v[160:163], v[52:55]
	v_mfma_f32_16x16x32_bf16 v[44:47], v[120:123], v[178:181], v[44:47]
	v_mfma_f32_16x16x32_bf16 v[36:39], v[136:139], v[178:181], v[36:39]
	v_mfma_f32_16x16x32_bf16 v[28:31], v[120:123], v[204:207], v[28:31]
	v_mfma_f32_16x16x32_bf16 v[20:23], v[136:139], v[204:207], v[20:23]
	v_mfma_f32_16x16x32_bf16 v[12:15], v[120:123], v[212:215], v[12:15]
	v_mfma_f32_16x16x32_bf16 v[4:7], v[136:139], v[212:215], v[4:7]
	v_mfma_f32_16x16x32_bf16 v[60:63], v[124:127], v[164:167], v[60:63]
	v_mfma_f32_16x16x32_bf16 v[52:55], v[140:143], v[164:167], v[52:55]
	v_mfma_f32_16x16x32_bf16 v[44:47], v[124:127], v[182:185], v[44:47]
	v_mfma_f32_16x16x32_bf16 v[36:39], v[140:143], v[182:185], v[36:39]
	v_mfma_f32_16x16x32_bf16 v[28:31], v[124:127], v[208:211], v[28:31]
	v_mfma_f32_16x16x32_bf16 v[20:23], v[140:143], v[208:211], v[20:23]
	v_mfma_f32_16x16x32_bf16 v[12:15], v[124:127], v[216:219], v[12:15]
	v_mfma_f32_16x16x32_bf16 v[4:7], v[140:143], v[216:219], v[4:7]
	v_mfma_f32_16x16x32_bf16 v[56:59], v[144:147], v[160:163], v[56:59]
	v_mfma_f32_16x16x32_bf16 v[48:51], v[152:155], v[160:163], v[48:51]
	v_mfma_f32_16x16x32_bf16 v[40:43], v[144:147], v[178:181], v[40:43]
	v_mfma_f32_16x16x32_bf16 v[32:35], v[152:155], v[178:181], v[32:35]
	v_mfma_f32_16x16x32_bf16 v[24:27], v[144:147], v[204:207], v[24:27]
	v_mfma_f32_16x16x32_bf16 v[16:19], v[152:155], v[204:207], v[16:19]
	v_mfma_f32_16x16x32_bf16 v[8:11], v[144:147], v[212:215], v[8:11]
	v_mfma_f32_16x16x32_bf16 v[0:3], v[152:155], v[212:215], v[0:3]
	v_mfma_f32_16x16x32_bf16 v[56:59], v[148:151], v[164:167], v[56:59]
	v_mfma_f32_16x16x32_bf16 v[48:51], v[156:159], v[164:167], v[48:51]
	v_mfma_f32_16x16x32_bf16 v[40:43], v[148:151], v[182:185], v[40:43]
	v_mfma_f32_16x16x32_bf16 v[32:35], v[156:159], v[182:185], v[32:35]
	v_mfma_f32_16x16x32_bf16 v[24:27], v[148:151], v[208:211], v[24:27]
	v_mfma_f32_16x16x32_bf16 v[16:19], v[156:159], v[208:211], v[16:19]
	v_mfma_f32_16x16x32_bf16 v[8:11], v[148:151], v[216:219], v[8:11]
	v_mfma_f32_16x16x32_bf16 v[0:3], v[156:159], v[216:219], v[0:3]
	s_setprio 0
	s_barrier
	s_add_i32 s47, 0, 0x1c000
	v_add_u32_e32 v140, s95, v201
	v_add_u32_e32 v156, s47, v201
	ds_read_b128 v[120:123], v140
	ds_read_b128 v[124:127], v140 offset:1024
	ds_read_b128 v[136:139], v140 offset:2048
	ds_read_b128 v[140:143], v140 offset:3072
	ds_read_b128 v[144:147], v156
	ds_read_b128 v[148:151], v156 offset:1024
	ds_read_b128 v[152:155], v156 offset:2048
	ds_read_b128 v[156:159], v156 offset:3072
	s_add_u32 s24, s24, 0x40000
	s_addc_u32 s25, s25, 0
	s_mov_b32 m0, s35
	v_lshl_add_u64 v[228:229], s[24:25], 0, v[172:173]
	ds_read_b128 v[160:163], v203 offset:32768
	ds_read_b128 v[164:167], v203 offset:33792
	ds_read_b128 v[178:181], v203 offset:34816
	ds_read_b128 v[182:185], v203 offset:35840
	ds_read_b128 v[204:207], v203 offset:36864
	ds_read_b128 v[208:211], v203 offset:37888
	ds_read_b128 v[212:215], v203 offset:38912
	ds_read_b128 v[216:219], v203 offset:39936
	global_load_lds_dwordx4 v[228:229], off
	v_lshl_add_u64 v[228:229], s[24:25], 0, v[170:171]
	s_mov_b32 m0, s36
	s_nop 0
	global_load_lds_dwordx4 v[228:229], off
	s_waitcnt vmcnt(8)
	s_waitcnt lgkmcnt(0)
	s_barrier
	s_setprio 1
	s_waitcnt lgkmcnt(0)
	v_mfma_f32_16x16x32_bf16 v[132:135], v[120:123], v[160:163], v[132:135]
	v_mfma_f32_16x16x32_bf16 v[116:119], v[136:139], v[160:163], v[116:119]
	v_mfma_f32_16x16x32_bf16 v[108:111], v[120:123], v[178:181], v[108:111]
	v_mfma_f32_16x16x32_bf16 v[100:103], v[136:139], v[178:181], v[100:103]
	v_mfma_f32_16x16x32_bf16 v[92:95], v[120:123], v[204:207], v[92:95]
	v_mfma_f32_16x16x32_bf16 v[84:87], v[136:139], v[204:207], v[84:87]
	v_mfma_f32_16x16x32_bf16 v[76:79], v[120:123], v[212:215], v[76:79]
	v_mfma_f32_16x16x32_bf16 v[68:71], v[136:139], v[212:215], v[68:71]
	v_mfma_f32_16x16x32_bf16 v[132:135], v[124:127], v[164:167], v[132:135]
	v_mfma_f32_16x16x32_bf16 v[116:119], v[140:143], v[164:167], v[116:119]
	v_mfma_f32_16x16x32_bf16 v[108:111], v[124:127], v[182:185], v[108:111]
	v_mfma_f32_16x16x32_bf16 v[100:103], v[140:143], v[182:185], v[100:103]
	v_mfma_f32_16x16x32_bf16 v[92:95], v[124:127], v[208:211], v[92:95]
	v_mfma_f32_16x16x32_bf16 v[84:87], v[140:143], v[208:211], v[84:87]
	v_mfma_f32_16x16x32_bf16 v[76:79], v[124:127], v[216:219], v[76:79]
	v_mfma_f32_16x16x32_bf16 v[68:71], v[140:143], v[216:219], v[68:71]
	v_mfma_f32_16x16x32_bf16 v[128:131], v[144:147], v[160:163], v[128:131]
	v_mfma_f32_16x16x32_bf16 v[112:115], v[152:155], v[160:163], v[112:115]
	v_mfma_f32_16x16x32_bf16 v[104:107], v[144:147], v[178:181], v[104:107]
	v_mfma_f32_16x16x32_bf16 v[96:99], v[152:155], v[178:181], v[96:99]
	v_mfma_f32_16x16x32_bf16 v[88:91], v[144:147], v[204:207], v[88:91]
	v_mfma_f32_16x16x32_bf16 v[80:83], v[152:155], v[204:207], v[80:83]
	v_mfma_f32_16x16x32_bf16 v[72:75], v[144:147], v[212:215], v[72:75]
	v_mfma_f32_16x16x32_bf16 v[64:67], v[152:155], v[212:215], v[64:67]
	v_mfma_f32_16x16x32_bf16 v[128:131], v[148:151], v[164:167], v[128:131]
	v_mfma_f32_16x16x32_bf16 v[112:115], v[156:159], v[164:167], v[112:115]
	v_mfma_f32_16x16x32_bf16 v[104:107], v[148:151], v[182:185], v[104:107]
	v_mfma_f32_16x16x32_bf16 v[96:99], v[156:159], v[182:185], v[96:99]
	v_mfma_f32_16x16x32_bf16 v[88:91], v[148:151], v[208:211], v[88:91]
	v_mfma_f32_16x16x32_bf16 v[80:83], v[156:159], v[208:211], v[80:83]
	v_mfma_f32_16x16x32_bf16 v[72:75], v[148:151], v[216:219], v[72:75]
	v_mfma_f32_16x16x32_bf16 v[64:67], v[156:159], v[216:219], v[64:67]
	s_setprio 0
	s_barrier
; #define PG8_STAGE(bufoff, gbase, voff) do { _Pragma("unroll") for (int _i = 0; _i < 2; ++_i) \
;         __builtin_amdgcn_global_load_lds((const unsigned*)((const char*)(gbase) + (voff)[_i]), (LAS unsigned*)(lds + (bufoff) + ldsw + _i * 8192), 16, 0, 0); } while (0)
; #define PG8_LDA(dst, b, h) do { _Pragma("unroll") for (int m = 0; m < 4; ++m) _Pragma("unroll") for (int k = 0; k < 2; ++k) dst[m][k] = *(const LAS bf16x8*)(lds + PG8_SA(b, h) + aoff + m * 2048 + k * 1024); } while (0)
; #define PG8_MMA(ai, bj, At, Bt) do { __builtin_amdgcn_s_setprio(1); _Pragma("unroll") for (int m = 0; m < 4; ++m) _Pragma("unroll") for (int n = 0; n < 2; ++n) _Pragma("unroll") for (int k = 0; k < 2; ++k) \
;         acc[ai][bj][m][n] = __builtin_amdgcn_mfma_f32_16x16x32_bf16(Bt[n][k], At[m][k], acc[ai][bj][m][n], 0, 0, 0); __builtin_amdgcn_s_setprio(0); } while (0)
; #define PG8_WAIT_V(n) asm volatile("s_waitcnt vmcnt(" #n ")" ::: "memory")
; #define PG8_WAIT_L(n) asm volatile("s_waitcnt lgkmcnt(" #n ")" ::: "memory")
; #define PG8_BAR __builtin_amdgcn_s_barrier()
; #define PG8_SCHED __builtin_amdgcn_sched_barrier(0)
; template <class Epi, class Sched>
; __device__ __forceinline__ void gemm_phase(int wv, LAS unsigned char* lds, const Gemm g, const Sched& S, const Epi& E) {
;     ...
;             PG8_LDA(At, 1, 1); PG8_STAGE(PG8_SB(1, 0), b3, voffB); PG8_STAGE(PG8_SB(1, 1), b3 + hstepB, voffB); PG8_STAGE(PG8_SA(1, 0), a3, voffA);
;             PG8_WAIT_V(8); PG8_WAIT_L(0); PG8_BAR; PG8_MMA(1, 0, At, B0); PG8_MMA(1, 1, At, B1); PG8_BAR; PG8_SCHED;
;         }
	s_add_i32 s24, s95, s30
	v_lshl_add_u64 v[186:187], v[186:187], 0, s[74:75]
	s_mov_b32 m0, s24
	ds_read_b128 v[160:163], v203 offset:49152
	ds_read_b128 v[164:167], v203 offset:50176
	ds_read_b128 v[178:181], v203 offset:51200
	ds_read_b128 v[182:185], v203 offset:52224
	ds_read_b128 v[204:207], v203 offset:53248
	ds_read_b128 v[208:211], v203 offset:54272
	ds_read_b128 v[212:215], v203 offset:55296
	ds_read_b128 v[216:219], v203 offset:56320
	global_load_lds_dwordx4 v[186:187], off
	s_add_i32 m0, s24, 0x2000
	s_add_u32 s22, s22, 0x200080
	v_lshl_add_u64 v[186:187], v[198:199], 0, s[74:75]
	s_addc_u32 s23, s23, 0
	s_add_i32 s24, s47, s30
	global_load_lds_dwordx4 v[186:187], off
	v_lshl_add_u64 v[186:187], s[22:23], 0, v[188:189]
	s_mov_b32 m0, s24
	s_nop 0
	global_load_lds_dwordx4 v[186:187], off
	v_lshl_add_u64 v[186:187], s[22:23], 0, v[168:169]
	s_add_i32 m0, s24, 0x2000
	s_nop 0
	global_load_lds_dwordx4 v[186:187], off
	v_lshl_add_u64 v[186:187], v[220:221], 0, s[74:75]
	s_mov_b32 m0, s37
	s_nop 0
	global_load_lds_dwordx4 v[186:187], off
	v_lshl_add_u64 v[186:187], v[222:223], 0, s[74:75]
	s_mov_b32 m0, s38
	s_nop 0
	global_load_lds_dwordx4 v[186:187], off
	s_waitcnt vmcnt(8)
	s_waitcnt lgkmcnt(0)
	s_barrier
	s_setprio 1
	s_waitcnt lgkmcnt(0)
	v_mfma_f32_16x16x32_bf16 v[60:63], v[120:123], v[160:163], v[60:63]
	v_mfma_f32_16x16x32_bf16 v[52:55], v[136:139], v[160:163], v[52:55]
	v_mfma_f32_16x16x32_bf16 v[44:47], v[120:123], v[178:181], v[44:47]
	v_mfma_f32_16x16x32_bf16 v[36:39], v[136:139], v[178:181], v[36:39]
	v_mfma_f32_16x16x32_bf16 v[28:31], v[120:123], v[204:207], v[28:31]
	v_mfma_f32_16x16x32_bf16 v[20:23], v[136:139], v[204:207], v[20:23]
	v_mfma_f32_16x16x32_bf16 v[12:15], v[120:123], v[212:215], v[12:15]
	v_mfma_f32_16x16x32_bf16 v[4:7], v[136:139], v[212:215], v[4:7]
	v_mfma_f32_16x16x32_bf16 v[60:63], v[124:127], v[164:167], v[60:63]
	v_mfma_f32_16x16x32_bf16 v[52:55], v[140:143], v[164:167], v[52:55]
	v_mfma_f32_16x16x32_bf16 v[44:47], v[124:127], v[182:185], v[44:47]
	v_mfma_f32_16x16x32_bf16 v[36:39], v[140:143], v[182:185], v[36:39]
	v_mfma_f32_16x16x32_bf16 v[28:31], v[124:127], v[208:211], v[28:31]
	v_mfma_f32_16x16x32_bf16 v[20:23], v[140:143], v[208:211], v[20:23]
	v_mfma_f32_16x16x32_bf16 v[12:15], v[124:127], v[216:219], v[12:15]
	v_mfma_f32_16x16x32_bf16 v[4:7], v[140:143], v[216:219], v[4:7]
	v_mfma_f32_16x16x32_bf16 v[56:59], v[144:147], v[160:163], v[56:59]
	v_mfma_f32_16x16x32_bf16 v[48:51], v[152:155], v[160:163], v[48:51]
	v_mfma_f32_16x16x32_bf16 v[40:43], v[144:147], v[178:181], v[40:43]
	v_mfma_f32_16x16x32_bf16 v[32:35], v[152:155], v[178:181], v[32:35]
	v_mfma_f32_16x16x32_bf16 v[24:27], v[144:147], v[204:207], v[24:27]
	v_mfma_f32_16x16x32_bf16 v[16:19], v[152:155], v[204:207], v[16:19]
	v_mfma_f32_16x16x32_bf16 v[8:11], v[144:147], v[212:215], v[8:11]
	v_mfma_f32_16x16x32_bf16 v[0:3], v[152:155], v[212:215], v[0:3]
	v_mfma_f32_16x16x32_bf16 v[56:59], v[148:151], v[164:167], v[56:59]
	v_mfma_f32_16x16x32_bf16 v[48:51], v[156:159], v[164:167], v[48:51]
	v_mfma_f32_16x16x32_bf16 v[40:43], v[148:151], v[182:185], v[40:43]
	v_mfma_f32_16x16x32_bf16 v[32:35], v[156:159], v[182:185], v[32:35]
	v_mfma_f32_16x16x32_bf16 v[24:27], v[148:151], v[208:211], v[24:27]
	v_mfma_f32_16x16x32_bf16 v[16:19], v[156:159], v[208:211], v[16:19]
	v_mfma_f32_16x16x32_bf16 v[8:11], v[148:151], v[216:219], v[8:11]
	v_mfma_f32_16x16x32_bf16 v[0:3], v[156:159], v[216:219], v[0:3]
	s_setprio 0
	s_barrier
	s_add_i32 s46, s46, 2
	s_add_u32 s20, s20, 0x100
	s_addc_u32 s21, s21, 0
	s_add_u32 s44, s44, 0x100
	s_addc_u32 s45, s45, 0
	s_cmp_gt_u32 s46, 13
	s_cbranch_scc0 .LBB0_821
	s_and_b64 vcc, exec, s[10:11]
	s_cbranch_vccz .LBB0_824
	s_barrier

; #define PG8_STAGE(bufoff, gbase, voff) do { _Pragma("unroll") for (int _i = 0; _i < 2; ++_i) \
;         __builtin_amdgcn_global_load_lds((const unsigned*)((const char*)(gbase) + (voff)[_i]), (LAS unsigned*)(lds + (bufoff) + ldsw + _i * 8192), 16, 0, 0); } while (0)
; #define PG8_LDA(dst, b, h) do { _Pragma("unroll") for (int m = 0; m < 4; ++m) _Pragma("unroll") for (int k = 0; k < 2; ++k) dst[m][k] = *(const LAS bf16x8*)(lds + PG8_SA(b, h) + aoff + m * 2048 + k * 1024); } while (0)
; #define PG8_LDB(dst, b, h) do { _Pragma("unroll") for (int n = 0; n < 2; ++n) _Pragma("unroll") for (int k = 0; k < 2; ++k) dst[n][k] = *(const LAS bf16x8*)(lds + PG8_SB(b, h) + boff + n * 2048 + k * 1024); } while (0)
; #define PG8_MMA(ai, bj, At, Bt) do { __builtin_amdgcn_s_setprio(1); _Pragma("unroll") for (int m = 0; m < 4; ++m) _Pragma("unroll") for (int n = 0; n < 2; ++n) _Pragma("unroll") for (int k = 0; k < 2; ++k) \
;         acc[ai][bj][m][n] = __builtin_amdgcn_mfma_f32_16x16x32_bf16(Bt[n][k], At[m][k], acc[ai][bj][m][n], 0, 0, 0); __builtin_amdgcn_s_setprio(0); } while (0)
; #define PG8_WAIT_V(n) asm volatile("s_waitcnt vmcnt(" #n ")" ::: "memory")
; #define PG8_WAIT_L(n) asm volatile("s_waitcnt lgkmcnt(" #n ")" ::: "memory")
; #define PG8_BAR __builtin_amdgcn_s_barrier()
; #define PG8_SCHED __builtin_amdgcn_sched_barrier(0)
; template <class Epi, class Sched>
; __device__ __forceinline__ void gemm_phase(int wv, LAS unsigned char* lds, const Gemm g, const Sched& S, const Epi& E) {
;     ...
;         for (int t = 0; t < nt; t += 2) {
;             const bool last = (t == nt - 2);
;             const char* a1 = cA + (size_t)(t + 1) * kstep;
;             const char* a2 = last ? nA : cA + (size_t)(t + 2) * kstep; const char* b2 = last ? nB : cB + (size_t)(t + 2) * kstep;
;             const char* a3 = a2 + kstep; const char* b3 = b2 + kstep;
;             PG8_LDB(B0, 0, 0); PG8_LDB(B1, 0, 1); PG8_SCHED; PG8_LDA(At, 0, 0); PG8_STAGE(PG8_SA(1, 1), a1 + hstep, voffA);
;             PG8_WAIT_V(8); PG8_WAIT_L(0); PG8_BAR; PG8_MMA(0, 0, At, B0); PG8_MMA(0, 1, At, B1); PG8_BAR; PG8_SCHED;
;             PG8_LDA(At, 0, 1); PG8_STAGE(PG8_SB(0, 0), b2, voffB); PG8_STAGE(PG8_SB(0, 1), b2 + hstepB, voffB); PG8_STAGE(PG8_SA(0, 0), a2, voffA);
;             PG8_WAIT_V(8); PG8_WAIT_L(0); PG8_BAR; PG8_MMA(1, 0, At, B0); PG8_MMA(1, 1, At, B1); PG8_BAR; PG8_SCHED;
.LBB0_893:
	s_add_u32 s26, s24, 0xfffc0080
	s_addc_u32 s27, s25, -1
	s_add_i32 s50, 0, 0x10000
	s_cmp_eq_u32 s49, 12
	s_cselect_b32 s29, s17, s27
	s_cselect_b32 s28, s45, s26
	s_cselect_b32 s27, s19, s48
	s_cselect_b32 s26, s46, s47
	s_add_i32 s52, 0, 0x14000
	v_add_u32_e32 v124, s50, v240
	v_add_u32_e32 v156, s52, v240
	ds_read_b128 v[112:115], v124
	ds_read_b128 v[116:119], v124 offset:1024
	ds_read_b128 v[120:123], v124 offset:2048
	ds_read_b128 v[124:127], v124 offset:3072
	ds_read_b128 v[128:131], v156
	ds_read_b128 v[140:143], v156 offset:1024
	ds_read_b128 v[152:155], v156 offset:2048
	ds_read_b128 v[156:159], v156 offset:3072
	v_lshl_add_u64 v[212:213], s[24:25], 0, v[204:205]
	s_add_i32 m0, s37, 0xc000
	ds_read_b128 v[160:163], v244
	ds_read_b128 v[164:167], v244 offset:1024
	ds_read_b128 v[168:171], v244 offset:2048
	ds_read_b128 v[172:175], v244 offset:3072
	ds_read_b128 v[176:179], v244 offset:4096
	ds_read_b128 v[180:183], v244 offset:5120
	ds_read_b128 v[184:187], v244 offset:6144
	ds_read_b128 v[208:211], v244 offset:7168
	global_load_lds_dwordx4 v[212:213], off
	v_lshl_add_u64 v[212:213], s[24:25], 0, v[206:207]
	s_add_i32 m0, s37, 0xe000
	s_nop 0
	global_load_lds_dwordx4 v[212:213], off
	s_waitcnt vmcnt(8)
	s_waitcnt lgkmcnt(0)
	s_barrier
	s_setprio 1
	s_waitcnt lgkmcnt(0)
	v_mfma_f32_16x16x32_bf16 v[148:151], v[112:115], v[160:163], v[148:151]
	v_mfma_f32_16x16x32_bf16 v[144:147], v[120:123], v[160:163], v[144:147]
	v_mfma_f32_16x16x32_bf16 v[108:111], v[112:115], v[168:171], v[108:111]
	v_mfma_f32_16x16x32_bf16 v[104:107], v[120:123], v[168:171], v[104:107]
	v_mfma_f32_16x16x32_bf16 v[92:95], v[112:115], v[176:179], v[92:95]
	v_mfma_f32_16x16x32_bf16 v[88:91], v[120:123], v[176:179], v[88:91]
	v_mfma_f32_16x16x32_bf16 v[76:79], v[112:115], v[184:187], v[76:79]
	v_mfma_f32_16x16x32_bf16 v[72:75], v[120:123], v[184:187], v[72:75]
	v_mfma_f32_16x16x32_bf16 v[148:151], v[116:119], v[164:167], v[148:151]
	v_mfma_f32_16x16x32_bf16 v[144:147], v[124:127], v[164:167], v[144:147]
	v_mfma_f32_16x16x32_bf16 v[108:111], v[116:119], v[172:175], v[108:111]
	v_mfma_f32_16x16x32_bf16 v[104:107], v[124:127], v[172:175], v[104:107]
	v_mfma_f32_16x16x32_bf16 v[92:95], v[116:119], v[180:183], v[92:95]
	v_mfma_f32_16x16x32_bf16 v[88:91], v[124:127], v[180:183], v[88:91]
	v_mfma_f32_16x16x32_bf16 v[76:79], v[116:119], v[208:211], v[76:79]
	v_mfma_f32_16x16x32_bf16 v[72:75], v[124:127], v[208:211], v[72:75]
	v_mfma_f32_16x16x32_bf16 v[136:139], v[128:131], v[160:163], v[136:139]
	v_mfma_f32_16x16x32_bf16 v[132:135], v[152:155], v[160:163], v[132:135]
	v_mfma_f32_16x16x32_bf16 v[100:103], v[128:131], v[168:171], v[100:103]
	v_mfma_f32_16x16x32_bf16 v[96:99], v[152:155], v[168:171], v[96:99]
	v_mfma_f32_16x16x32_bf16 v[84:87], v[128:131], v[176:179], v[84:87]
	v_mfma_f32_16x16x32_bf16 v[80:83], v[152:155], v[176:179], v[80:83]
	v_mfma_f32_16x16x32_bf16 v[68:71], v[128:131], v[184:187], v[68:71]
	v_mfma_f32_16x16x32_bf16 v[64:67], v[152:155], v[184:187], v[64:67]
	v_mfma_f32_16x16x32_bf16 v[136:139], v[140:143], v[164:167], v[136:139]
	v_mfma_f32_16x16x32_bf16 v[132:135], v[156:159], v[164:167], v[132:135]
	v_mfma_f32_16x16x32_bf16 v[100:103], v[140:143], v[172:175], v[100:103]
	v_mfma_f32_16x16x32_bf16 v[96:99], v[156:159], v[172:175], v[96:99]
	v_mfma_f32_16x16x32_bf16 v[84:87], v[140:143], v[180:183], v[84:87]
	v_mfma_f32_16x16x32_bf16 v[80:83], v[156:159], v[180:183], v[80:83]
	v_mfma_f32_16x16x32_bf16 v[68:71], v[140:143], v[208:211], v[68:71]
	v_mfma_f32_16x16x32_bf16 v[64:67], v[156:159], v[208:211], v[64:67]
	s_setprio 0
	s_barrier
	s_add_i32 s50, s50, s36
	v_lshl_add_u64 v[212:213], s[26:27], 0, v[188:189]
	s_mov_b32 m0, s50
	ds_read_b128 v[160:163], v244 offset:16384
	ds_read_b128 v[164:167], v244 offset:17408
	ds_read_b128 v[168:171], v244 offset:18432
	ds_read_b128 v[172:175], v244 offset:19456
	ds_read_b128 v[176:179], v244 offset:20480
	ds_read_b128 v[180:183], v244 offset:21504
	ds_read_b128 v[184:187], v244 offset:22528
	ds_read_b128 v[208:211], v244 offset:23552
	global_load_lds_dwordx4 v[212:213], off
	s_add_i32 m0, s50, 0x2000
	s_add_u32 s50, s26, 0x4000
	v_lshl_add_u64 v[214:215], s[26:27], 0, v[198:199]
	s_addc_u32 s51, s27, 0
	s_add_i32 s52, s52, s36
	global_load_lds_dwordx4 v[214:215], off
	v_lshl_add_u64 v[216:217], s[50:51], 0, v[188:189]
	s_mov_b32 m0, s52
	v_lshl_add_u64 v[218:219], s[28:29], 0, v[200:201]
	global_load_lds_dwordx4 v[216:217], off
	v_lshl_add_u64 v[216:217], s[50:51], 0, v[198:199]
	s_add_i32 m0, s52, 0x2000
	s_nop 0
	global_load_lds_dwordx4 v[216:217], off
	v_lshl_add_u64 v[216:217], s[28:29], 0, v[202:203]
	s_mov_b32 m0, s37
	s_nop 0
	global_load_lds_dwordx4 v[216:217], off
	s_mov_b32 m0, s38
	s_nop 0
	global_load_lds_dwordx4 v[218:219], off
	s_waitcnt vmcnt(8)
	s_waitcnt lgkmcnt(0)
	s_barrier
; #define PG8_STAGE(bufoff, gbase, voff) do { _Pragma("unroll") for (int _i = 0; _i < 2; ++_i) \
;         __builtin_amdgcn_global_load_lds((const unsigned*)((const char*)(gbase) + (voff)[_i]), (LAS unsigned*)(lds + (bufoff) + ldsw + _i * 8192), 16, 0, 0); } while (0)
; #define PG8_LDA(dst, b, h) do { _Pragma("unroll") for (int m = 0; m < 4; ++m) _Pragma("unroll") for (int k = 0; k < 2; ++k) dst[m][k] = *(const LAS bf16x8*)(lds + PG8_SA(b, h) + aoff + m * 2048 + k * 1024); } while (0)
; #define PG8_LDB(dst, b, h) do { _Pragma("unroll") for (int n = 0; n < 2; ++n) _Pragma("unroll") for (int k = 0; k < 2; ++k) dst[n][k] = *(const LAS bf16x8*)(lds + PG8_SB(b, h) + boff + n * 2048 + k * 1024); } while (0)
; #define PG8_MMA(ai, bj, At, Bt) do { __builtin_amdgcn_s_setprio(1); _Pragma("unroll") for (int m = 0; m < 4; ++m) _Pragma("unroll") for (int n = 0; n < 2; ++n) _Pragma("unroll") for (int k = 0; k < 2; ++k) \
;         acc[ai][bj][m][n] = __builtin_amdgcn_mfma_f32_16x16x32_bf16(Bt[n][k], At[m][k], acc[ai][bj][m][n], 0, 0, 0); __builtin_amdgcn_s_setprio(0); } while (0)
; #define PG8_WAIT_V(n) asm volatile("s_waitcnt vmcnt(" #n ")" ::: "memory")
; #define PG8_WAIT_L(n) asm volatile("s_waitcnt lgkmcnt(" #n ")" ::: "memory")
; #define PG8_BAR __builtin_amdgcn_s_barrier()
; #define PG8_SCHED __builtin_amdgcn_sched_barrier(0)
; template <class Epi, class Sched>
; __device__ __forceinline__ void gemm_phase(int wv, LAS unsigned char* lds, const Gemm g, const Sched& S, const Epi& E) {
;     ...
;             PG8_WAIT_V(8); PG8_WAIT_L(0); PG8_BAR; PG8_MMA(1, 0, At, B0); PG8_MMA(1, 1, At, B1); PG8_BAR; PG8_SCHED;
;             PG8_LDB(B0, 1, 0); PG8_LDB(B1, 1, 1); PG8_SCHED; PG8_LDA(At, 1, 0); PG8_STAGE(PG8_SA(0, 1), a2 + hstep, voffA);
;             PG8_WAIT_V(8); PG8_WAIT_L(0); PG8_BAR; PG8_MMA(0, 0, At, B0); PG8_MMA(0, 1, At, B1); PG8_BAR; PG8_SCHED;
	s_setprio 1
	s_waitcnt lgkmcnt(0)
	v_mfma_f32_16x16x32_bf16 v[60:63], v[112:115], v[160:163], v[60:63]
	v_mfma_f32_16x16x32_bf16 v[56:59], v[120:123], v[160:163], v[56:59]
	v_mfma_f32_16x16x32_bf16 v[44:47], v[112:115], v[168:171], v[44:47]
	v_mfma_f32_16x16x32_bf16 v[40:43], v[120:123], v[168:171], v[40:43]
	v_mfma_f32_16x16x32_bf16 v[28:31], v[112:115], v[176:179], v[28:31]
	v_mfma_f32_16x16x32_bf16 v[24:27], v[120:123], v[176:179], v[24:27]
	v_mfma_f32_16x16x32_bf16 v[12:15], v[112:115], v[184:187], v[12:15]
	v_mfma_f32_16x16x32_bf16 v[8:11], v[120:123], v[184:187], v[8:11]
	v_mfma_f32_16x16x32_bf16 v[60:63], v[116:119], v[164:167], v[60:63]
	v_mfma_f32_16x16x32_bf16 v[56:59], v[124:127], v[164:167], v[56:59]
	v_mfma_f32_16x16x32_bf16 v[44:47], v[116:119], v[172:175], v[44:47]
	v_mfma_f32_16x16x32_bf16 v[40:43], v[124:127], v[172:175], v[40:43]
	v_mfma_f32_16x16x32_bf16 v[28:31], v[116:119], v[180:183], v[28:31]
	v_mfma_f32_16x16x32_bf16 v[24:27], v[124:127], v[180:183], v[24:27]
	v_mfma_f32_16x16x32_bf16 v[12:15], v[116:119], v[208:211], v[12:15]
	v_mfma_f32_16x16x32_bf16 v[8:11], v[124:127], v[208:211], v[8:11]
	v_mfma_f32_16x16x32_bf16 v[52:55], v[128:131], v[160:163], v[52:55]
	v_mfma_f32_16x16x32_bf16 v[48:51], v[152:155], v[160:163], v[48:51]
	v_mfma_f32_16x16x32_bf16 v[36:39], v[128:131], v[168:171], v[36:39]
	v_mfma_f32_16x16x32_bf16 v[32:35], v[152:155], v[168:171], v[32:35]
	v_mfma_f32_16x16x32_bf16 v[20:23], v[128:131], v[176:179], v[20:23]
	v_mfma_f32_16x16x32_bf16 v[16:19], v[152:155], v[176:179], v[16:19]
	v_mfma_f32_16x16x32_bf16 v[4:7], v[128:131], v[184:187], v[4:7]
	v_mfma_f32_16x16x32_bf16 v[0:3], v[152:155], v[184:187], v[0:3]
	v_mfma_f32_16x16x32_bf16 v[52:55], v[140:143], v[164:167], v[52:55]
	v_mfma_f32_16x16x32_bf16 v[48:51], v[156:159], v[164:167], v[48:51]
	v_mfma_f32_16x16x32_bf16 v[36:39], v[140:143], v[172:175], v[36:39]
	v_mfma_f32_16x16x32_bf16 v[32:35], v[156:159], v[172:175], v[32:35]
	v_mfma_f32_16x16x32_bf16 v[20:23], v[140:143], v[180:183], v[20:23]
	v_mfma_f32_16x16x32_bf16 v[16:19], v[156:159], v[180:183], v[16:19]
	v_mfma_f32_16x16x32_bf16 v[4:7], v[140:143], v[208:211], v[4:7]
	v_mfma_f32_16x16x32_bf16 v[0:3], v[156:159], v[208:211], v[0:3]
	s_setprio 0
	s_barrier
	s_add_i32 s50, 0, 0x1c000
	v_add_u32_e32 v124, s95, v240
	v_add_u32_e32 v156, s50, v240
	ds_read_b128 v[112:115], v124
	ds_read_b128 v[116:119], v124 offset:1024
	ds_read_b128 v[120:123], v124 offset:2048
	ds_read_b128 v[124:127], v124 offset:3072
	ds_read_b128 v[128:131], v156
	ds_read_b128 v[140:143], v156 offset:1024
	ds_read_b128 v[152:155], v156 offset:2048
	ds_read_b128 v[156:159], v156 offset:3072
	s_add_u32 s28, s28, 0x40000
	s_addc_u32 s29, s29, 0
	s_mov_b32 m0, s39
	v_lshl_add_u64 v[220:221], s[28:29], 0, v[202:203]
	ds_read_b128 v[160:163], v244 offset:32768
	ds_read_b128 v[164:167], v244 offset:33792
	ds_read_b128 v[168:171], v244 offset:34816
	ds_read_b128 v[172:175], v244 offset:35840
	ds_read_b128 v[176:179], v244 offset:36864
	ds_read_b128 v[180:183], v244 offset:37888
	ds_read_b128 v[184:187], v244 offset:38912
	ds_read_b128 v[208:211], v244 offset:39936
	global_load_lds_dwordx4 v[220:221], off
	v_lshl_add_u64 v[220:221], s[28:29], 0, v[200:201]
	s_mov_b32 m0, s40
	s_nop 0
	global_load_lds_dwordx4 v[220:221], off
	s_waitcnt vmcnt(8)
	s_waitcnt lgkmcnt(0)
	s_barrier
	s_setprio 1
	s_waitcnt lgkmcnt(0)
	v_mfma_f32_16x16x32_bf16 v[148:151], v[112:115], v[160:163], v[148:151]
	v_mfma_f32_16x16x32_bf16 v[144:147], v[120:123], v[160:163], v[144:147]
	v_mfma_f32_16x16x32_bf16 v[108:111], v[112:115], v[168:171], v[108:111]
	v_mfma_f32_16x16x32_bf16 v[104:107], v[120:123], v[168:171], v[104:107]
	v_mfma_f32_16x16x32_bf16 v[92:95], v[112:115], v[176:179], v[92:95]
	v_mfma_f32_16x16x32_bf16 v[88:91], v[120:123], v[176:179], v[88:91]
	v_mfma_f32_16x16x32_bf16 v[76:79], v[112:115], v[184:187], v[76:79]
	v_mfma_f32_16x16x32_bf16 v[72:75], v[120:123], v[184:187], v[72:75]
	v_mfma_f32_16x16x32_bf16 v[148:151], v[116:119], v[164:167], v[148:151]
	v_mfma_f32_16x16x32_bf16 v[144:147], v[124:127], v[164:167], v[144:147]
	v_mfma_f32_16x16x32_bf16 v[108:111], v[116:119], v[172:175], v[108:111]
	v_mfma_f32_16x16x32_bf16 v[104:107], v[124:127], v[172:175], v[104:107]
	v_mfma_f32_16x16x32_bf16 v[92:95], v[116:119], v[180:183], v[92:95]
	v_mfma_f32_16x16x32_bf16 v[88:91], v[124:127], v[180:183], v[88:91]
	v_mfma_f32_16x16x32_bf16 v[76:79], v[116:119], v[208:211], v[76:79]
	v_mfma_f32_16x16x32_bf16 v[72:75], v[124:127], v[208:211], v[72:75]
	v_mfma_f32_16x16x32_bf16 v[136:139], v[128:131], v[160:163], v[136:139]
	v_mfma_f32_16x16x32_bf16 v[132:135], v[152:155], v[160:163], v[132:135]
	v_mfma_f32_16x16x32_bf16 v[100:103], v[128:131], v[168:171], v[100:103]
	v_mfma_f32_16x16x32_bf16 v[96:99], v[152:155], v[168:171], v[96:99]
	v_mfma_f32_16x16x32_bf16 v[84:87], v[128:131], v[176:179], v[84:87]
	v_mfma_f32_16x16x32_bf16 v[80:83], v[152:155], v[176:179], v[80:83]
	v_mfma_f32_16x16x32_bf16 v[68:71], v[128:131], v[184:187], v[68:71]
	v_mfma_f32_16x16x32_bf16 v[64:67], v[152:155], v[184:187], v[64:67]
	v_mfma_f32_16x16x32_bf16 v[136:139], v[140:143], v[164:167], v[136:139]
	v_mfma_f32_16x16x32_bf16 v[132:135], v[156:159], v[164:167], v[132:135]
	v_mfma_f32_16x16x32_bf16 v[100:103], v[140:143], v[172:175], v[100:103]
	v_mfma_f32_16x16x32_bf16 v[96:99], v[156:159], v[172:175], v[96:99]
	v_mfma_f32_16x16x32_bf16 v[84:87], v[140:143], v[180:183], v[84:87]
	v_mfma_f32_16x16x32_bf16 v[80:83], v[156:159], v[180:183], v[80:83]
	v_mfma_f32_16x16x32_bf16 v[68:71], v[140:143], v[208:211], v[68:71]
	v_mfma_f32_16x16x32_bf16 v[64:67], v[156:159], v[208:211], v[64:67]
	s_setprio 0
	s_barrier
; #define PG8_STAGE(bufoff, gbase, voff) do { _Pragma("unroll") for (int _i = 0; _i < 2; ++_i) \
;         __builtin_amdgcn_global_load_lds((const unsigned*)((const char*)(gbase) + (voff)[_i]), (LAS unsigned*)(lds + (bufoff) + ldsw + _i * 8192), 16, 0, 0); } while (0)
; #define PG8_LDA(dst, b, h) do { _Pragma("unroll") for (int m = 0; m < 4; ++m) _Pragma("unroll") for (int k = 0; k < 2; ++k) dst[m][k] = *(const LAS bf16x8*)(lds + PG8_SA(b, h) + aoff + m * 2048 + k * 1024); } while (0)
; #define PG8_MMA(ai, bj, At, Bt) do { __builtin_amdgcn_s_setprio(1); _Pragma("unroll") for (int m = 0; m < 4; ++m) _Pragma("unroll") for (int n = 0; n < 2; ++n) _Pragma("unroll") for (int k = 0; k < 2; ++k) \
;         acc[ai][bj][m][n] = __builtin_amdgcn_mfma_f32_16x16x32_bf16(Bt[n][k], At[m][k], acc[ai][bj][m][n], 0, 0, 0); __builtin_amdgcn_s_setprio(0); } while (0)
; #define PG8_WAIT_V(n) asm volatile("s_waitcnt vmcnt(" #n ")" ::: "memory")
; #define PG8_WAIT_L(n) asm volatile("s_waitcnt lgkmcnt(" #n ")" ::: "memory")
; #define PG8_BAR __builtin_amdgcn_s_barrier()
; #define PG8_SCHED __builtin_amdgcn_sched_barrier(0)
; template <class Epi, class Sched>
; __device__ __forceinline__ void gemm_phase(int wv, LAS unsigned char* lds, const Gemm g, const Sched& S, const Epi& E) {
;     ...
;             PG8_LDA(At, 1, 1); PG8_STAGE(PG8_SB(1, 0), b3, voffB); PG8_STAGE(PG8_SB(1, 1), b3 + hstepB, voffB); PG8_STAGE(PG8_SA(1, 0), a3, voffA);
;             PG8_WAIT_V(8); PG8_WAIT_L(0); PG8_BAR; PG8_MMA(1, 0, At, B0); PG8_MMA(1, 1, At, B1); PG8_BAR; PG8_SCHED;
;         }
;         if (wr == 0) PG8_BAR;
	s_add_i32 s28, s95, s36
	v_lshl_add_u64 v[212:213], v[212:213], 0, s[74:75]
	s_mov_b32 m0, s28
	ds_read_b128 v[160:163], v244 offset:49152
	ds_read_b128 v[164:167], v244 offset:50176
	ds_read_b128 v[168:171], v244 offset:51200
	ds_read_b128 v[172:175], v244 offset:52224
	ds_read_b128 v[176:179], v244 offset:53248
	ds_read_b128 v[180:183], v244 offset:54272
	ds_read_b128 v[184:187], v244 offset:55296
	ds_read_b128 v[208:211], v244 offset:56320
	global_load_lds_dwordx4 v[212:213], off
	s_add_i32 m0, s28, 0x2000
	s_add_u32 s26, s26, 0x4080
	v_lshl_add_u64 v[212:213], v[214:215], 0, s[74:75]
	s_addc_u32 s27, s27, 0
	s_add_i32 s28, s50, s36
	global_load_lds_dwordx4 v[212:213], off
	v_lshl_add_u64 v[212:213], s[26:27], 0, v[188:189]
	s_mov_b32 m0, s28
	s_nop 0
	global_load_lds_dwordx4 v[212:213], off
	v_lshl_add_u64 v[212:213], s[26:27], 0, v[198:199]
	s_add_i32 m0, s28, 0x2000
	s_nop 0
	global_load_lds_dwordx4 v[212:213], off
	v_lshl_add_u64 v[212:213], v[216:217], 0, s[74:75]
	s_mov_b32 m0, s41
	s_nop 0
	global_load_lds_dwordx4 v[212:213], off
	v_lshl_add_u64 v[212:213], v[218:219], 0, s[74:75]
	s_mov_b32 m0, s42
	s_nop 0
	global_load_lds_dwordx4 v[212:213], off
	s_waitcnt vmcnt(8)
	s_waitcnt lgkmcnt(0)
	s_barrier
	s_setprio 1
	s_waitcnt lgkmcnt(0)
	v_mfma_f32_16x16x32_bf16 v[60:63], v[112:115], v[160:163], v[60:63]
	v_mfma_f32_16x16x32_bf16 v[56:59], v[120:123], v[160:163], v[56:59]
	v_mfma_f32_16x16x32_bf16 v[44:47], v[112:115], v[168:171], v[44:47]
	v_mfma_f32_16x16x32_bf16 v[40:43], v[120:123], v[168:171], v[40:43]
	v_mfma_f32_16x16x32_bf16 v[28:31], v[112:115], v[176:179], v[28:31]
	v_mfma_f32_16x16x32_bf16 v[24:27], v[120:123], v[176:179], v[24:27]
	v_mfma_f32_16x16x32_bf16 v[12:15], v[112:115], v[184:187], v[12:15]
	v_mfma_f32_16x16x32_bf16 v[8:11], v[120:123], v[184:187], v[8:11]
	v_mfma_f32_16x16x32_bf16 v[60:63], v[116:119], v[164:167], v[60:63]
	v_mfma_f32_16x16x32_bf16 v[56:59], v[124:127], v[164:167], v[56:59]
	v_mfma_f32_16x16x32_bf16 v[44:47], v[116:119], v[172:175], v[44:47]
	v_mfma_f32_16x16x32_bf16 v[40:43], v[124:127], v[172:175], v[40:43]
	v_mfma_f32_16x16x32_bf16 v[28:31], v[116:119], v[180:183], v[28:31]
	v_mfma_f32_16x16x32_bf16 v[24:27], v[124:127], v[180:183], v[24:27]
	v_mfma_f32_16x16x32_bf16 v[12:15], v[116:119], v[208:211], v[12:15]
	v_mfma_f32_16x16x32_bf16 v[8:11], v[124:127], v[208:211], v[8:11]
	v_mfma_f32_16x16x32_bf16 v[52:55], v[128:131], v[160:163], v[52:55]
	v_mfma_f32_16x16x32_bf16 v[48:51], v[152:155], v[160:163], v[48:51]
	v_mfma_f32_16x16x32_bf16 v[36:39], v[128:131], v[168:171], v[36:39]
	v_mfma_f32_16x16x32_bf16 v[32:35], v[152:155], v[168:171], v[32:35]
	v_mfma_f32_16x16x32_bf16 v[20:23], v[128:131], v[176:179], v[20:23]
	v_mfma_f32_16x16x32_bf16 v[16:19], v[152:155], v[176:179], v[16:19]
	v_mfma_f32_16x16x32_bf16 v[4:7], v[128:131], v[184:187], v[4:7]
	v_mfma_f32_16x16x32_bf16 v[0:3], v[152:155], v[184:187], v[0:3]
	v_mfma_f32_16x16x32_bf16 v[52:55], v[140:143], v[164:167], v[52:55]
	v_mfma_f32_16x16x32_bf16 v[48:51], v[156:159], v[164:167], v[48:51]
	v_mfma_f32_16x16x32_bf16 v[36:39], v[140:143], v[172:175], v[36:39]
	v_mfma_f32_16x16x32_bf16 v[32:35], v[156:159], v[172:175], v[32:35]
	v_mfma_f32_16x16x32_bf16 v[20:23], v[140:143], v[180:183], v[20:23]
	v_mfma_f32_16x16x32_bf16 v[16:19], v[156:159], v[180:183], v[16:19]
	v_mfma_f32_16x16x32_bf16 v[4:7], v[140:143], v[208:211], v[4:7]
	v_mfma_f32_16x16x32_bf16 v[0:3], v[156:159], v[208:211], v[0:3]
	s_setprio 0
	s_barrier
	s_add_i32 s49, s49, 2
	s_add_u32 s24, s24, 0x100
	s_addc_u32 s25, s25, 0
	s_add_u32 s47, s47, 0x100
	s_addc_u32 s48, s48, 0
	s_cmp_gt_u32 s49, 13
	s_cbranch_scc0 .LBB0_893
	s_and_b64 vcc, exec, s[14:15]
	s_cbranch_vccz .LBB0_896
	s_barrier

; #define PG8_STAGE(bufoff, gbase, voff) do { _Pragma("unroll") for (int _i = 0; _i < 2; ++_i) \
;         __builtin_amdgcn_global_load_lds((const unsigned*)((const char*)(gbase) + (voff)[_i]), (LAS unsigned*)(lds + (bufoff) + ldsw + _i * 8192), 16, 0, 0); } while (0)
; #define PG8_LDA(dst, b, h) do { _Pragma("unroll") for (int m = 0; m < 4; ++m) _Pragma("unroll") for (int k = 0; k < 2; ++k) dst[m][k] = *(const LAS bf16x8*)(lds + PG8_SA(b, h) + aoff + m * 2048 + k * 1024); } while (0)
; #define PG8_LDB(dst, b, h) do { _Pragma("unroll") for (int n = 0; n < 2; ++n) _Pragma("unroll") for (int k = 0; k < 2; ++k) dst[n][k] = *(const LAS bf16x8*)(lds + PG8_SB(b, h) + boff + n * 2048 + k * 1024); } while (0)
; #define PG8_MMA(ai, bj, At, Bt) do { __builtin_amdgcn_s_setprio(1); _Pragma("unroll") for (int m = 0; m < 4; ++m) _Pragma("unroll") for (int n = 0; n < 2; ++n) _Pragma("unroll") for (int k = 0; k < 2; ++k) \
;         acc[ai][bj][m][n] = __builtin_amdgcn_mfma_f32_16x16x32_bf16(Bt[n][k], At[m][k], acc[ai][bj][m][n], 0, 0, 0); __builtin_amdgcn_s_setprio(0); } while (0)
; #define PG8_WAIT_V(n) asm volatile("s_waitcnt vmcnt(" #n ")" ::: "memory")
; #define PG8_WAIT_L(n) asm volatile("s_waitcnt lgkmcnt(" #n ")" ::: "memory")
; #define PG8_BAR __builtin_amdgcn_s_barrier()
; #define PG8_SCHED __builtin_amdgcn_sched_barrier(0)
; template <class Epi, class Sched>
; __device__ __forceinline__ void gemm_phase(int wv, LAS unsigned char* lds, const Gemm g, const Sched& S, const Epi& E) {
;     ...
;         for (int t = 0; t < nt; t += 2) {
;             const bool last = (t == nt - 2);
;             const char* a1 = cA + (size_t)(t + 1) * kstep;
;             const char* a2 = last ? nA : cA + (size_t)(t + 2) * kstep; const char* b2 = last ? nB : cB + (size_t)(t + 2) * kstep;
;             const char* a3 = a2 + kstep; const char* b3 = b2 + kstep;
;             PG8_LDB(B0, 0, 0); PG8_LDB(B1, 0, 1); PG8_SCHED; PG8_LDA(At, 0, 0); PG8_STAGE(PG8_SA(1, 1), a1 + hstep, voffA);
;             PG8_WAIT_V(8); PG8_WAIT_L(0); PG8_BAR; PG8_MMA(0, 0, At, B0); PG8_MMA(0, 1, At, B1); PG8_BAR; PG8_SCHED;
;             PG8_LDA(At, 0, 1); PG8_STAGE(PG8_SB(0, 0), b2, voffB); PG8_STAGE(PG8_SB(0, 1), b2 + hstepB, voffB); PG8_STAGE(PG8_SA(0, 0), a2, voffA);
;             PG8_WAIT_V(8); PG8_WAIT_L(0); PG8_BAR; PG8_MMA(1, 0, At, B0); PG8_MMA(1, 1, At, B1); PG8_BAR; PG8_SCHED;
.LBB0_978:
	s_add_u32 s20, s18, 0xfffc0080
	s_addc_u32 s21, s19, -1
	s_add_i32 s44, 0, 0x10000
	s_cmp_eq_u32 s43, 12
	s_cselect_b32 s23, s11, s21
	s_cselect_b32 s22, s39, s20
	s_cselect_b32 s21, s13, s42
	s_cselect_b32 s20, s40, s41
	s_add_i32 s46, 0, 0x14000
	v_add_u32_e32 v154, s44, v143
	v_add_u32_e32 v170, s46, v143
	ds_read_b128 v[138:141], v154
	ds_read_b128 v[146:149], v154 offset:1024
	ds_read_b128 v[150:153], v154 offset:2048
	ds_read_b128 v[154:157], v154 offset:3072
	ds_read_b128 v[158:161], v170
	ds_read_b128 v[162:165], v170 offset:1024
	ds_read_b128 v[166:169], v170 offset:2048
	ds_read_b128 v[170:173], v170 offset:3072
	v_lshl_add_u64 v[186:187], s[18:19], 0, v[134:135]
	s_add_i32 m0, s29, 0xc000
	ds_read_b128 v[174:177], v145
	ds_read_b128 v[178:181], v145 offset:1024
	ds_read_b128 v[182:185], v145 offset:2048
	ds_read_b128 v[198:201], v145 offset:3072
	ds_read_b128 v[202:205], v145 offset:4096
	ds_read_b128 v[206:209], v145 offset:5120
	ds_read_b128 v[210:213], v145 offset:6144
	ds_read_b128 v[214:217], v145 offset:7168
	global_load_lds_dwordx4 v[186:187], off
	v_lshl_add_u64 v[186:187], s[18:19], 0, v[136:137]
	s_add_i32 m0, s29, 0xe000
	s_nop 0
	global_load_lds_dwordx4 v[186:187], off
	s_waitcnt vmcnt(8)
	s_waitcnt lgkmcnt(0)
	s_barrier
	s_setprio 1
	s_waitcnt lgkmcnt(0)
	v_mfma_f32_16x16x32_bf16 v[124:127], v[138:141], v[174:177], v[124:127]
	v_mfma_f32_16x16x32_bf16 v[120:123], v[150:153], v[174:177], v[120:123]
	v_mfma_f32_16x16x32_bf16 v[108:111], v[138:141], v[182:185], v[108:111]
	v_mfma_f32_16x16x32_bf16 v[100:103], v[150:153], v[182:185], v[100:103]
	v_mfma_f32_16x16x32_bf16 v[92:95], v[138:141], v[202:205], v[92:95]
	v_mfma_f32_16x16x32_bf16 v[84:87], v[150:153], v[202:205], v[84:87]
	v_mfma_f32_16x16x32_bf16 v[76:79], v[138:141], v[210:213], v[76:79]
	v_mfma_f32_16x16x32_bf16 v[68:71], v[150:153], v[210:213], v[68:71]
	v_mfma_f32_16x16x32_bf16 v[124:127], v[146:149], v[178:181], v[124:127]
	v_mfma_f32_16x16x32_bf16 v[120:123], v[154:157], v[178:181], v[120:123]
	v_mfma_f32_16x16x32_bf16 v[108:111], v[146:149], v[198:201], v[108:111]
	v_mfma_f32_16x16x32_bf16 v[100:103], v[154:157], v[198:201], v[100:103]
	v_mfma_f32_16x16x32_bf16 v[92:95], v[146:149], v[206:209], v[92:95]
	v_mfma_f32_16x16x32_bf16 v[84:87], v[154:157], v[206:209], v[84:87]
	v_mfma_f32_16x16x32_bf16 v[76:79], v[146:149], v[214:217], v[76:79]
	v_mfma_f32_16x16x32_bf16 v[68:71], v[154:157], v[214:217], v[68:71]
	v_mfma_f32_16x16x32_bf16 v[116:119], v[158:161], v[174:177], v[116:119]
	v_mfma_f32_16x16x32_bf16 v[112:115], v[166:169], v[174:177], v[112:115]
	v_mfma_f32_16x16x32_bf16 v[104:107], v[158:161], v[182:185], v[104:107]
	v_mfma_f32_16x16x32_bf16 v[96:99], v[166:169], v[182:185], v[96:99]
	v_mfma_f32_16x16x32_bf16 v[88:91], v[158:161], v[202:205], v[88:91]
	v_mfma_f32_16x16x32_bf16 v[80:83], v[166:169], v[202:205], v[80:83]
	v_mfma_f32_16x16x32_bf16 v[72:75], v[158:161], v[210:213], v[72:75]
	v_mfma_f32_16x16x32_bf16 v[64:67], v[166:169], v[210:213], v[64:67]
	v_mfma_f32_16x16x32_bf16 v[116:119], v[162:165], v[178:181], v[116:119]
	v_mfma_f32_16x16x32_bf16 v[112:115], v[170:173], v[178:181], v[112:115]
	v_mfma_f32_16x16x32_bf16 v[104:107], v[162:165], v[198:201], v[104:107]
	v_mfma_f32_16x16x32_bf16 v[96:99], v[170:173], v[198:201], v[96:99]
	v_mfma_f32_16x16x32_bf16 v[88:91], v[162:165], v[206:209], v[88:91]
	v_mfma_f32_16x16x32_bf16 v[80:83], v[170:173], v[206:209], v[80:83]
	v_mfma_f32_16x16x32_bf16 v[72:75], v[162:165], v[214:217], v[72:75]
	v_mfma_f32_16x16x32_bf16 v[64:67], v[170:173], v[214:217], v[64:67]
	s_setprio 0
	s_barrier
	s_add_i32 s44, s44, s28
	v_lshl_add_u64 v[186:187], s[20:21], 0, v[188:189]
	s_mov_b32 m0, s44
	ds_read_b128 v[174:177], v145 offset:16384
	ds_read_b128 v[178:181], v145 offset:17408
	ds_read_b128 v[182:185], v145 offset:18432
	ds_read_b128 v[198:201], v145 offset:19456
	ds_read_b128 v[202:205], v145 offset:20480
	ds_read_b128 v[206:209], v145 offset:21504
	ds_read_b128 v[210:213], v145 offset:22528
	ds_read_b128 v[214:217], v145 offset:23552
	global_load_lds_dwordx4 v[186:187], off
	s_add_i32 m0, s44, 0x2000
	s_add_u32 s44, s20, 0x40000
	v_lshl_add_u64 v[218:219], s[20:21], 0, v[128:129]
	s_addc_u32 s45, s21, 0
	s_add_i32 s46, s46, s28
	global_load_lds_dwordx4 v[218:219], off
	v_lshl_add_u64 v[220:221], s[44:45], 0, v[188:189]
	s_mov_b32 m0, s46
	v_lshl_add_u64 v[222:223], s[22:23], 0, v[130:131]
	global_load_lds_dwordx4 v[220:221], off
	v_lshl_add_u64 v[220:221], s[44:45], 0, v[128:129]
	s_add_i32 m0, s46, 0x2000
	s_nop 0
	global_load_lds_dwordx4 v[220:221], off
	v_lshl_add_u64 v[220:221], s[22:23], 0, v[132:133]
	s_mov_b32 m0, s29
	s_nop 0
	global_load_lds_dwordx4 v[220:221], off
	s_mov_b32 m0, s30
	s_nop 0
	global_load_lds_dwordx4 v[222:223], off
	s_waitcnt vmcnt(8)
	s_waitcnt lgkmcnt(0)
	s_barrier
; #define PG8_STAGE(bufoff, gbase, voff) do { _Pragma("unroll") for (int _i = 0; _i < 2; ++_i) \
;         __builtin_amdgcn_global_load_lds((const unsigned*)((const char*)(gbase) + (voff)[_i]), (LAS unsigned*)(lds + (bufoff) + ldsw + _i * 8192), 16, 0, 0); } while (0)
; #define PG8_LDA(dst, b, h) do { _Pragma("unroll") for (int m = 0; m < 4; ++m) _Pragma("unroll") for (int k = 0; k < 2; ++k) dst[m][k] = *(const LAS bf16x8*)(lds + PG8_SA(b, h) + aoff + m * 2048 + k * 1024); } while (0)
; #define PG8_LDB(dst, b, h) do { _Pragma("unroll") for (int n = 0; n < 2; ++n) _Pragma("unroll") for (int k = 0; k < 2; ++k) dst[n][k] = *(const LAS bf16x8*)(lds + PG8_SB(b, h) + boff + n * 2048 + k * 1024); } while (0)
; #define PG8_MMA(ai, bj, At, Bt) do { __builtin_amdgcn_s_setprio(1); _Pragma("unroll") for (int m = 0; m < 4; ++m) _Pragma("unroll") for (int n = 0; n < 2; ++n) _Pragma("unroll") for (int k = 0; k < 2; ++k) \
;         acc[ai][bj][m][n] = __builtin_amdgcn_mfma_f32_16x16x32_bf16(Bt[n][k], At[m][k], acc[ai][bj][m][n], 0, 0, 0); __builtin_amdgcn_s_setprio(0); } while (0)
; #define PG8_WAIT_V(n) asm volatile("s_waitcnt vmcnt(" #n ")" ::: "memory")
; #define PG8_WAIT_L(n) asm volatile("s_waitcnt lgkmcnt(" #n ")" ::: "memory")
; #define PG8_BAR __builtin_amdgcn_s_barrier()
; #define PG8_SCHED __builtin_amdgcn_sched_barrier(0)
; template <class Epi, class Sched>
; __device__ __forceinline__ void gemm_phase(int wv, LAS unsigned char* lds, const Gemm g, const Sched& S, const Epi& E) {
;     ...
;             PG8_WAIT_V(8); PG8_WAIT_L(0); PG8_BAR; PG8_MMA(1, 0, At, B0); PG8_MMA(1, 1, At, B1); PG8_BAR; PG8_SCHED;
;             PG8_LDB(B0, 1, 0); PG8_LDB(B1, 1, 1); PG8_SCHED; PG8_LDA(At, 1, 0); PG8_STAGE(PG8_SA(0, 1), a2 + hstep, voffA);
;             PG8_WAIT_V(8); PG8_WAIT_L(0); PG8_BAR; PG8_MMA(0, 0, At, B0); PG8_MMA(0, 1, At, B1); PG8_BAR; PG8_SCHED;
	s_setprio 1
	s_waitcnt lgkmcnt(0)
	v_mfma_f32_16x16x32_bf16 v[60:63], v[138:141], v[174:177], v[60:63]
	v_mfma_f32_16x16x32_bf16 v[52:55], v[150:153], v[174:177], v[52:55]
	v_mfma_f32_16x16x32_bf16 v[44:47], v[138:141], v[182:185], v[44:47]
	v_mfma_f32_16x16x32_bf16 v[36:39], v[150:153], v[182:185], v[36:39]
	v_mfma_f32_16x16x32_bf16 v[28:31], v[138:141], v[202:205], v[28:31]
	v_mfma_f32_16x16x32_bf16 v[20:23], v[150:153], v[202:205], v[20:23]
	v_mfma_f32_16x16x32_bf16 v[12:15], v[138:141], v[210:213], v[12:15]
	v_mfma_f32_16x16x32_bf16 v[4:7], v[150:153], v[210:213], v[4:7]
	v_mfma_f32_16x16x32_bf16 v[60:63], v[146:149], v[178:181], v[60:63]
	v_mfma_f32_16x16x32_bf16 v[52:55], v[154:157], v[178:181], v[52:55]
	v_mfma_f32_16x16x32_bf16 v[44:47], v[146:149], v[198:201], v[44:47]
	v_mfma_f32_16x16x32_bf16 v[36:39], v[154:157], v[198:201], v[36:39]
	v_mfma_f32_16x16x32_bf16 v[28:31], v[146:149], v[206:209], v[28:31]
	v_mfma_f32_16x16x32_bf16 v[20:23], v[154:157], v[206:209], v[20:23]
	v_mfma_f32_16x16x32_bf16 v[12:15], v[146:149], v[214:217], v[12:15]
	v_mfma_f32_16x16x32_bf16 v[4:7], v[154:157], v[214:217], v[4:7]
	v_mfma_f32_16x16x32_bf16 v[56:59], v[158:161], v[174:177], v[56:59]
	v_mfma_f32_16x16x32_bf16 v[48:51], v[166:169], v[174:177], v[48:51]
	v_mfma_f32_16x16x32_bf16 v[40:43], v[158:161], v[182:185], v[40:43]
	v_mfma_f32_16x16x32_bf16 v[32:35], v[166:169], v[182:185], v[32:35]
	v_mfma_f32_16x16x32_bf16 v[24:27], v[158:161], v[202:205], v[24:27]
	v_mfma_f32_16x16x32_bf16 v[16:19], v[166:169], v[202:205], v[16:19]
	v_mfma_f32_16x16x32_bf16 v[8:11], v[158:161], v[210:213], v[8:11]
	v_mfma_f32_16x16x32_bf16 v[0:3], v[166:169], v[210:213], v[0:3]
	v_mfma_f32_16x16x32_bf16 v[56:59], v[162:165], v[178:181], v[56:59]
	v_mfma_f32_16x16x32_bf16 v[48:51], v[170:173], v[178:181], v[48:51]
	v_mfma_f32_16x16x32_bf16 v[40:43], v[162:165], v[198:201], v[40:43]
	v_mfma_f32_16x16x32_bf16 v[32:35], v[170:173], v[198:201], v[32:35]
	v_mfma_f32_16x16x32_bf16 v[24:27], v[162:165], v[206:209], v[24:27]
	v_mfma_f32_16x16x32_bf16 v[16:19], v[170:173], v[206:209], v[16:19]
	v_mfma_f32_16x16x32_bf16 v[8:11], v[162:165], v[214:217], v[8:11]
	v_mfma_f32_16x16x32_bf16 v[0:3], v[170:173], v[214:217], v[0:3]
	s_setprio 0
	s_barrier
	s_add_i32 s44, 0, 0x1c000
	v_add_u32_e32 v154, s95, v143
	v_add_u32_e32 v170, s44, v143
	ds_read_b128 v[138:141], v154
	ds_read_b128 v[146:149], v154 offset:1024
	ds_read_b128 v[150:153], v154 offset:2048
	ds_read_b128 v[154:157], v154 offset:3072
	ds_read_b128 v[158:161], v170
	ds_read_b128 v[162:165], v170 offset:1024
	ds_read_b128 v[166:169], v170 offset:2048
	ds_read_b128 v[170:173], v170 offset:3072
	s_add_u32 s22, s22, 0x40000
	s_addc_u32 s23, s23, 0
	s_mov_b32 m0, s31
	v_lshl_add_u64 v[228:229], s[22:23], 0, v[132:133]
	ds_read_b128 v[174:177], v145 offset:32768
	ds_read_b128 v[178:181], v145 offset:33792
	ds_read_b128 v[182:185], v145 offset:34816
	ds_read_b128 v[198:201], v145 offset:35840
	ds_read_b128 v[202:205], v145 offset:36864
	ds_read_b128 v[206:209], v145 offset:37888
	ds_read_b128 v[210:213], v145 offset:38912
	ds_read_b128 v[214:217], v145 offset:39936
	global_load_lds_dwordx4 v[228:229], off
	v_lshl_add_u64 v[228:229], s[22:23], 0, v[130:131]
	s_mov_b32 m0, s34
	s_nop 0
	global_load_lds_dwordx4 v[228:229], off
	s_waitcnt vmcnt(8)
	s_waitcnt lgkmcnt(0)
	s_barrier
	s_setprio 1
	s_waitcnt lgkmcnt(0)
	v_mfma_f32_16x16x32_bf16 v[124:127], v[138:141], v[174:177], v[124:127]
	v_mfma_f32_16x16x32_bf16 v[120:123], v[150:153], v[174:177], v[120:123]
	v_mfma_f32_16x16x32_bf16 v[108:111], v[138:141], v[182:185], v[108:111]
	v_mfma_f32_16x16x32_bf16 v[100:103], v[150:153], v[182:185], v[100:103]
	v_mfma_f32_16x16x32_bf16 v[92:95], v[138:141], v[202:205], v[92:95]
	v_mfma_f32_16x16x32_bf16 v[84:87], v[150:153], v[202:205], v[84:87]
	v_mfma_f32_16x16x32_bf16 v[76:79], v[138:141], v[210:213], v[76:79]
	v_mfma_f32_16x16x32_bf16 v[68:71], v[150:153], v[210:213], v[68:71]
	v_mfma_f32_16x16x32_bf16 v[124:127], v[146:149], v[178:181], v[124:127]
	v_mfma_f32_16x16x32_bf16 v[120:123], v[154:157], v[178:181], v[120:123]
	v_mfma_f32_16x16x32_bf16 v[108:111], v[146:149], v[198:201], v[108:111]
	v_mfma_f32_16x16x32_bf16 v[100:103], v[154:157], v[198:201], v[100:103]
	v_mfma_f32_16x16x32_bf16 v[92:95], v[146:149], v[206:209], v[92:95]
	v_mfma_f32_16x16x32_bf16 v[84:87], v[154:157], v[206:209], v[84:87]
	v_mfma_f32_16x16x32_bf16 v[76:79], v[146:149], v[214:217], v[76:79]
	v_mfma_f32_16x16x32_bf16 v[68:71], v[154:157], v[214:217], v[68:71]
	v_mfma_f32_16x16x32_bf16 v[116:119], v[158:161], v[174:177], v[116:119]
	v_mfma_f32_16x16x32_bf16 v[112:115], v[166:169], v[174:177], v[112:115]
	v_mfma_f32_16x16x32_bf16 v[104:107], v[158:161], v[182:185], v[104:107]
	v_mfma_f32_16x16x32_bf16 v[96:99], v[166:169], v[182:185], v[96:99]
	v_mfma_f32_16x16x32_bf16 v[88:91], v[158:161], v[202:205], v[88:91]
	v_mfma_f32_16x16x32_bf16 v[80:83], v[166:169], v[202:205], v[80:83]
	v_mfma_f32_16x16x32_bf16 v[72:75], v[158:161], v[210:213], v[72:75]
	v_mfma_f32_16x16x32_bf16 v[64:67], v[166:169], v[210:213], v[64:67]
	v_mfma_f32_16x16x32_bf16 v[116:119], v[162:165], v[178:181], v[116:119]
	v_mfma_f32_16x16x32_bf16 v[112:115], v[170:173], v[178:181], v[112:115]
	v_mfma_f32_16x16x32_bf16 v[104:107], v[162:165], v[198:201], v[104:107]
	v_mfma_f32_16x16x32_bf16 v[96:99], v[170:173], v[198:201], v[96:99]
	v_mfma_f32_16x16x32_bf16 v[88:91], v[162:165], v[206:209], v[88:91]
	v_mfma_f32_16x16x32_bf16 v[80:83], v[170:173], v[206:209], v[80:83]
	v_mfma_f32_16x16x32_bf16 v[72:75], v[162:165], v[214:217], v[72:75]
	v_mfma_f32_16x16x32_bf16 v[64:67], v[170:173], v[214:217], v[64:67]
	s_setprio 0
	s_barrier
; #define PG8_STAGE(bufoff, gbase, voff) do { _Pragma("unroll") for (int _i = 0; _i < 2; ++_i) \
;         __builtin_amdgcn_global_load_lds((const unsigned*)((const char*)(gbase) + (voff)[_i]), (LAS unsigned*)(lds + (bufoff) + ldsw + _i * 8192), 16, 0, 0); } while (0)
; #define PG8_LDA(dst, b, h) do { _Pragma("unroll") for (int m = 0; m < 4; ++m) _Pragma("unroll") for (int k = 0; k < 2; ++k) dst[m][k] = *(const LAS bf16x8*)(lds + PG8_SA(b, h) + aoff + m * 2048 + k * 1024); } while (0)
; #define PG8_MMA(ai, bj, At, Bt) do { __builtin_amdgcn_s_setprio(1); _Pragma("unroll") for (int m = 0; m < 4; ++m) _Pragma("unroll") for (int n = 0; n < 2; ++n) _Pragma("unroll") for (int k = 0; k < 2; ++k) \
;         acc[ai][bj][m][n] = __builtin_amdgcn_mfma_f32_16x16x32_bf16(Bt[n][k], At[m][k], acc[ai][bj][m][n], 0, 0, 0); __builtin_amdgcn_s_setprio(0); } while (0)
; #define PG8_WAIT_V(n) asm volatile("s_waitcnt vmcnt(" #n ")" ::: "memory")
; #define PG8_WAIT_L(n) asm volatile("s_waitcnt lgkmcnt(" #n ")" ::: "memory")
; #define PG8_BAR __builtin_amdgcn_s_barrier()
; #define PG8_SCHED __builtin_amdgcn_sched_barrier(0)
; template <class Epi, class Sched>
; __device__ __forceinline__ void gemm_phase(int wv, LAS unsigned char* lds, const Gemm g, const Sched& S, const Epi& E) {
;     ...
;             PG8_LDA(At, 1, 1); PG8_STAGE(PG8_SB(1, 0), b3, voffB); PG8_STAGE(PG8_SB(1, 1), b3 + hstepB, voffB); PG8_STAGE(PG8_SA(1, 0), a3, voffA);
;             PG8_WAIT_V(8); PG8_WAIT_L(0); PG8_BAR; PG8_MMA(1, 0, At, B0); PG8_MMA(1, 1, At, B1); PG8_BAR; PG8_SCHED;
;         }
;         if (wr == 0) PG8_BAR;
	s_add_i32 s22, s95, s28
	v_lshl_add_u64 v[186:187], v[186:187], 0, s[74:75]
	s_mov_b32 m0, s22
	ds_read_b128 v[174:177], v145 offset:49152
	ds_read_b128 v[178:181], v145 offset:50176
	ds_read_b128 v[182:185], v145 offset:51200
	ds_read_b128 v[198:201], v145 offset:52224
	ds_read_b128 v[202:205], v145 offset:53248
	ds_read_b128 v[206:209], v145 offset:54272
	ds_read_b128 v[210:213], v145 offset:55296
	ds_read_b128 v[214:217], v145 offset:56320
	global_load_lds_dwordx4 v[186:187], off
	s_add_i32 m0, s22, 0x2000
	s_add_u32 s20, s20, 0x40080
	v_lshl_add_u64 v[186:187], v[218:219], 0, s[74:75]
	s_addc_u32 s21, s21, 0
	s_add_i32 s22, s44, s28
	global_load_lds_dwordx4 v[186:187], off
	v_lshl_add_u64 v[186:187], s[20:21], 0, v[188:189]
	s_mov_b32 m0, s22
	s_nop 0
	global_load_lds_dwordx4 v[186:187], off
	v_lshl_add_u64 v[186:187], s[20:21], 0, v[128:129]
	s_add_i32 m0, s22, 0x2000
	s_nop 0
	global_load_lds_dwordx4 v[186:187], off
	v_lshl_add_u64 v[186:187], v[220:221], 0, s[74:75]
	s_mov_b32 m0, s35
	s_nop 0
	global_load_lds_dwordx4 v[186:187], off
	v_lshl_add_u64 v[186:187], v[222:223], 0, s[74:75]
	s_mov_b32 m0, s36
	s_nop 0
	global_load_lds_dwordx4 v[186:187], off
	s_waitcnt vmcnt(8)
	s_waitcnt lgkmcnt(0)
	s_barrier
	s_setprio 1
	s_waitcnt lgkmcnt(0)
	v_mfma_f32_16x16x32_bf16 v[60:63], v[138:141], v[174:177], v[60:63]
	v_mfma_f32_16x16x32_bf16 v[52:55], v[150:153], v[174:177], v[52:55]
	v_mfma_f32_16x16x32_bf16 v[44:47], v[138:141], v[182:185], v[44:47]
	v_mfma_f32_16x16x32_bf16 v[36:39], v[150:153], v[182:185], v[36:39]
	v_mfma_f32_16x16x32_bf16 v[28:31], v[138:141], v[202:205], v[28:31]
	v_mfma_f32_16x16x32_bf16 v[20:23], v[150:153], v[202:205], v[20:23]
	v_mfma_f32_16x16x32_bf16 v[12:15], v[138:141], v[210:213], v[12:15]
	v_mfma_f32_16x16x32_bf16 v[4:7], v[150:153], v[210:213], v[4:7]
	v_mfma_f32_16x16x32_bf16 v[60:63], v[146:149], v[178:181], v[60:63]
	v_mfma_f32_16x16x32_bf16 v[52:55], v[154:157], v[178:181], v[52:55]
	v_mfma_f32_16x16x32_bf16 v[44:47], v[146:149], v[198:201], v[44:47]
	v_mfma_f32_16x16x32_bf16 v[36:39], v[154:157], v[198:201], v[36:39]
	v_mfma_f32_16x16x32_bf16 v[28:31], v[146:149], v[206:209], v[28:31]
	v_mfma_f32_16x16x32_bf16 v[20:23], v[154:157], v[206:209], v[20:23]
	v_mfma_f32_16x16x32_bf16 v[12:15], v[146:149], v[214:217], v[12:15]
	v_mfma_f32_16x16x32_bf16 v[4:7], v[154:157], v[214:217], v[4:7]
	v_mfma_f32_16x16x32_bf16 v[56:59], v[158:161], v[174:177], v[56:59]
	v_mfma_f32_16x16x32_bf16 v[48:51], v[166:169], v[174:177], v[48:51]
	v_mfma_f32_16x16x32_bf16 v[40:43], v[158:161], v[182:185], v[40:43]
	v_mfma_f32_16x16x32_bf16 v[32:35], v[166:169], v[182:185], v[32:35]
	v_mfma_f32_16x16x32_bf16 v[24:27], v[158:161], v[202:205], v[24:27]
	v_mfma_f32_16x16x32_bf16 v[16:19], v[166:169], v[202:205], v[16:19]
	v_mfma_f32_16x16x32_bf16 v[8:11], v[158:161], v[210:213], v[8:11]
	v_mfma_f32_16x16x32_bf16 v[0:3], v[166:169], v[210:213], v[0:3]
	v_mfma_f32_16x16x32_bf16 v[56:59], v[162:165], v[178:181], v[56:59]
	v_mfma_f32_16x16x32_bf16 v[48:51], v[170:173], v[178:181], v[48:51]
	v_mfma_f32_16x16x32_bf16 v[40:43], v[162:165], v[198:201], v[40:43]
	v_mfma_f32_16x16x32_bf16 v[32:35], v[170:173], v[198:201], v[32:35]
	v_mfma_f32_16x16x32_bf16 v[24:27], v[162:165], v[206:209], v[24:27]
	v_mfma_f32_16x16x32_bf16 v[16:19], v[170:173], v[206:209], v[16:19]
	v_mfma_f32_16x16x32_bf16 v[8:11], v[162:165], v[214:217], v[8:11]
	v_mfma_f32_16x16x32_bf16 v[0:3], v[170:173], v[214:217], v[0:3]
	s_setprio 0
	s_barrier
	s_add_i32 s43, s43, 2
	s_add_u32 s18, s18, 0x100
	s_addc_u32 s19, s19, 0
	s_add_u32 s41, s41, 0x100
	s_addc_u32 s42, s42, 0
	s_cmp_gt_u32 s43, 13
	s_cbranch_scc0 .LBB0_978
	s_and_b64 vcc, exec, s[8:9]
	s_cbranch_vccz .LBB0_981
	s_barrier

; #define PG8_STAGE(bufoff, gbase, voff) do { _Pragma("unroll") for (int _i = 0; _i < 2; ++_i) \
;         __builtin_amdgcn_global_load_lds((const unsigned*)((const char*)(gbase) + (voff)[_i]), (LAS unsigned*)(lds + (bufoff) + ldsw + _i * 8192), 16, 0, 0); } while (0)
; #define PG8_LDA(dst, b, h) do { _Pragma("unroll") for (int m = 0; m < 4; ++m) _Pragma("unroll") for (int k = 0; k < 2; ++k) dst[m][k] = *(const LAS bf16x8*)(lds + PG8_SA(b, h) + aoff + m * 2048 + k * 1024); } while (0)
; #define PG8_LDB(dst, b, h) do { _Pragma("unroll") for (int n = 0; n < 2; ++n) _Pragma("unroll") for (int k = 0; k < 2; ++k) dst[n][k] = *(const LAS bf16x8*)(lds + PG8_SB(b, h) + boff + n * 2048 + k * 1024); } while (0)
; #define PG8_MMA(ai, bj, At, Bt) do { __builtin_amdgcn_s_setprio(1); _Pragma("unroll") for (int m = 0; m < 4; ++m) _Pragma("unroll") for (int n = 0; n < 2; ++n) _Pragma("unroll") for (int k = 0; k < 2; ++k) \
;         acc[ai][bj][m][n] = __builtin_amdgcn_mfma_f32_16x16x32_bf16(Bt[n][k], At[m][k], acc[ai][bj][m][n], 0, 0, 0); __builtin_amdgcn_s_setprio(0); } while (0)
; #define PG8_WAIT_V(n) asm volatile("s_waitcnt vmcnt(" #n ")" ::: "memory")
; #define PG8_WAIT_L(n) asm volatile("s_waitcnt lgkmcnt(" #n ")" ::: "memory")
; #define PG8_BAR __builtin_amdgcn_s_barrier()
; #define PG8_SCHED __builtin_amdgcn_sched_barrier(0)
; template <class Epi, class Sched>
; __device__ __forceinline__ void gemm_phase(int wv, LAS unsigned char* lds, const Gemm g, const Sched& S, const Epi& E) {
;     ...
;         for (int t = 0; t < nt; t += 2) {
;             const bool last = (t == nt - 2);
;             const char* a1 = cA + (size_t)(t + 1) * kstep;
;             const char* a2 = last ? nA : cA + (size_t)(t + 2) * kstep; const char* b2 = last ? nB : cB + (size_t)(t + 2) * kstep;
;             const char* a3 = a2 + kstep; const char* b3 = b2 + kstep;
;             PG8_LDB(B0, 0, 0); PG8_LDB(B1, 0, 1); PG8_SCHED; PG8_LDA(At, 0, 0); PG8_STAGE(PG8_SA(1, 1), a1 + hstep, voffA);
;             PG8_WAIT_V(8); PG8_WAIT_L(0); PG8_BAR; PG8_MMA(0, 0, At, B0); PG8_MMA(0, 1, At, B1); PG8_BAR; PG8_SCHED;
;             PG8_LDA(At, 0, 1); PG8_STAGE(PG8_SB(0, 0), b2, voffB); PG8_STAGE(PG8_SB(0, 1), b2 + hstepB, voffB); PG8_STAGE(PG8_SA(0, 0), a2, voffA);
;             PG8_WAIT_V(8); PG8_WAIT_L(0); PG8_BAR; PG8_MMA(1, 0, At, B0); PG8_MMA(1, 1, At, B1); PG8_BAR; PG8_SCHED;
.LBB0_1055:
	s_add_u32 s4, s22, 0x100
	s_addc_u32 s5, s23, 0
	s_add_i32 s48, 0, 0x10000
	s_cmp_eq_u32 s47, 40
	s_cselect_b32 s27, s19, s5
	s_cselect_b32 s26, s18, s4
	s_cselect_b32 s25, s21, s46
	s_cselect_b32 s24, s20, s45
	s_add_i32 s49, 0, 0x14000
	v_add_u32_e32 v136, s48, v213
	v_add_u32_e32 v156, s49, v213
	ds_read_b128 v[96:99], v136
	ds_read_b128 v[100:103], v136 offset:1024
	ds_read_b128 v[104:107], v136 offset:2048
	ds_read_b128 v[136:139], v136 offset:3072
	ds_read_b128 v[140:143], v156
	ds_read_b128 v[144:147], v156 offset:1024
	ds_read_b128 v[152:155], v156 offset:2048
	ds_read_b128 v[156:159], v156 offset:3072
	v_lshl_add_u64 v[186:187], s[22:23], 0, v[182:183]
	s_add_i32 m0, s35, 0xc000
	ds_read_b128 v[160:163], v217
	ds_read_b128 v[164:167], v217 offset:1024
	ds_read_b128 v[168:171], v217 offset:2048
	ds_read_b128 v[172:175], v217 offset:3072
	ds_read_b128 v[198:201], v217 offset:4096
	ds_read_b128 v[202:205], v217 offset:5120
	ds_read_b128 v[206:209], v217 offset:6144
	ds_read_b128 v[218:221], v217 offset:7168
	global_load_lds_dwordx4 v[186:187], off
	v_lshl_add_u64 v[186:187], s[22:23], 0, v[184:185]
	s_add_i32 m0, s35, 0xe000
	s_nop 0
	global_load_lds_dwordx4 v[186:187], off
	s_waitcnt vmcnt(8)
	s_waitcnt lgkmcnt(0)
	s_barrier
	s_setprio 1
	s_waitcnt lgkmcnt(0)
	v_mfma_f32_16x16x32_bf16 v[148:151], v[96:99], v[160:163], v[148:151]
	v_mfma_f32_16x16x32_bf16 v[124:127], v[104:107], v[160:163], v[124:127]
	v_mfma_f32_16x16x32_bf16 v[132:135], v[96:99], v[168:171], v[132:135]
	v_mfma_f32_16x16x32_bf16 v[128:131], v[104:107], v[168:171], v[128:131]
	v_mfma_f32_16x16x32_bf16 v[92:95], v[96:99], v[198:201], v[92:95]
	v_mfma_f32_16x16x32_bf16 v[88:91], v[104:107], v[198:201], v[88:91]
	v_mfma_f32_16x16x32_bf16 v[76:79], v[96:99], v[206:209], v[76:79]
	v_mfma_f32_16x16x32_bf16 v[72:75], v[104:107], v[206:209], v[72:75]
	v_mfma_f32_16x16x32_bf16 v[148:151], v[100:103], v[164:167], v[148:151]
	v_mfma_f32_16x16x32_bf16 v[124:127], v[136:139], v[164:167], v[124:127]
	v_mfma_f32_16x16x32_bf16 v[132:135], v[100:103], v[172:175], v[132:135]
	v_mfma_f32_16x16x32_bf16 v[128:131], v[136:139], v[172:175], v[128:131]
	v_mfma_f32_16x16x32_bf16 v[92:95], v[100:103], v[202:205], v[92:95]
	v_mfma_f32_16x16x32_bf16 v[88:91], v[136:139], v[202:205], v[88:91]
	v_mfma_f32_16x16x32_bf16 v[76:79], v[100:103], v[218:221], v[76:79]
	v_mfma_f32_16x16x32_bf16 v[72:75], v[136:139], v[218:221], v[72:75]
	v_mfma_f32_16x16x32_bf16 v[116:119], v[140:143], v[160:163], v[116:119]
	v_mfma_f32_16x16x32_bf16 v[108:111], v[152:155], v[160:163], v[108:111]
	v_mfma_f32_16x16x32_bf16 v[120:123], v[140:143], v[168:171], v[120:123]
	v_mfma_f32_16x16x32_bf16 v[112:115], v[152:155], v[168:171], v[112:115]
	v_mfma_f32_16x16x32_bf16 v[84:87], v[140:143], v[198:201], v[84:87]
	v_mfma_f32_16x16x32_bf16 v[80:83], v[152:155], v[198:201], v[80:83]
	v_mfma_f32_16x16x32_bf16 v[68:71], v[140:143], v[206:209], v[68:71]
	v_mfma_f32_16x16x32_bf16 v[64:67], v[152:155], v[206:209], v[64:67]
	v_mfma_f32_16x16x32_bf16 v[116:119], v[144:147], v[164:167], v[116:119]
	v_mfma_f32_16x16x32_bf16 v[108:111], v[156:159], v[164:167], v[108:111]
	v_mfma_f32_16x16x32_bf16 v[120:123], v[144:147], v[172:175], v[120:123]
	v_mfma_f32_16x16x32_bf16 v[112:115], v[156:159], v[172:175], v[112:115]
	v_mfma_f32_16x16x32_bf16 v[84:87], v[144:147], v[202:205], v[84:87]
	v_mfma_f32_16x16x32_bf16 v[80:83], v[156:159], v[202:205], v[80:83]
	v_mfma_f32_16x16x32_bf16 v[68:71], v[144:147], v[218:221], v[68:71]
	v_mfma_f32_16x16x32_bf16 v[64:67], v[156:159], v[218:221], v[64:67]
	s_setprio 0
	s_barrier
	s_add_i32 s22, s48, s34
	v_lshl_add_u64 v[186:187], s[24:25], 0, v[188:189]
	s_mov_b32 m0, s22
	ds_read_b128 v[160:163], v217 offset:16384
	ds_read_b128 v[164:167], v217 offset:17408
	ds_read_b128 v[168:171], v217 offset:18432
	ds_read_b128 v[172:175], v217 offset:19456
	ds_read_b128 v[198:201], v217 offset:20480
	ds_read_b128 v[202:205], v217 offset:21504
	ds_read_b128 v[206:209], v217 offset:22528
	ds_read_b128 v[218:221], v217 offset:23552
	global_load_lds_dwordx4 v[186:187], off
	s_add_i32 m0, s22, 0x2000
	s_add_u32 s22, s24, 0xb000
	v_lshl_add_u64 v[210:211], s[24:25], 0, v[176:177]
	s_addc_u32 s23, s25, 0
	s_add_i32 s48, s49, s34
	global_load_lds_dwordx4 v[210:211], off
	v_lshl_add_u64 v[222:223], s[22:23], 0, v[188:189]
	s_mov_b32 m0, s48
	v_lshl_add_u64 v[228:229], s[26:27], 0, v[178:179]
	global_load_lds_dwordx4 v[222:223], off
	v_lshl_add_u64 v[222:223], s[22:23], 0, v[176:177]
	s_add_i32 m0, s48, 0x2000
	s_nop 0
	global_load_lds_dwordx4 v[222:223], off
	v_lshl_add_u64 v[222:223], s[26:27], 0, v[180:181]
	s_mov_b32 m0, s35
	s_nop 0
	global_load_lds_dwordx4 v[222:223], off
	s_mov_b32 m0, s36
	s_nop 0
	global_load_lds_dwordx4 v[228:229], off
	s_waitcnt vmcnt(8)
	s_waitcnt lgkmcnt(0)
	s_barrier
; #define PG8_STAGE(bufoff, gbase, voff) do { _Pragma("unroll") for (int _i = 0; _i < 2; ++_i) \
;         __builtin_amdgcn_global_load_lds((const unsigned*)((const char*)(gbase) + (voff)[_i]), (LAS unsigned*)(lds + (bufoff) + ldsw + _i * 8192), 16, 0, 0); } while (0)
; #define PG8_LDA(dst, b, h) do { _Pragma("unroll") for (int m = 0; m < 4; ++m) _Pragma("unroll") for (int k = 0; k < 2; ++k) dst[m][k] = *(const LAS bf16x8*)(lds + PG8_SA(b, h) + aoff + m * 2048 + k * 1024); } while (0)
; #define PG8_LDB(dst, b, h) do { _Pragma("unroll") for (int n = 0; n < 2; ++n) _Pragma("unroll") for (int k = 0; k < 2; ++k) dst[n][k] = *(const LAS bf16x8*)(lds + PG8_SB(b, h) + boff + n * 2048 + k * 1024); } while (0)
; #define PG8_MMA(ai, bj, At, Bt) do { __builtin_amdgcn_s_setprio(1); _Pragma("unroll") for (int m = 0; m < 4; ++m) _Pragma("unroll") for (int n = 0; n < 2; ++n) _Pragma("unroll") for (int k = 0; k < 2; ++k) \
;         acc[ai][bj][m][n] = __builtin_amdgcn_mfma_f32_16x16x32_bf16(Bt[n][k], At[m][k], acc[ai][bj][m][n], 0, 0, 0); __builtin_amdgcn_s_setprio(0); } while (0)
; #define PG8_WAIT_V(n) asm volatile("s_waitcnt vmcnt(" #n ")" ::: "memory")
; #define PG8_WAIT_L(n) asm volatile("s_waitcnt lgkmcnt(" #n ")" ::: "memory")
; #define PG8_BAR __builtin_amdgcn_s_barrier()
; #define PG8_SCHED __builtin_amdgcn_sched_barrier(0)
; template <class Epi, class Sched>
; __device__ __forceinline__ void gemm_phase(int wv, LAS unsigned char* lds, const Gemm g, const Sched& S, const Epi& E) {
;     ...
;             PG8_WAIT_V(8); PG8_WAIT_L(0); PG8_BAR; PG8_MMA(1, 0, At, B0); PG8_MMA(1, 1, At, B1); PG8_BAR; PG8_SCHED;
;             PG8_LDB(B0, 1, 0); PG8_LDB(B1, 1, 1); PG8_SCHED; PG8_LDA(At, 1, 0); PG8_STAGE(PG8_SA(0, 1), a2 + hstep, voffA);
;             PG8_WAIT_V(8); PG8_WAIT_L(0); PG8_BAR; PG8_MMA(0, 0, At, B0); PG8_MMA(0, 1, At, B1); PG8_BAR; PG8_SCHED;
	s_setprio 1
	s_waitcnt lgkmcnt(0)
	v_mfma_f32_16x16x32_bf16 v[60:63], v[96:99], v[160:163], v[60:63]
	v_mfma_f32_16x16x32_bf16 v[56:59], v[104:107], v[160:163], v[56:59]
	v_mfma_f32_16x16x32_bf16 v[44:47], v[96:99], v[168:171], v[44:47]
	v_mfma_f32_16x16x32_bf16 v[40:43], v[104:107], v[168:171], v[40:43]
	v_mfma_f32_16x16x32_bf16 v[28:31], v[96:99], v[198:201], v[28:31]
	v_mfma_f32_16x16x32_bf16 v[24:27], v[104:107], v[198:201], v[24:27]
	v_mfma_f32_16x16x32_bf16 v[12:15], v[96:99], v[206:209], v[12:15]
	v_mfma_f32_16x16x32_bf16 v[8:11], v[104:107], v[206:209], v[8:11]
	v_mfma_f32_16x16x32_bf16 v[60:63], v[100:103], v[164:167], v[60:63]
	v_mfma_f32_16x16x32_bf16 v[56:59], v[136:139], v[164:167], v[56:59]
	v_mfma_f32_16x16x32_bf16 v[44:47], v[100:103], v[172:175], v[44:47]
	v_mfma_f32_16x16x32_bf16 v[40:43], v[136:139], v[172:175], v[40:43]
	v_mfma_f32_16x16x32_bf16 v[28:31], v[100:103], v[202:205], v[28:31]
	v_mfma_f32_16x16x32_bf16 v[24:27], v[136:139], v[202:205], v[24:27]
	v_mfma_f32_16x16x32_bf16 v[12:15], v[100:103], v[218:221], v[12:15]
	v_mfma_f32_16x16x32_bf16 v[8:11], v[136:139], v[218:221], v[8:11]
	v_mfma_f32_16x16x32_bf16 v[52:55], v[140:143], v[160:163], v[52:55]
	v_mfma_f32_16x16x32_bf16 v[48:51], v[152:155], v[160:163], v[48:51]
	v_mfma_f32_16x16x32_bf16 v[36:39], v[140:143], v[168:171], v[36:39]
	v_mfma_f32_16x16x32_bf16 v[32:35], v[152:155], v[168:171], v[32:35]
	v_mfma_f32_16x16x32_bf16 v[20:23], v[140:143], v[198:201], v[20:23]
	v_mfma_f32_16x16x32_bf16 v[16:19], v[152:155], v[198:201], v[16:19]
	v_mfma_f32_16x16x32_bf16 v[4:7], v[140:143], v[206:209], v[4:7]
	v_mfma_f32_16x16x32_bf16 v[0:3], v[152:155], v[206:209], v[0:3]
	v_mfma_f32_16x16x32_bf16 v[52:55], v[144:147], v[164:167], v[52:55]
	v_mfma_f32_16x16x32_bf16 v[48:51], v[156:159], v[164:167], v[48:51]
	v_mfma_f32_16x16x32_bf16 v[36:39], v[144:147], v[172:175], v[36:39]
	v_mfma_f32_16x16x32_bf16 v[32:35], v[156:159], v[172:175], v[32:35]
	v_mfma_f32_16x16x32_bf16 v[20:23], v[144:147], v[202:205], v[20:23]
	v_mfma_f32_16x16x32_bf16 v[16:19], v[156:159], v[202:205], v[16:19]
	v_mfma_f32_16x16x32_bf16 v[4:7], v[144:147], v[218:221], v[4:7]
	v_mfma_f32_16x16x32_bf16 v[0:3], v[156:159], v[218:221], v[0:3]
	s_setprio 0
	s_barrier
	s_add_i32 s48, 0, 0x1c000
	v_add_u32_e32 v136, s95, v213
	v_add_u32_e32 v156, s48, v213
	ds_read_b128 v[96:99], v136
	ds_read_b128 v[100:103], v136 offset:1024
	ds_read_b128 v[104:107], v136 offset:2048
	ds_read_b128 v[136:139], v136 offset:3072
	ds_read_b128 v[140:143], v156
	ds_read_b128 v[144:147], v156 offset:1024
	ds_read_b128 v[152:155], v156 offset:2048
	ds_read_b128 v[156:159], v156 offset:3072
	s_add_u32 s22, s26, 0xb0000
	s_addc_u32 s23, s27, 0
	s_mov_b32 m0, s37
	v_lshl_add_u64 v[230:231], s[22:23], 0, v[180:181]
	ds_read_b128 v[160:163], v217 offset:32768
	ds_read_b128 v[164:167], v217 offset:33792
	ds_read_b128 v[168:171], v217 offset:34816
	ds_read_b128 v[172:175], v217 offset:35840
	ds_read_b128 v[198:201], v217 offset:36864
	ds_read_b128 v[202:205], v217 offset:37888
	ds_read_b128 v[206:209], v217 offset:38912
	ds_read_b128 v[218:221], v217 offset:39936
	global_load_lds_dwordx4 v[230:231], off
	v_lshl_add_u64 v[230:231], s[22:23], 0, v[178:179]
	s_mov_b32 m0, s38
	s_nop 0
	global_load_lds_dwordx4 v[230:231], off
	s_waitcnt vmcnt(8)
	s_waitcnt lgkmcnt(0)
	s_barrier
	s_setprio 1
	s_waitcnt lgkmcnt(0)
	v_mfma_f32_16x16x32_bf16 v[148:151], v[96:99], v[160:163], v[148:151]
	v_mfma_f32_16x16x32_bf16 v[124:127], v[104:107], v[160:163], v[124:127]
	v_mfma_f32_16x16x32_bf16 v[132:135], v[96:99], v[168:171], v[132:135]
	v_mfma_f32_16x16x32_bf16 v[128:131], v[104:107], v[168:171], v[128:131]
	v_mfma_f32_16x16x32_bf16 v[92:95], v[96:99], v[198:201], v[92:95]
	v_mfma_f32_16x16x32_bf16 v[88:91], v[104:107], v[198:201], v[88:91]
	v_mfma_f32_16x16x32_bf16 v[76:79], v[96:99], v[206:209], v[76:79]
	v_mfma_f32_16x16x32_bf16 v[72:75], v[104:107], v[206:209], v[72:75]
	v_mfma_f32_16x16x32_bf16 v[148:151], v[100:103], v[164:167], v[148:151]
	v_mfma_f32_16x16x32_bf16 v[124:127], v[136:139], v[164:167], v[124:127]
	v_mfma_f32_16x16x32_bf16 v[132:135], v[100:103], v[172:175], v[132:135]
	v_mfma_f32_16x16x32_bf16 v[128:131], v[136:139], v[172:175], v[128:131]
	v_mfma_f32_16x16x32_bf16 v[92:95], v[100:103], v[202:205], v[92:95]
	v_mfma_f32_16x16x32_bf16 v[88:91], v[136:139], v[202:205], v[88:91]
	v_mfma_f32_16x16x32_bf16 v[76:79], v[100:103], v[218:221], v[76:79]
	v_mfma_f32_16x16x32_bf16 v[72:75], v[136:139], v[218:221], v[72:75]
	v_mfma_f32_16x16x32_bf16 v[116:119], v[140:143], v[160:163], v[116:119]
	v_mfma_f32_16x16x32_bf16 v[108:111], v[152:155], v[160:163], v[108:111]
	v_mfma_f32_16x16x32_bf16 v[120:123], v[140:143], v[168:171], v[120:123]
	v_mfma_f32_16x16x32_bf16 v[112:115], v[152:155], v[168:171], v[112:115]
	v_mfma_f32_16x16x32_bf16 v[84:87], v[140:143], v[198:201], v[84:87]
	v_mfma_f32_16x16x32_bf16 v[80:83], v[152:155], v[198:201], v[80:83]
	v_mfma_f32_16x16x32_bf16 v[68:71], v[140:143], v[206:209], v[68:71]
	v_mfma_f32_16x16x32_bf16 v[64:67], v[152:155], v[206:209], v[64:67]
	v_mfma_f32_16x16x32_bf16 v[116:119], v[144:147], v[164:167], v[116:119]
	v_mfma_f32_16x16x32_bf16 v[108:111], v[156:159], v[164:167], v[108:111]
	v_mfma_f32_16x16x32_bf16 v[120:123], v[144:147], v[172:175], v[120:123]
	v_mfma_f32_16x16x32_bf16 v[112:115], v[156:159], v[172:175], v[112:115]
	v_mfma_f32_16x16x32_bf16 v[84:87], v[144:147], v[202:205], v[84:87]
	v_mfma_f32_16x16x32_bf16 v[80:83], v[156:159], v[202:205], v[80:83]
	v_mfma_f32_16x16x32_bf16 v[68:71], v[144:147], v[218:221], v[68:71]
	v_mfma_f32_16x16x32_bf16 v[64:67], v[156:159], v[218:221], v[64:67]
	s_setprio 0
	s_barrier
; #define PG8_STAGE(bufoff, gbase, voff) do { _Pragma("unroll") for (int _i = 0; _i < 2; ++_i) \
;         __builtin_amdgcn_global_load_lds((const unsigned*)((const char*)(gbase) + (voff)[_i]), (LAS unsigned*)(lds + (bufoff) + ldsw + _i * 8192), 16, 0, 0); } while (0)
; #define PG8_LDA(dst, b, h) do { _Pragma("unroll") for (int m = 0; m < 4; ++m) _Pragma("unroll") for (int k = 0; k < 2; ++k) dst[m][k] = *(const LAS bf16x8*)(lds + PG8_SA(b, h) + aoff + m * 2048 + k * 1024); } while (0)
; #define PG8_MMA(ai, bj, At, Bt) do { __builtin_amdgcn_s_setprio(1); _Pragma("unroll") for (int m = 0; m < 4; ++m) _Pragma("unroll") for (int n = 0; n < 2; ++n) _Pragma("unroll") for (int k = 0; k < 2; ++k) \
;         acc[ai][bj][m][n] = __builtin_amdgcn_mfma_f32_16x16x32_bf16(Bt[n][k], At[m][k], acc[ai][bj][m][n], 0, 0, 0); __builtin_amdgcn_s_setprio(0); } while (0)
; #define PG8_WAIT_V(n) asm volatile("s_waitcnt vmcnt(" #n ")" ::: "memory")
; #define PG8_WAIT_L(n) asm volatile("s_waitcnt lgkmcnt(" #n ")" ::: "memory")
; #define PG8_BAR __builtin_amdgcn_s_barrier()
; #define PG8_SCHED __builtin_amdgcn_sched_barrier(0)
; template <class Epi, class Sched>
; __device__ __forceinline__ void gemm_phase(int wv, LAS unsigned char* lds, const Gemm g, const Sched& S, const Epi& E) {
;     ...
;             PG8_LDA(At, 1, 1); PG8_STAGE(PG8_SB(1, 0), b3, voffB); PG8_STAGE(PG8_SB(1, 1), b3 + hstepB, voffB); PG8_STAGE(PG8_SA(1, 0), a3, voffA);
;             PG8_WAIT_V(8); PG8_WAIT_L(0); PG8_BAR; PG8_MMA(1, 0, At, B0); PG8_MMA(1, 1, At, B1); PG8_BAR; PG8_SCHED;
;         }
;         if (wr == 0) PG8_BAR;
	s_add_i32 s22, s95, s34
	v_lshl_add_u64 v[186:187], v[186:187], 0, s[74:75]
	s_mov_b32 m0, s22
	ds_read_b128 v[160:163], v217 offset:49152
	ds_read_b128 v[164:167], v217 offset:50176
	ds_read_b128 v[168:171], v217 offset:51200
	ds_read_b128 v[172:175], v217 offset:52224
	ds_read_b128 v[198:201], v217 offset:53248
	ds_read_b128 v[202:205], v217 offset:54272
	ds_read_b128 v[206:209], v217 offset:55296
	ds_read_b128 v[218:221], v217 offset:56320
	global_load_lds_dwordx4 v[186:187], off
	s_add_i32 m0, s22, 0x2000
	s_add_u32 s22, s24, 0xb080
	v_lshl_add_u64 v[186:187], v[210:211], 0, s[74:75]
	s_addc_u32 s23, s25, 0
	s_add_i32 s24, s48, s34
	global_load_lds_dwordx4 v[186:187], off
	v_lshl_add_u64 v[186:187], s[22:23], 0, v[188:189]
	s_mov_b32 m0, s24
	s_nop 0
	global_load_lds_dwordx4 v[186:187], off
	v_lshl_add_u64 v[186:187], s[22:23], 0, v[176:177]
	s_add_i32 m0, s24, 0x2000
	s_nop 0
	global_load_lds_dwordx4 v[186:187], off
	v_lshl_add_u64 v[186:187], v[222:223], 0, s[74:75]
	s_mov_b32 m0, s39
	s_nop 0
	global_load_lds_dwordx4 v[186:187], off
	v_lshl_add_u64 v[186:187], v[228:229], 0, s[74:75]
	s_mov_b32 m0, s40
	s_nop 0
	global_load_lds_dwordx4 v[186:187], off
	s_waitcnt vmcnt(8)
	s_waitcnt lgkmcnt(0)
	s_barrier
	s_setprio 1
	s_waitcnt lgkmcnt(0)
	v_mfma_f32_16x16x32_bf16 v[60:63], v[96:99], v[160:163], v[60:63]
	v_mfma_f32_16x16x32_bf16 v[56:59], v[104:107], v[160:163], v[56:59]
	v_mfma_f32_16x16x32_bf16 v[44:47], v[96:99], v[168:171], v[44:47]
	v_mfma_f32_16x16x32_bf16 v[40:43], v[104:107], v[168:171], v[40:43]
	v_mfma_f32_16x16x32_bf16 v[28:31], v[96:99], v[198:201], v[28:31]
	v_mfma_f32_16x16x32_bf16 v[24:27], v[104:107], v[198:201], v[24:27]
	v_mfma_f32_16x16x32_bf16 v[12:15], v[96:99], v[206:209], v[12:15]
	v_mfma_f32_16x16x32_bf16 v[8:11], v[104:107], v[206:209], v[8:11]
	v_mfma_f32_16x16x32_bf16 v[60:63], v[100:103], v[164:167], v[60:63]
	v_mfma_f32_16x16x32_bf16 v[56:59], v[136:139], v[164:167], v[56:59]
	v_mfma_f32_16x16x32_bf16 v[44:47], v[100:103], v[172:175], v[44:47]
	v_mfma_f32_16x16x32_bf16 v[40:43], v[136:139], v[172:175], v[40:43]
	v_mfma_f32_16x16x32_bf16 v[28:31], v[100:103], v[202:205], v[28:31]
	v_mfma_f32_16x16x32_bf16 v[24:27], v[136:139], v[202:205], v[24:27]
	v_mfma_f32_16x16x32_bf16 v[12:15], v[100:103], v[218:221], v[12:15]
	v_mfma_f32_16x16x32_bf16 v[8:11], v[136:139], v[218:221], v[8:11]
	v_mfma_f32_16x16x32_bf16 v[52:55], v[140:143], v[160:163], v[52:55]
	v_mfma_f32_16x16x32_bf16 v[48:51], v[152:155], v[160:163], v[48:51]
	v_mfma_f32_16x16x32_bf16 v[36:39], v[140:143], v[168:171], v[36:39]
	v_mfma_f32_16x16x32_bf16 v[32:35], v[152:155], v[168:171], v[32:35]
	v_mfma_f32_16x16x32_bf16 v[20:23], v[140:143], v[198:201], v[20:23]
	v_mfma_f32_16x16x32_bf16 v[16:19], v[152:155], v[198:201], v[16:19]
	v_mfma_f32_16x16x32_bf16 v[4:7], v[140:143], v[206:209], v[4:7]
	v_mfma_f32_16x16x32_bf16 v[0:3], v[152:155], v[206:209], v[0:3]
	v_mfma_f32_16x16x32_bf16 v[52:55], v[144:147], v[164:167], v[52:55]
	v_mfma_f32_16x16x32_bf16 v[48:51], v[156:159], v[164:167], v[48:51]
	v_mfma_f32_16x16x32_bf16 v[36:39], v[144:147], v[172:175], v[36:39]
	v_mfma_f32_16x16x32_bf16 v[32:35], v[156:159], v[172:175], v[32:35]
	v_mfma_f32_16x16x32_bf16 v[20:23], v[144:147], v[202:205], v[20:23]
	v_mfma_f32_16x16x32_bf16 v[16:19], v[156:159], v[202:205], v[16:19]
	v_mfma_f32_16x16x32_bf16 v[4:7], v[144:147], v[218:221], v[4:7]
	v_mfma_f32_16x16x32_bf16 v[0:3], v[156:159], v[218:221], v[0:3]
	s_setprio 0
	s_barrier
	s_add_i32 s47, s47, 2
	s_add_u32 s45, s45, 0x100
	s_addc_u32 s46, s46, 0
	s_cmp_gt_u32 s47, 41
	s_mov_b64 s[22:23], s[4:5]
	s_cbranch_scc0 .LBB0_1055
	s_and_b64 vcc, exec, s[16:17]
	s_cbranch_vccz .LBB0_1058
	s_barrier
